# gMLP item gate stage: all 32 z loads issued up front into dead registers (were 32 serial load/vmcnt(0)/silu/store groups)
# speedup vs baseline: 1.0127x; 1.0024x over previous
.LBB0_897:
	s_or_b64 exec, exec, s[12:13]
	v_bfe_u32 v32, v4, 2, 7
	v_lshl_add_u64 v[0:1], s[4:5], 0, v[32:33]
	v_mad_u64_u32 v[2:3], s[12:13], v0, s9, v[34:35]
	v_mov_b32_e32 v0, v3
	v_mad_u64_u32 v[0:1], s[12:13], v1, s9, v[0:1]
	v_mov_b32_e32 v3, v0
	v_lshlrev_b32_e32 v0, 3, v4
	v_and_b32_e32 v5, 24, v0
	v_lshlrev_b32_e32 v0, 1, v5
	v_mov_b32_e32 v1, v33
	v_lshl_add_u64 v[46:47], v[2:3], 0, v[0:1]
	global_load_dwordx4 v[8:11], v[46:47], off offset:2048
	v_lshlrev_b32_e32 v157, 2, v5
	global_load_dwordx4 v[12:15], v[46:47], off offset:2112
	global_load_dwordx4 v[16:19], v[46:47], off offset:2176
	global_load_dwordx4 v[0:3], v[46:47], off offset:2240
	s_waitcnt lgkmcnt(0)
	s_barrier
	global_load_dwordx4 v[20:23], v157, s[48:49]
	global_load_dwordx4 v[24:27], v157, s[50:51]
	global_load_dwordx4 v[28:31], v157, s[48:49] offset:16
	global_load_dwordx4 v[36:39], v157, s[50:51] offset:16
	v_lshl_add_u32 v6, v32, 3, 0
	v_lshlrev_b32_e32 v7, 1, v32
	v_add_u32_e32 v160, 0x11000, v6
	v_mul_u32_u24_e32 v5, 0x110, v5
	v_add3_u32 v155, 0, v7, v5
	ds_read_b64 v[6:7], v160
	v_ashrrev_i32_e32 v44, 2, v4
	v_and_b32_e32 v50, 15, v4
	v_mov_b32_e32 v49, v33
	v_readlane_b32 s56, v254, 12
	v_readlane_b32 s58, v254, 14
	v_readlane_b32 s59, v254, 15
	v_readlane_b32 s57, v254, 13
	v_readlane_b32 s60, v254, 16
	v_readlane_b32 s61, v254, 17
	v_readlane_b32 s62, v254, 18
	v_readlane_b32 s63, v254, 19
	v_readlane_b32 s64, v254, 20
	v_readlane_b32 s65, v254, 21
	v_readlane_b32 s66, v254, 22
	v_readlane_b32 s67, v254, 23
	v_readlane_b32 s68, v254, 24
	v_readlane_b32 s69, v254, 25
	v_readlane_b32 s70, v254, 26
	v_readlane_b32 s71, v254, 27
	s_waitcnt vmcnt(7)
	v_lshlrev_b32_e32 v5, 16, v8
	s_waitcnt lgkmcnt(0)
	v_sub_f32_e32 v5, v5, v6
	v_and_b32_e32 v8, 0xffff0000, v8
	v_mul_f32_e32 v5, v7, v5
	v_lshlrev_b32_e32 v32, 16, v9
	v_sub_f32_e32 v8, v8, v6
	s_waitcnt vmcnt(2)
	v_fma_f32 v5, v20, v5, v24
	v_and_b32_e32 v9, 0xffff0000, v9
	v_sub_f32_e32 v32, v32, v6
	v_mul_f32_e32 v8, v7, v8
	v_cvt_pk_bf16_f32 v5, v5, v33
	v_lshlrev_b32_e32 v40, 16, v10
	v_sub_f32_e32 v9, v9, v6
	v_mul_f32_e32 v32, v7, v32
	v_fma_f32 v8, v21, v8, v25
	ds_write_b16 v155, v5
	v_cvt_pk_bf16_f32 v5, v8, v33
	v_and_b32_e32 v10, 0xffff0000, v10
	v_sub_f32_e32 v40, v40, v6
	v_mul_f32_e32 v9, v7, v9
	v_fma_f32 v20, v22, v32, v26
	ds_write_b16 v155, v5 offset:272
	v_cvt_pk_bf16_f32 v5, v20, v33
	v_lshlrev_b32_e32 v41, 16, v11
	v_sub_f32_e32 v10, v10, v6
	v_mul_f32_e32 v40, v7, v40
	v_fmac_f32_e32 v27, v23, v9
	ds_write_b16 v155, v5 offset:544
	v_cvt_pk_bf16_f32 v5, v27, v33
	v_and_b32_e32 v11, 0xffff0000, v11
	v_sub_f32_e32 v41, v41, v6
	v_mul_f32_e32 v10, v7, v10
	s_waitcnt vmcnt(0)
	v_fma_f32 v9, v40, v28, v36
	ds_write_b16 v155, v5 offset:816
	v_cvt_pk_bf16_f32 v5, v9, v33
	v_sub_f32_e32 v11, v11, v6
	v_mul_f32_e32 v41, v7, v41
	v_fma_f32 v10, v10, v29, v37
	ds_write_b16 v155, v5 offset:1088
	v_cvt_pk_bf16_f32 v5, v10, v33
	v_mul_f32_e32 v11, v7, v11
	v_fma_f32 v21, v41, v30, v38
	ds_write_b16 v155, v5 offset:1360
	v_cvt_pk_bf16_f32 v5, v21, v33
	v_fmac_f32_e32 v39, v11, v31
	ds_write_b16 v155, v5 offset:1632
	v_cvt_pk_bf16_f32 v5, v39, v33
	global_load_dwordx4 v[8:11], v157, s[48:49] offset:128
	global_load_dwordx4 v[20:23], v157, s[50:51] offset:128
	global_load_dwordx4 v[24:27], v157, s[48:49] offset:144
	global_load_dwordx4 v[28:31], v157, s[50:51] offset:144
	v_lshlrev_b32_e32 v32, 16, v12
	v_sub_f32_e32 v32, v32, v6
	v_and_b32_e32 v12, 0xffff0000, v12
	v_mul_f32_e32 v32, v7, v32
	v_lshlrev_b32_e32 v36, 16, v13
	v_sub_f32_e32 v12, v12, v6
	ds_write_b16 v155, v5 offset:1904
	v_and_b32_e32 v13, 0xffff0000, v13
	v_sub_f32_e32 v36, v36, v6
	v_mul_f32_e32 v12, v7, v12
	v_lshlrev_b32_e32 v37, 16, v14
	v_sub_f32_e32 v13, v13, v6
	v_mul_f32_e32 v36, v7, v36
	v_and_b32_e32 v14, 0xffff0000, v14
	v_sub_f32_e32 v37, v37, v6
	v_mul_f32_e32 v13, v7, v13
	v_lshlrev_b32_e32 v38, 16, v15
	v_sub_f32_e32 v14, v14, v6
	v_mul_f32_e32 v37, v7, v37
	v_and_b32_e32 v15, 0xffff0000, v15
	v_sub_f32_e32 v38, v38, v6
	v_mul_f32_e32 v14, v7, v14
	v_sub_f32_e32 v15, v15, v6
	v_mul_f32_e32 v38, v7, v38
	v_mul_f32_e32 v15, v7, v15
	s_waitcnt vmcnt(2)
	v_fma_f32 v5, v32, v8, v20
	v_cvt_pk_bf16_f32 v5, v5, v33
	v_fma_f32 v8, v12, v9, v21
	ds_write_b16 v155, v5 offset:8704
	v_cvt_pk_bf16_f32 v5, v8, v33
	v_fma_f32 v9, v36, v10, v22
	ds_write_b16 v155, v5 offset:8976
	v_cvt_pk_bf16_f32 v5, v9, v33
	v_fmac_f32_e32 v23, v13, v11
	ds_write_b16 v155, v5 offset:9248
	v_cvt_pk_bf16_f32 v5, v23, v33
	s_waitcnt vmcnt(0)
	v_fma_f32 v10, v37, v24, v28
	ds_write_b16 v155, v5 offset:9520
	v_cvt_pk_bf16_f32 v5, v10, v33
	v_fma_f32 v11, v14, v25, v29
	ds_write_b16 v155, v5 offset:9792
	v_cvt_pk_bf16_f32 v5, v11, v33
	v_fma_f32 v12, v38, v26, v30
	ds_write_b16 v155, v5 offset:10064
	v_cvt_pk_bf16_f32 v5, v12, v33
	v_fmac_f32_e32 v31, v15, v27
	ds_write_b16 v155, v5 offset:10336
	v_cvt_pk_bf16_f32 v5, v31, v33
	global_load_dwordx4 v[8:11], v157, s[48:49] offset:256
	global_load_dwordx4 v[12:15], v157, s[50:51] offset:256
	global_load_dwordx4 v[20:23], v157, s[48:49] offset:272
	global_load_dwordx4 v[24:27], v157, s[50:51] offset:272
	v_lshlrev_b32_e32 v28, 16, v16
	v_sub_f32_e32 v28, v28, v6
	v_and_b32_e32 v16, 0xffff0000, v16
	v_mul_f32_e32 v28, v7, v28
	v_lshlrev_b32_e32 v29, 16, v17
	v_sub_f32_e32 v16, v16, v6
	ds_write_b16 v155, v5 offset:10608
	v_and_b32_e32 v17, 0xffff0000, v17
	v_sub_f32_e32 v29, v29, v6
	v_mul_f32_e32 v16, v7, v16
	v_lshlrev_b32_e32 v30, 16, v18
	v_sub_f32_e32 v17, v17, v6
	v_mul_f32_e32 v29, v7, v29
	v_and_b32_e32 v18, 0xffff0000, v18
	v_sub_f32_e32 v30, v30, v6
	v_mul_f32_e32 v17, v7, v17
	v_lshlrev_b32_e32 v31, 16, v19
	v_sub_f32_e32 v18, v18, v6
	v_mul_f32_e32 v30, v7, v30
	v_and_b32_e32 v19, 0xffff0000, v19
	v_sub_f32_e32 v31, v31, v6
	v_mul_f32_e32 v18, v7, v18
	v_sub_f32_e32 v19, v19, v6
	v_mul_f32_e32 v31, v7, v31
	v_mul_f32_e32 v19, v7, v19
	s_waitcnt vmcnt(2)
	v_fma_f32 v5, v28, v8, v12
	v_cvt_pk_bf16_f32 v5, v5, v33
	v_fma_f32 v8, v16, v9, v13
	ds_write_b16 v155, v5 offset:17408
	v_cvt_pk_bf16_f32 v5, v8, v33
	v_fma_f32 v9, v29, v10, v14
	ds_write_b16 v155, v5 offset:17680
	v_cvt_pk_bf16_f32 v5, v9, v33
	v_fmac_f32_e32 v15, v17, v11
	ds_write_b16 v155, v5 offset:17952
	v_cvt_pk_bf16_f32 v5, v15, v33
	s_waitcnt vmcnt(0)
	v_fma_f32 v10, v30, v20, v24
	ds_write_b16 v155, v5 offset:18224
	v_cvt_pk_bf16_f32 v5, v10, v33
	v_fma_f32 v11, v18, v21, v25
	ds_write_b16 v155, v5 offset:18496
	v_cvt_pk_bf16_f32 v5, v11, v33
	v_fma_f32 v12, v31, v22, v26
	ds_write_b16 v155, v5 offset:18768
	v_cvt_pk_bf16_f32 v5, v12, v33
	v_fmac_f32_e32 v27, v19, v23
	ds_write_b16 v155, v5 offset:19040
	v_cvt_pk_bf16_f32 v5, v27, v33
	global_load_dwordx4 v[8:11], v157, s[48:49] offset:384
	global_load_dwordx4 v[12:15], v157, s[50:51] offset:384
	global_load_dwordx4 v[16:19], v157, s[48:49] offset:400
	global_load_dwordx4 v[20:23], v157, s[50:51] offset:400
	v_bfe_u32 v24, v4, 4, 2
	v_and_b32_e32 v26, -16, v44
	v_lshlrev_b32_e32 v32, 3, v24
	v_lshlrev_b32_e32 v48, 4, v24
	v_ashrrev_i32_e32 v25, 31, v26
	v_or_b32_e32 v24, v26, v50
	v_lshl_add_u64 v[26:27], s[0:1], 0, v[48:49]
	v_lshl_add_u64 v[36:37], s[4:5], 0, v[24:25]
	v_lshlrev_b64 v[24:25], 8, v[24:25]
	v_lshl_add_u64 v[42:43], v[26:27], 0, v[24:25]
	v_lshlrev_b32_e32 v24, 16, v0
	v_and_b32_e32 v0, 0xffff0000, v0
	v_lshlrev_b32_e32 v27, 16, v3
	v_and_b32_e32 v3, 0xffff0000, v3
	v_sub_f32_e32 v0, v0, v6
	v_lshlrev_b32_e32 v25, 16, v1
	v_and_b32_e32 v1, 0xffff0000, v1
	v_lshlrev_b32_e32 v26, 16, v2
	v_and_b32_e32 v2, 0xffff0000, v2
	v_sub_f32_e32 v24, v24, v6
	v_sub_f32_e32 v3, v3, v6
	v_mul_f32_e32 v0, v7, v0
	v_sub_f32_e32 v25, v25, v6
	v_sub_f32_e32 v1, v1, v6
	v_sub_f32_e32 v26, v26, v6
	v_sub_f32_e32 v2, v2, v6
	v_sub_f32_e32 v27, v27, v6
	v_mul_f32_e32 v6, v7, v24
	v_mul_f32_e32 v3, v7, v3
	v_mul_f32_e32 v24, v7, v25
	ds_write_b16 v155, v5 offset:19312
	v_mul_f32_e32 v1, v7, v1
	v_mul_f32_e32 v25, v7, v26
	v_mul_f32_e32 v2, v7, v2
	v_mul_f32_e32 v26, v7, v27
	v_mad_u64_u32 v[38:39], s[12:13], v36, s9, v[34:35]
	s_waitcnt vmcnt(2)
	v_fma_f32 v0, v0, v9, v13
	v_fma_f32 v5, v6, v8, v12
	s_waitcnt vmcnt(0)
	v_fmac_f32_e32 v23, v3, v19
	v_cvt_pk_bf16_f32 v3, v5, v33
	ds_write_b16 v155, v3 offset:26112
	v_cvt_pk_bf16_f32 v0, v0, v33
	v_fma_f32 v6, v24, v10, v14
	ds_write_b16 v155, v0 offset:26384
	v_cvt_pk_bf16_f32 v0, v6, v33
	v_fmac_f32_e32 v15, v1, v11
	ds_write_b16 v155, v0 offset:26656
	v_cvt_pk_bf16_f32 v0, v15, v33
	v_fma_f32 v1, v25, v16, v20
	ds_write_b16 v155, v0 offset:26928
	v_cvt_pk_bf16_f32 v0, v1, v33
	v_fma_f32 v2, v2, v17, v21
	ds_write_b16 v155, v0 offset:27200
	v_cvt_pk_bf16_f32 v0, v2, v33
	v_fma_f32 v7, v26, v18, v22
	ds_write_b16 v155, v0 offset:27472
	v_cvt_pk_bf16_f32 v0, v7, v33
	ds_write_b16 v155, v0 offset:27744
	v_cvt_pk_bf16_f32 v0, v23, v33
	ds_write_b16 v155, v0 offset:28016
	s_waitcnt lgkmcnt(0)
	s_barrier
	global_load_dwordx4 v[20:23], v[42:43], off
	global_load_dwordx4 v[24:27], v[42:43], off offset:64
	v_mov_b32_e32 v0, v39
	v_mad_u64_u32 v[0:1], s[12:13], v37, s9, v[0:1]
	v_mov_b32_e32 v39, v0
	v_lshl_add_u64 v[40:41], v[38:39], 0, v[32:33]
	global_load_dwordx2 v[52:53], v[40:41], off offset:1024
	global_load_dwordx4 v[28:31], v[42:43], off offset:128
	global_load_dwordx4 v[16:19], v[42:43], off offset:192
	v_bfi_b32 v0, -16, v44, v4
	v_ashrrev_i32_e32 v1, 31, v0
	v_lshl_add_u64 v[44:45], v[0:1], 2, s[58:59]
	global_load_dword v54, v[44:45], off
	v_mul_u32_u24_e32 v0, 0x110, v50
	v_add3_u32 v152, 0, v48, v0
	ds_read_b128 v[0:3], v152
	ds_read_b128 v[4:7], v152 offset:64
	ds_read_b128 v[48:51], v152 offset:128
	s_waitcnt vmcnt(5) lgkmcnt(2)
	v_mfma_f32_16x16x32_bf16 v[0:3], v[0:3], v[20:23], 0
	global_load_dwordx4 v[12:15], v[46:47], off offset:2304
	global_load_dwordx4 v[8:11], v[46:47], off offset:2368
	ds_read_b128 v[56:59], v152 offset:192
	s_waitcnt vmcnt(5)
	v_lshlrev_b32_e32 v64, 16, v52
	s_waitcnt lgkmcnt(2)
	v_mfma_f32_16x16x32_bf16 v[60:63], v[4:7], v[24:27], v[0:3]
	v_and_b32_e32 v65, 0xffff0000, v52
	v_lshlrev_b32_e32 v52, 16, v53
	v_and_b32_e32 v53, 0xffff0000, v53
	s_waitcnt vmcnt(4) lgkmcnt(1)
	v_mfma_f32_16x16x32_bf16 v[48:51], v[48:51], v[28:31], v[60:63]
	global_load_dwordx4 v[4:7], v[46:47], off offset:2432
	global_load_dwordx4 v[0:3], v[46:47], off offset:2496
	s_waitcnt vmcnt(0)
	v_lshlrev_b32_e32 v101, 16, v2
	s_waitcnt lgkmcnt(0)
	v_mfma_f32_16x16x32_bf16 v[48:51], v[56:59], v[16:19], v[48:51]
	v_and_b32_e32 v102, 0xffff0000, v2
	v_and_b32_e32 v100, 0xffff0000, v1
	v_lshlrev_b32_e32 v103, 16, v3
	v_and_b32_e32 v104, 0xffff0000, v3
	s_nop 3
	v_pk_add_f32 v[48:49], v[54:55], v[48:49] op_sel_hi:[0,1]
	v_pk_add_f32 v[50:51], v[54:55], v[50:51] op_sel_hi:[0,1]
	v_pk_mul_f32 v[48:49], v[48:49], v[64:65]
	v_pk_mul_f32 v[50:51], v[50:51], v[52:53]
	v_cvt_pk_bf16_f32 v150, v48, v49
	v_mul_f32_e32 v2, v49, v49
	v_cvt_pk_bf16_f32 v148, v50, v51
	ds_read_b128 v[56:59], v152 offset:4352
	ds_read_b128 v[60:63], v152 offset:4416
	s_waitcnt lgkmcnt(1)
	v_mfma_f32_16x16x32_bf16 v[56:59], v[56:59], v[20:23], 0
	v_pk_fma_f32 v[2:3], v[48:49], v[48:49], v[2:3] op_sel_hi:[1,1,0]
	s_nop 0
	v_mov_b32_e32 v84, v2
	s_waitcnt lgkmcnt(0)
	v_mfma_f32_16x16x32_bf16 v[56:59], v[60:63], v[24:27], v[56:59]
	ds_read_b128 v[60:63], v152 offset:4480
	ds_read_b128 v[64:67], v152 offset:4544
	global_load_dwordx2 v[52:53], v[40:41], off offset:1056
	s_waitcnt lgkmcnt(1)
	v_mfma_f32_16x16x32_bf16 v[56:59], v[60:63], v[28:31], v[56:59]
	s_waitcnt vmcnt(0)
	v_lshlrev_b32_e32 v60, 16, v52
	s_waitcnt lgkmcnt(0)
	v_mfma_f32_16x16x32_bf16 v[56:59], v[64:67], v[16:19], v[56:59]
	v_and_b32_e32 v61, 0xffff0000, v52
	v_lshlrev_b32_e32 v62, 16, v53
	v_and_b32_e32 v63, 0xffff0000, v53
	s_nop 4
	v_pk_add_f32 v[56:57], v[54:55], v[56:57] op_sel_hi:[0,1]
	v_pk_add_f32 v[58:59], v[54:55], v[58:59] op_sel_hi:[0,1]
	v_pk_mul_f32 v[52:53], v[56:57], v[60:61]
	v_pk_mul_f32 v[60:61], v[58:59], v[62:63]
	v_cvt_pk_bf16_f32 v145, v52, v53
	s_nop 0
	v_cvt_pk_bf16_f32 v142, v60, v61
	ds_read_b128 v[56:59], v152 offset:8704
	ds_read_b128 v[62:65], v152 offset:8768
	s_waitcnt lgkmcnt(1)
	v_mfma_f32_16x16x32_bf16 v[56:59], v[56:59], v[20:23], 0
	s_waitcnt lgkmcnt(0)
	v_mfma_f32_16x16x32_bf16 v[56:59], v[62:65], v[24:27], v[56:59]
	ds_read_b128 v[62:65], v152 offset:8832
	ds_read_b128 v[66:69], v152 offset:8896
	s_waitcnt lgkmcnt(1)
	v_mfma_f32_16x16x32_bf16 v[56:59], v[62:65], v[28:31], v[56:59]
	global_load_dwordx2 v[62:63], v[40:41], off offset:1088
	s_waitcnt vmcnt(0)
	v_lshlrev_b32_e32 v65, 16, v63
	s_waitcnt lgkmcnt(0)
	v_mfma_f32_16x16x32_bf16 v[56:59], v[66:69], v[16:19], v[56:59]
	v_and_b32_e32 v63, 0xffff0000, v63
	s_nop 6
	v_add_f32_e32 v55, v54, v56
	v_add_f32_e32 v56, v54, v57
	v_add_f32_e32 v57, v54, v58
	v_add_f32_e32 v58, v54, v59
	v_lshlrev_b32_e32 v59, 16, v62
	v_and_b32_e32 v62, 0xffff0000, v62
	v_mul_f32_e32 v64, v55, v59
	v_mul_f32_e32 v68, v56, v62
	v_mul_f32_e32 v66, v57, v65
	v_mul_f32_e32 v62, v58, v63
	v_cvt_pk_bf16_f32 v139, v64, v68
	v_cvt_pk_bf16_f32 v137, v66, v62
	ds_read_b128 v[56:59], v152 offset:13056
	ds_read_b128 v[70:73], v152 offset:13120
	s_waitcnt lgkmcnt(1)
	v_mfma_f32_16x16x32_bf16 v[56:59], v[56:59], v[20:23], 0
	s_waitcnt lgkmcnt(0)
	v_mfma_f32_16x16x32_bf16 v[56:59], v[70:73], v[24:27], v[56:59]
	ds_read_b128 v[70:73], v152 offset:13184
	ds_read_b128 v[74:77], v152 offset:13248
	global_load_dwordx2 v[78:79], v[40:41], off offset:1120
	s_waitcnt lgkmcnt(1)
	v_mfma_f32_16x16x32_bf16 v[56:59], v[70:73], v[28:31], v[56:59]
	v_mov_b32_e32 v70, v64
	v_mov_b32_e32 v72, v66
	s_waitcnt vmcnt(0)
	v_lshlrev_b32_e32 v71, 16, v79
	s_waitcnt lgkmcnt(0)
	v_mfma_f32_16x16x32_bf16 v[56:59], v[74:77], v[16:19], v[56:59]
	v_and_b32_e32 v73, 0xffff0000, v79
	s_nop 6
	v_add_f32_e32 v55, v54, v56
	v_add_f32_e32 v56, v54, v57
	v_add_f32_e32 v65, v54, v58
	v_add_f32_e32 v67, v54, v59
	v_lshlrev_b32_e32 v57, 16, v78
	v_and_b32_e32 v58, 0xffff0000, v78
	v_mul_f32_e32 v85, v55, v57
	v_mul_f32_e32 v75, v56, v58
	v_pk_mul_f32 v[86:87], v[64:65], v[70:71]
	v_pk_mul_f32 v[88:89], v[66:67], v[72:73]
	v_cvt_pk_bf16_f32 v136, v85, v75
	v_lshlrev_b32_e32 v72, 16, v15
	v_cvt_pk_bf16_f32 v133, v87, v89
	ds_read_b128 v[56:59], v152 offset:17408
	ds_read_b128 v[76:79], v152 offset:17472
	s_waitcnt lgkmcnt(1)
	v_mfma_f32_16x16x32_bf16 v[56:59], v[56:59], v[20:23], 0
	v_and_b32_e32 v15, 0xffff0000, v15
	v_pk_mul_f32 v[48:49], v[88:89], v[88:89]
	s_waitcnt lgkmcnt(0)
	v_mfma_f32_16x16x32_bf16 v[56:59], v[76:79], v[24:27], v[56:59]
	ds_read_b128 v[76:79], v152 offset:17536
	ds_read_b128 v[80:83], v152 offset:17600
	s_waitcnt lgkmcnt(1)
	v_mfma_f32_16x16x32_bf16 v[56:59], v[76:79], v[28:31], v[56:59]
	global_load_dwordx2 v[76:77], v[40:41], off offset:1152
	s_waitcnt lgkmcnt(0)
	v_mfma_f32_16x16x32_bf16 v[56:59], v[80:83], v[16:19], v[56:59]
	s_nop 7
	v_mov_b32_e32 v78, v56
	v_mov_b32_e32 v79, v58
	v_mov_b32_e32 v58, v57
	v_pk_add_f32 v[56:57], v[54:55], v[78:79] op_sel_hi:[0,1]
	v_pk_add_f32 v[58:59], v[54:55], v[58:59] op_sel_hi:[0,1]
	s_waitcnt vmcnt(0)
	v_lshlrev_b32_e32 v79, 16, v77
	v_lshlrev_b32_e32 v78, 16, v76
	v_and_b32_e32 v77, 0xffff0000, v77
	v_and_b32_e32 v76, 0xffff0000, v76
	v_pk_mul_f32 v[90:91], v[56:57], v[78:79]
	v_pk_mul_f32 v[92:93], v[58:59], v[76:77]
	s_nop 0
	v_cvt_pk_bf16_f32 v134, v90, v92
	v_cvt_pk_bf16_f32 v132, v91, v93
	ds_read_b128 v[56:59], v152 offset:21760
	ds_read_b128 v[76:79], v152 offset:21824
	s_waitcnt lgkmcnt(1)
	v_mfma_f32_16x16x32_bf16 v[56:59], v[56:59], v[20:23], 0
	s_waitcnt lgkmcnt(0)
	v_mfma_f32_16x16x32_bf16 v[56:59], v[76:79], v[24:27], v[56:59]
	ds_read_b128 v[76:79], v152 offset:21888
	ds_read_b128 v[80:83], v152 offset:21952
	s_waitcnt lgkmcnt(1)
	v_mfma_f32_16x16x32_bf16 v[56:59], v[76:79], v[28:31], v[56:59]
	global_load_dwordx2 v[76:77], v[40:41], off offset:1184
	s_waitcnt lgkmcnt(0)
	v_mfma_f32_16x16x32_bf16 v[56:59], v[80:83], v[16:19], v[56:59]
	s_nop 7
	v_pk_add_f32 v[56:57], v[54:55], v[56:57] op_sel_hi:[0,1]
	v_pk_add_f32 v[78:79], v[54:55], v[58:59] op_sel_hi:[0,1]
	s_waitcnt vmcnt(0)
	v_lshlrev_b32_e32 v58, 16, v76
	v_and_b32_e32 v59, 0xffff0000, v76
	v_lshlrev_b32_e32 v76, 16, v77
	v_and_b32_e32 v77, 0xffff0000, v77
	v_pk_mul_f32 v[58:59], v[56:57], v[58:59]
	v_pk_mul_f32 v[94:95], v[78:79], v[76:77]
	v_cvt_pk_bf16_f32 v130, v58, v59
	s_nop 0
	v_cvt_pk_bf16_f32 v129, v94, v95
	ds_read_b128 v[76:79], v152 offset:26112
	ds_read_b128 v[80:83], v152 offset:26176
	s_waitcnt lgkmcnt(1)
	v_mfma_f32_16x16x32_bf16 v[76:79], v[76:79], v[20:23], 0
	s_waitcnt lgkmcnt(0)
	v_mfma_f32_16x16x32_bf16 v[76:79], v[80:83], v[24:27], v[76:79]
	ds_read_b128 v[80:83], v152 offset:26240
	ds_read_b128 v[96:99], v152 offset:26304
	global_load_dwordx2 v[56:57], v[40:41], off offset:1216
	s_waitcnt vmcnt(0)
	v_lshlrev_b32_e32 v66, 16, v56
	s_waitcnt lgkmcnt(1)
	v_mfma_f32_16x16x32_bf16 v[76:79], v[80:83], v[28:31], v[76:79]
	v_and_b32_e32 v56, 0xffff0000, v56
	v_lshlrev_b32_e32 v70, 16, v57
	v_and_b32_e32 v57, 0xffff0000, v57
	s_waitcnt lgkmcnt(0)
	v_mfma_f32_16x16x32_bf16 v[76:79], v[96:99], v[16:19], v[76:79]
	s_nop 7
	v_add_f32_e32 v55, v54, v76
	v_add_f32_e32 v63, v54, v77
	v_add_f32_e32 v64, v54, v78
	v_add_f32_e32 v69, v54, v79
	v_mul_f32_e32 v96, v55, v66
	v_mul_f32_e32 v66, v63, v56
	v_mul_f32_e32 v98, v64, v70
	v_mul_f32_e32 v64, v69, v57
	v_cvt_pk_bf16_f32 v128, v96, v66
	v_cvt_pk_bf16_f32 v127, v98, v64
	ds_read_b128 v[76:79], v152 offset:30464
	ds_read_b128 v[80:83], v152 offset:30528
	s_waitcnt lgkmcnt(1)
	v_mfma_f32_16x16x32_bf16 v[20:23], v[76:79], v[20:23], 0
	v_mov_b32_e32 v76, v96
	v_mov_b32_e32 v78, v98
	v_and_b32_e32 v56, 0xffff0000, v12
	s_waitcnt lgkmcnt(0)
	v_mfma_f32_16x16x32_bf16 v[20:23], v[80:83], v[24:27], v[20:23]
	ds_read_b128 v[24:27], v152 offset:30592
	ds_read_b128 v[80:83], v152 offset:30656
	v_lshlrev_b32_e32 v63, 16, v13
	v_and_b32_e32 v69, 0xffff0000, v13
	s_waitcnt lgkmcnt(1)
	v_mfma_f32_16x16x32_bf16 v[20:23], v[24:27], v[28:31], v[20:23]
	global_load_dwordx2 v[24:25], v[40:41], off offset:1248
	v_lshlrev_b32_e32 v70, 16, v14
	v_and_b32_e32 v14, 0xffff0000, v14
	s_waitcnt lgkmcnt(0)
	v_mfma_f32_16x16x32_bf16 v[16:19], v[80:83], v[16:19], v[20:23]
	s_waitcnt vmcnt(0)
	v_lshlrev_b32_e32 v77, 16, v25
	s_nop 5
	v_add_f32_e32 v16, v54, v16
	v_add_f32_e32 v17, v54, v17
	v_add_f32_e32 v97, v54, v18
	v_add_f32_e32 v99, v54, v19
	v_lshlrev_b32_e32 v18, 16, v24
	v_and_b32_e32 v19, 0xffff0000, v24
	v_and_b32_e32 v79, 0xffff0000, v25
	v_mul_f32_e32 v57, v16, v18
	v_mul_f32_e32 v55, v17, v19
	v_pk_mul_f32 v[80:81], v[96:97], v[76:77]
	v_pk_mul_f32 v[82:83], v[98:99], v[78:79]
	v_cvt_pk_bf16_f32 v126, v57, v55
	v_lshlrev_b32_e32 v54, 16, v12
	v_cvt_pk_bf16_f32 v125, v81, v83
	global_load_dwordx4 v[16:19], v157, s[48:49] offset:512
	global_load_dwordx4 v[20:23], v157, s[50:51] offset:512
	global_load_dwordx4 v[24:27], v157, s[48:49] offset:528
	global_load_dwordx4 v[28:31], v157, s[50:51] offset:528
	ds_read_b64 v[12:13], v160
	v_and_b32_e32 v96, 0xffff0000, v0
	v_lshlrev_b32_e32 v98, 16, v1
	v_mov_b32_e32 v76, v66
	v_mov_b32_e32 v78, v64
	s_waitcnt lgkmcnt(0)
	v_sub_f32_e32 v54, v54, v12
	v_sub_f32_e32 v15, v15, v12
	v_sub_f32_e32 v56, v56, v12
	v_mul_f32_e32 v54, v13, v54
	v_mul_f32_e32 v15, v13, v15
	v_sub_f32_e32 v63, v63, v12
	v_mul_f32_e32 v56, v13, v56
	v_sub_f32_e32 v69, v69, v12
	v_sub_f32_e32 v14, v14, v12
	v_mul_f32_e32 v63, v13, v63
	v_sub_f32_e32 v70, v70, v12
	v_mul_f32_e32 v69, v13, v69
	v_mul_f32_e32 v14, v13, v14
	v_sub_f32_e32 v72, v72, v12
	v_mul_f32_e32 v70, v13, v70
	v_mul_f32_e32 v72, v13, v72
	s_waitcnt vmcnt(2)
	v_fma_f32 v16, v16, v54, v20
	v_fma_f32 v17, v17, v56, v21
	s_waitcnt vmcnt(0)
	v_fmac_f32_e32 v31, v27, v15
	v_cvt_pk_bf16_f32 v15, v16, v33
	ds_write_b16 v155, v15 offset:34816
	v_cvt_pk_bf16_f32 v15, v17, v33
	v_fma_f32 v18, v18, v63, v22
	ds_write_b16 v155, v15 offset:35088
	v_cvt_pk_bf16_f32 v15, v18, v33
	v_fmac_f32_e32 v23, v19, v69
	v_fma_f32 v14, v25, v14, v29
	ds_write_b16 v155, v15 offset:35360
	v_cvt_pk_bf16_f32 v15, v23, v33
	v_fma_f32 v19, v24, v70, v28
	ds_write_b16 v155, v15 offset:35632
	v_cvt_pk_bf16_f32 v15, v19, v33
	ds_write_b16 v155, v15 offset:35904
	v_cvt_pk_bf16_f32 v14, v14, v33
	v_fma_f32 v20, v26, v72, v30
	ds_write_b16 v155, v14 offset:36176
	v_cvt_pk_bf16_f32 v14, v20, v33
	ds_write_b16 v155, v14 offset:36448
	v_cvt_pk_bf16_f32 v30, v31, v33
	global_load_dwordx4 v[14:17], v157, s[48:49] offset:640
	global_load_dwordx4 v[18:21], v157, s[50:51] offset:640
	global_load_dwordx4 v[22:25], v157, s[48:49] offset:656
	global_load_dwordx4 v[26:29], v157, s[50:51] offset:656
	v_lshlrev_b32_e32 v31, 16, v8
	v_and_b32_e32 v8, 0xffff0000, v8
	v_lshlrev_b32_e32 v63, 16, v11
	v_and_b32_e32 v11, 0xffff0000, v11
	v_sub_f32_e32 v8, v8, v12
	v_lshlrev_b32_e32 v54, 16, v9
	v_sub_f32_e32 v31, v31, v12
	v_sub_f32_e32 v11, v11, v12
	v_mul_f32_e32 v8, v13, v8
	v_and_b32_e32 v9, 0xffff0000, v9
	v_sub_f32_e32 v54, v54, v12
	v_mul_f32_e32 v31, v13, v31
	v_mul_f32_e32 v11, v13, v11
	v_lshlrev_b32_e32 v56, 16, v10
	v_sub_f32_e32 v9, v9, v12
	v_mul_f32_e32 v54, v13, v54
	ds_write_b16 v155, v30 offset:36720
	v_and_b32_e32 v10, 0xffff0000, v10
	v_sub_f32_e32 v56, v56, v12
	v_mul_f32_e32 v9, v13, v9
	v_sub_f32_e32 v10, v10, v12
	v_mul_f32_e32 v56, v13, v56
	v_sub_f32_e32 v63, v63, v12
	v_mul_f32_e32 v10, v13, v10
	v_mul_f32_e32 v63, v13, v63
	v_lshlrev_b32_e32 v30, 16, v7
	v_and_b32_e32 v7, 0xffff0000, v7
	v_sub_f32_e32 v7, v7, v12
	v_mul_f32_e32 v7, v13, v7
	v_sub_f32_e32 v30, v30, v12
	v_mul_f32_e32 v30, v13, v30
	v_mov_b32_e32 v69, v65
	v_mov_b32_e32 v70, v68
	v_mov_b32_e32 v72, v62
	v_mov_b32_e32 v65, v99
	s_waitcnt vmcnt(2)
	v_fma_f32 v8, v8, v15, v19
	v_fma_f32 v14, v31, v14, v18
	s_waitcnt vmcnt(0)
	v_fmac_f32_e32 v29, v11, v25
	v_cvt_pk_bf16_f32 v11, v14, v33
	ds_write_b16 v155, v11 offset:43520
	v_cvt_pk_bf16_f32 v8, v8, v33
	v_fma_f32 v15, v54, v16, v20
	ds_write_b16 v155, v8 offset:43792
	v_cvt_pk_bf16_f32 v8, v15, v33
	v_fmac_f32_e32 v21, v9, v17
	ds_write_b16 v155, v8 offset:44064
	v_cvt_pk_bf16_f32 v8, v21, v33
	v_fma_f32 v9, v56, v22, v26
	ds_write_b16 v155, v8 offset:44336
	v_cvt_pk_bf16_f32 v8, v9, v33
	v_fma_f32 v10, v10, v23, v27
	ds_write_b16 v155, v8 offset:44608
	v_cvt_pk_bf16_f32 v8, v10, v33
	v_fma_f32 v16, v63, v24, v28
	ds_write_b16 v155, v8 offset:44880
	v_cvt_pk_bf16_f32 v8, v16, v33
	ds_write_b16 v155, v8 offset:45152
	v_cvt_pk_bf16_f32 v26, v29, v33
	global_load_dwordx4 v[8:11], v157, s[48:49] offset:768
	global_load_dwordx4 v[14:17], v157, s[50:51] offset:768
	global_load_dwordx4 v[18:21], v157, s[48:49] offset:784
	global_load_dwordx4 v[22:25], v157, s[50:51] offset:784
	v_lshlrev_b32_e32 v27, 16, v4
	v_and_b32_e32 v4, 0xffff0000, v4
	v_sub_f32_e32 v4, v4, v12
	v_lshlrev_b32_e32 v28, 16, v5
	v_sub_f32_e32 v27, v27, v12
	v_mul_f32_e32 v4, v13, v4
	v_and_b32_e32 v5, 0xffff0000, v5
	v_sub_f32_e32 v28, v28, v12
	v_mul_f32_e32 v27, v13, v27
	v_lshlrev_b32_e32 v29, 16, v6
	v_sub_f32_e32 v5, v5, v12
	v_mul_f32_e32 v28, v13, v28
	ds_write_b16 v155, v26 offset:45424
	v_and_b32_e32 v6, 0xffff0000, v6
	v_sub_f32_e32 v29, v29, v12
	v_mul_f32_e32 v5, v13, v5
	v_sub_f32_e32 v6, v6, v12
	v_mul_f32_e32 v29, v13, v29
	v_mul_f32_e32 v6, v13, v6
	v_lshlrev_b32_e32 v56, 16, v0
	v_mul_f32_e32 v0, v51, v51
	v_pk_fma_f32 v[0:1], v[50:51], v[50:51], v[0:1] op_sel_hi:[1,1,0]
	v_mov_b32_e32 v63, v67
	v_mov_b32_e32 v67, v97
	s_waitcnt vmcnt(2)
	v_fma_f32 v4, v4, v9, v15
	v_fma_f32 v8, v27, v8, v14
	s_waitcnt vmcnt(0)
	v_fmac_f32_e32 v25, v7, v21
	v_cvt_pk_bf16_f32 v7, v8, v33
	ds_write_b16 v155, v7 offset:52224
	v_cvt_pk_bf16_f32 v4, v4, v33
	v_fma_f32 v9, v28, v10, v16
	ds_write_b16 v155, v4 offset:52496
	v_cvt_pk_bf16_f32 v4, v9, v33
	v_fmac_f32_e32 v17, v5, v11
	ds_write_b16 v155, v4 offset:52768
	v_cvt_pk_bf16_f32 v4, v17, v33
	v_fma_f32 v5, v29, v18, v22
	ds_write_b16 v155, v4 offset:53040
	v_cvt_pk_bf16_f32 v4, v5, v33
	v_fma_f32 v6, v6, v19, v23
	ds_write_b16 v155, v4 offset:53312
	v_cvt_pk_bf16_f32 v4, v6, v33
	v_fma_f32 v10, v30, v20, v24
	ds_write_b16 v155, v4 offset:53584
	v_cvt_pk_bf16_f32 v4, v10, v33
	ds_write_b16 v155, v4 offset:53856
	v_cvt_pk_bf16_f32 v54, v25, v33
	global_load_dwordx4 v[4:7], v157, s[48:49] offset:896
	global_load_dwordx4 v[8:11], v157, s[50:51] offset:896
	global_load_dwordx4 v[14:17], v157, s[48:49] offset:912
	global_load_dwordx4 v[18:21], v157, s[50:51] offset:912
	v_mov_b32_e32 v22, v0
	v_pk_add_f32 v[0:1], v[2:3], v[0:1]
	v_mul_f32_e32 v2, v61, v61
	v_mul_f32_e32 v24, v53, v53
	v_pk_fma_f32 v[2:3], v[60:61], v[60:61], v[2:3] op_sel_hi:[1,1,0]
	v_pk_fma_f32 v[24:25], v[52:53], v[52:53], v[24:25] op_sel_hi:[1,1,0]
	v_mov_b32_e32 v26, v2
	v_mov_b32_e32 v74, v24
	v_mov_b32_e32 v23, v85
	v_mov_b32_e32 v27, v75
	v_pk_add_f32 v[2:3], v[24:25], v[2:3]
	v_pk_fma_f32 v[24:25], v[68:69], v[70:71], v[86:87]
	v_pk_mul_f32 v[28:29], v[86:87], v[86:87]
	v_pk_fma_f32 v[30:31], v[62:63], v[72:73], v[88:89]
	v_pk_mul_f32 v[22:23], v[84:85], v[22:23]
	v_pk_mul_f32 v[26:27], v[74:75], v[26:27]
	v_mov_b32_e32 v25, v29
	v_mov_b32_e32 v31, v49
	v_mov_b32_e32 v1, v23
	v_mov_b32_e32 v3, v27
	v_pk_add_f32 v[22:23], v[24:25], v[30:31]
	v_pk_add_f32 v[0:1], v[0:1], v[2:3]
	v_sub_f32_e32 v2, v98, v12
	v_pk_add_f32 v[88:89], v[0:1], v[22:23]
	v_pk_mul_f32 v[0:1], v[92:93], v[92:93]
	ds_write_b16 v155, v54 offset:54128
	v_pk_fma_f32 v[0:1], v[90:91], v[90:91], v[0:1]
	v_sub_f32_e32 v3, v100, v12
	v_pk_add_f32 v[86:87], v[0:1], v[0:1] op_sel:[0,1] op_sel_hi:[1,0]
	v_mul_f32_e32 v0, v95, v95
	v_pk_fma_f32 v[84:85], v[94:95], v[94:95], v[0:1] op_sel_hi:[1,1,0]
	v_sub_f32_e32 v0, v56, v12
	v_mul_f32_e32 v0, v13, v0
	v_sub_f32_e32 v1, v96, v12
	v_mul_f32_e32 v1, v13, v1
	v_mul_f32_e32 v2, v13, v2
	v_sub_f32_e32 v22, v101, v12
	v_mul_f32_e32 v3, v13, v3
	v_sub_f32_e32 v23, v102, v12
	v_mul_f32_e32 v22, v13, v22
	v_sub_f32_e32 v24, v103, v12
	v_mul_f32_e32 v23, v13, v23
	v_sub_f32_e32 v12, v104, v12
	v_mul_f32_e32 v24, v13, v24
	v_mul_f32_e32 v12, v13, v12
	s_waitcnt vmcnt(2)
	v_fma_f32 v0, v0, v4, v8
	v_cvt_pk_bf16_f32 v0, v0, v33
	v_fma_f32 v1, v1, v5, v9
	ds_write_b16 v155, v0 offset:60928
	v_cvt_pk_bf16_f32 v0, v1, v33
	v_fma_f32 v2, v2, v6, v10
	ds_write_b16 v155, v0 offset:61200
	v_cvt_pk_bf16_f32 v0, v2, v33
	v_fmac_f32_e32 v11, v3, v7
	ds_write_b16 v155, v0 offset:61472
	v_cvt_pk_bf16_f32 v0, v11, v33
	s_waitcnt vmcnt(0)
	v_fma_f32 v3, v22, v14, v18
	ds_write_b16 v155, v0 offset:61744
	v_cvt_pk_bf16_f32 v0, v3, v33
	v_fma_f32 v4, v23, v15, v19
	ds_write_b16 v155, v0 offset:62016
	v_cvt_pk_bf16_f32 v0, v4, v33
	v_fma_f32 v5, v24, v16, v20
	ds_write_b16 v155, v0 offset:62288
	v_cvt_pk_bf16_f32 v0, v5, v33
	v_fmac_f32_e32 v21, v12, v17
	ds_write_b16 v155, v0 offset:62560
	v_cvt_pk_bf16_f32 v0, v21, v33
	ds_write_b16 v155, v0 offset:62832
	s_waitcnt lgkmcnt(0)
	s_barrier
	v_add_co_u32_e32 v0, vcc, s26, v42
	v_pk_fma_f32 v[66:67], v[66:67], v[76:77], v[80:81]
	s_nop 0
	v_addc_co_u32_e32 v1, vcc, 0, v43, vcc
	global_load_dwordx4 v[20:23], v[0:1], off
	global_load_dwordx4 v[24:27], v[0:1], off offset:64
	global_load_dwordx2 v[72:73], v[40:41], off offset:1280
	global_load_dwordx4 v[28:31], v[0:1], off offset:128
	global_load_dwordx4 v[16:19], v[0:1], off offset:192
	global_load_dword v48, v[44:45], off offset:512
	ds_read_b128 v[0:3], v152 offset:34816
	ds_read_b128 v[4:7], v152 offset:34880
	ds_read_b128 v[50:53], v152 offset:34944
	global_load_dwordx4 v[12:15], v[46:47], off offset:2560
	global_load_dwordx4 v[8:11], v[46:47], off offset:2624
	ds_read_b128 v[60:63], v152 offset:35008
	v_pk_mul_f32 v[76:77], v[80:81], v[80:81]
	v_pk_fma_f32 v[64:65], v[64:65], v[78:79], v[82:83]
	v_pk_mul_f32 v[78:79], v[82:83], v[82:83]
	v_mov_b32_e32 v67, v77
	v_mov_b32_e32 v65, v79
	s_waitcnt vmcnt(7) lgkmcnt(3)
	v_mfma_f32_16x16x32_bf16 v[0:3], v[0:3], v[20:23], 0
	s_waitcnt vmcnt(5)
	v_lshlrev_b32_e32 v75, 16, v73
	v_lshlrev_b32_e32 v74, 16, v72
	s_waitcnt lgkmcnt(2)
	v_mfma_f32_16x16x32_bf16 v[68:71], v[4:7], v[24:27], v[0:3]
	global_load_dwordx4 v[4:7], v[46:47], off offset:2688
	s_nop 1
	global_load_dwordx4 v[0:3], v[46:47], off offset:2752
	s_waitcnt vmcnt(0)
	v_and_b32_e32 v76, 0xffff0000, v1
	s_waitcnt lgkmcnt(1)
	v_mfma_f32_16x16x32_bf16 v[50:53], v[50:53], v[28:31], v[68:71]
	v_lshlrev_b32_e32 v77, 16, v2
	v_and_b32_e32 v78, 0xffff0000, v2
	v_lshlrev_b32_e32 v79, 16, v3
	s_waitcnt lgkmcnt(0)
	v_mfma_f32_16x16x32_bf16 v[50:53], v[60:63], v[16:19], v[50:53]
	v_and_b32_e32 v69, 0xffff0000, v73
	v_and_b32_e32 v68, 0xffff0000, v72
	v_and_b32_e32 v80, 0xffff0000, v3
	s_nop 4
	v_mov_b32_e32 v60, v50
	v_mov_b32_e32 v61, v52
	v_mov_b32_e32 v52, v51
	v_pk_add_f32 v[50:51], v[48:49], v[60:61] op_sel_hi:[0,1]
	v_pk_add_f32 v[52:53], v[48:49], v[52:53] op_sel_hi:[0,1]
	v_pk_mul_f32 v[90:91], v[50:51], v[74:75]
	v_pk_mul_f32 v[92:93], v[52:53], v[68:69]
	s_nop 0
	v_cvt_pk_bf16_f32 v156, v90, v92
	v_cvt_pk_bf16_f32 v154, v91, v93
	ds_read_b128 v[50:53], v152 offset:39168
	ds_read_b128 v[60:63], v152 offset:39232
	s_waitcnt lgkmcnt(1)
	v_mfma_f32_16x16x32_bf16 v[50:53], v[50:53], v[20:23], 0
	s_waitcnt lgkmcnt(0)
	v_mfma_f32_16x16x32_bf16 v[50:53], v[60:63], v[24:27], v[50:53]
	ds_read_b128 v[60:63], v152 offset:39296
	ds_read_b128 v[68:71], v152 offset:39360
	s_waitcnt lgkmcnt(1)
	v_mfma_f32_16x16x32_bf16 v[50:53], v[60:63], v[28:31], v[50:53]
	global_load_dwordx2 v[60:61], v[40:41], off offset:1312
	s_waitcnt vmcnt(0)
	v_lshlrev_b32_e32 v62, 16, v60
	s_waitcnt lgkmcnt(0)
	v_mfma_f32_16x16x32_bf16 v[50:53], v[68:71], v[16:19], v[50:53]
	v_and_b32_e32 v63, 0xffff0000, v60
	v_lshlrev_b32_e32 v60, 16, v61
	v_and_b32_e32 v61, 0xffff0000, v61
	s_nop 4
	v_pk_add_f32 v[50:51], v[48:49], v[50:51] op_sel_hi:[0,1]
	v_pk_add_f32 v[52:53], v[48:49], v[52:53] op_sel_hi:[0,1]
	v_pk_mul_f32 v[94:95], v[50:51], v[62:63]
	v_pk_mul_f32 v[96:97], v[52:53], v[60:61]
	v_cvt_pk_bf16_f32 v153, v94, v95
	s_nop 0
	v_cvt_pk_bf16_f32 v151, v96, v97
	ds_read_b128 v[50:53], v152 offset:43520
	ds_read_b128 v[60:63], v152 offset:43584
	s_waitcnt lgkmcnt(1)
	v_mfma_f32_16x16x32_bf16 v[50:53], v[50:53], v[20:23], 0
	s_waitcnt lgkmcnt(0)
	v_mfma_f32_16x16x32_bf16 v[50:53], v[60:63], v[24:27], v[50:53]
	ds_read_b128 v[60:63], v152 offset:43648
	ds_read_b128 v[68:71], v152 offset:43712
	s_waitcnt lgkmcnt(1)
	v_mfma_f32_16x16x32_bf16 v[50:53], v[60:63], v[28:31], v[50:53]
	global_load_dwordx2 v[60:61], v[40:41], off offset:1344
	s_waitcnt vmcnt(0)
	v_and_b32_e32 v54, 0xffff0000, v60
	s_waitcnt lgkmcnt(0)
	v_mfma_f32_16x16x32_bf16 v[50:53], v[68:71], v[16:19], v[50:53]
	v_lshlrev_b32_e32 v56, 16, v61
	v_and_b32_e32 v61, 0xffff0000, v61
	s_nop 5
	v_add_f32_e32 v49, v48, v50
	v_add_f32_e32 v50, v48, v51
	v_add_f32_e32 v51, v48, v52
	v_add_f32_e32 v52, v48, v53
	v_lshlrev_b32_e32 v53, 16, v60
	v_mul_f32_e32 v60, v49, v53
	v_mul_f32_e32 v100, v50, v54
	v_mul_f32_e32 v62, v51, v56
	v_mul_f32_e32 v98, v52, v61
	v_cvt_pk_bf16_f32 v149, v60, v100
	v_cvt_pk_bf16_f32 v147, v62, v98
	ds_read_b128 v[50:53], v152 offset:47872
	ds_read_b128 v[68:71], v152 offset:47936
	s_waitcnt lgkmcnt(1)
	v_mfma_f32_16x16x32_bf16 v[50:53], v[50:53], v[20:23], 0
	v_mov_b32_e32 v102, v60
	v_mov_b32_e32 v104, v62
	s_waitcnt lgkmcnt(0)
	v_mfma_f32_16x16x32_bf16 v[50:53], v[68:71], v[24:27], v[50:53]
	ds_read_b128 v[68:71], v152 offset:48000
	ds_read_b128 v[72:75], v152 offset:48064
	s_waitcnt lgkmcnt(1)
	v_mfma_f32_16x16x32_bf16 v[50:53], v[68:71], v[28:31], v[50:53]
	global_load_dwordx2 v[68:69], v[40:41], off offset:1376
	s_waitcnt vmcnt(0)
	v_lshlrev_b32_e32 v103, 16, v69
	s_waitcnt lgkmcnt(0)
	v_mfma_f32_16x16x32_bf16 v[50:53], v[72:75], v[16:19], v[50:53]
	v_and_b32_e32 v105, 0xffff0000, v69
	s_nop 6
	v_add_f32_e32 v49, v48, v50
	v_add_f32_e32 v50, v48, v51
	v_add_f32_e32 v61, v48, v52
	v_add_f32_e32 v63, v48, v53
	v_lshlrev_b32_e32 v51, 16, v68
	v_and_b32_e32 v52, 0xffff0000, v68
	v_mul_f32_e32 v109, v49, v51
	v_mul_f32_e32 v107, v50, v52
	v_pk_mul_f32 v[110:111], v[60:61], v[102:103]
	v_pk_mul_f32 v[112:113], v[62:63], v[104:105]
	v_cvt_pk_bf16_f32 v146, v109, v107
	v_mov_b32_e32 v101, v61
	v_cvt_pk_bf16_f32 v143, v111, v113
	ds_read_b128 v[50:53], v152 offset:52224
	ds_read_b128 v[68:71], v152 offset:52288
	s_waitcnt lgkmcnt(1)
	v_mfma_f32_16x16x32_bf16 v[50:53], v[50:53], v[20:23], 0
	v_mov_b32_e32 v99, v63
	v_mov_b32_e32 v102, v100
	v_mov_b32_e32 v104, v98
	s_waitcnt lgkmcnt(0)
	v_mfma_f32_16x16x32_bf16 v[50:53], v[68:71], v[24:27], v[50:53]
	ds_read_b128 v[68:71], v152 offset:52352
	ds_read_b128 v[72:75], v152 offset:52416
	v_mov_b32_e32 v3, v109
	s_waitcnt lgkmcnt(1)
	v_mfma_f32_16x16x32_bf16 v[50:53], v[68:71], v[28:31], v[50:53]
	global_load_dwordx2 v[68:69], v[40:41], off offset:1408
	s_waitcnt lgkmcnt(0)
	v_mfma_f32_16x16x32_bf16 v[50:53], v[72:75], v[16:19], v[50:53]
	s_nop 7
	v_mov_b32_e32 v70, v50
	v_mov_b32_e32 v71, v52
	v_mov_b32_e32 v52, v51
	v_pk_add_f32 v[50:51], v[48:49], v[70:71] op_sel_hi:[0,1]
	v_pk_add_f32 v[52:53], v[48:49], v[52:53] op_sel_hi:[0,1]
	s_waitcnt vmcnt(0)
	v_lshlrev_b32_e32 v71, 16, v69
	v_lshlrev_b32_e32 v70, 16, v68
	v_and_b32_e32 v69, 0xffff0000, v69
	v_and_b32_e32 v68, 0xffff0000, v68
	v_pk_mul_f32 v[114:115], v[50:51], v[70:71]
	v_pk_mul_f32 v[116:117], v[52:53], v[68:69]
	s_nop 0
	v_cvt_pk_bf16_f32 v144, v114, v116
	v_cvt_pk_bf16_f32 v141, v115, v117
	ds_read_b128 v[50:53], v152 offset:56576
	ds_read_b128 v[68:71], v152 offset:56640
	s_waitcnt lgkmcnt(1)
	v_mfma_f32_16x16x32_bf16 v[50:53], v[50:53], v[20:23], 0
	s_waitcnt lgkmcnt(0)
	v_mfma_f32_16x16x32_bf16 v[50:53], v[68:71], v[24:27], v[50:53]
	ds_read_b128 v[68:71], v152 offset:56704
	ds_read_b128 v[72:75], v152 offset:56768
	s_waitcnt lgkmcnt(1)
	v_mfma_f32_16x16x32_bf16 v[50:53], v[68:71], v[28:31], v[50:53]
	global_load_dwordx2 v[68:69], v[40:41], off offset:1440
	s_waitcnt lgkmcnt(0)
	v_mfma_f32_16x16x32_bf16 v[50:53], v[72:75], v[16:19], v[50:53]
	s_nop 7
	v_pk_add_f32 v[50:51], v[48:49], v[50:51] op_sel_hi:[0,1]
	v_pk_add_f32 v[70:71], v[48:49], v[52:53] op_sel_hi:[0,1]
	s_waitcnt vmcnt(0)
	v_lshlrev_b32_e32 v52, 16, v68
	v_and_b32_e32 v53, 0xffff0000, v68
	v_lshlrev_b32_e32 v68, 16, v69
	v_and_b32_e32 v69, 0xffff0000, v69
	v_pk_mul_f32 v[52:53], v[50:51], v[52:53]
	v_pk_mul_f32 v[118:119], v[70:71], v[68:69]
	v_cvt_pk_bf16_f32 v140, v52, v53
	s_nop 0
	v_cvt_pk_bf16_f32 v138, v118, v119
	ds_read_b128 v[68:71], v152 offset:60928
	ds_read_b128 v[72:75], v152 offset:60992
	s_waitcnt lgkmcnt(1)
	v_mfma_f32_16x16x32_bf16 v[68:71], v[68:71], v[20:23], 0
	s_waitcnt lgkmcnt(0)
	v_mfma_f32_16x16x32_bf16 v[68:71], v[72:75], v[24:27], v[68:71]
	ds_read_b128 v[72:75], v152 offset:61056
	ds_read_b128 v[120:123], v152 offset:61120
	global_load_dwordx2 v[50:51], v[40:41], off offset:1472
	s_waitcnt vmcnt(0)
	v_lshlrev_b32_e32 v62, 16, v50
	s_waitcnt lgkmcnt(1)
	v_mfma_f32_16x16x32_bf16 v[68:71], v[72:75], v[28:31], v[68:71]
	v_and_b32_e32 v50, 0xffff0000, v50
	s_waitcnt lgkmcnt(0)
	v_mfma_f32_16x16x32_bf16 v[68:71], v[120:123], v[16:19], v[68:71]
	s_nop 7
	v_add_f32_e32 v49, v48, v68
	v_add_f32_e32 v54, v48, v69
	v_add_f32_e32 v56, v48, v70
	v_add_f32_e32 v60, v48, v71
	v_lshlrev_b32_e32 v68, 16, v51
	v_and_b32_e32 v51, 0xffff0000, v51
	v_mul_f32_e32 v120, v49, v62
	v_mul_f32_e32 v62, v54, v50
	v_mul_f32_e32 v122, v56, v68
	v_mul_f32_e32 v60, v60, v51
	v_cvt_pk_bf16_f32 v135, v120, v62
	v_cvt_pk_bf16_f32 v131, v122, v60
	ds_read_b128 v[68:71], v152 offset:65280
	ds_read_b128 v[72:75], v152 offset:65344
	s_waitcnt lgkmcnt(1)
	v_mfma_f32_16x16x32_bf16 v[20:23], v[68:71], v[20:23], 0
	v_mov_b32_e32 v68, v120
	v_mov_b32_e32 v70, v122
	v_and_b32_e32 v50, 0xffff0000, v12
	s_waitcnt lgkmcnt(0)
	v_mfma_f32_16x16x32_bf16 v[20:23], v[72:75], v[24:27], v[20:23]
	ds_read_b128 v[24:27], v152 offset:65408
	ds_read_b128 v[72:75], v152 offset:65472
	v_lshlrev_b32_e32 v54, 16, v13
	v_and_b32_e32 v56, 0xffff0000, v13
	s_waitcnt lgkmcnt(1)
	v_mfma_f32_16x16x32_bf16 v[20:23], v[24:27], v[28:31], v[20:23]
	global_load_dwordx2 v[24:25], v[40:41], off offset:1504
	s_waitcnt vmcnt(0)
	v_lshlrev_b32_e32 v69, 16, v25
	s_waitcnt lgkmcnt(0)
	v_mfma_f32_16x16x32_bf16 v[16:19], v[72:75], v[16:19], v[20:23]
	v_and_b32_e32 v71, 0xffff0000, v25
	s_nop 6
	v_add_f32_e32 v16, v48, v16
	v_add_f32_e32 v17, v48, v17
	v_add_f32_e32 v121, v48, v18
	v_add_f32_e32 v123, v48, v19
	v_lshlrev_b32_e32 v18, 16, v24
	v_and_b32_e32 v19, 0xffff0000, v24
	v_mul_f32_e32 v51, v16, v18
	v_mul_f32_e32 v49, v17, v19
	v_pk_mul_f32 v[72:73], v[120:121], v[68:69]
	v_pk_mul_f32 v[74:75], v[122:123], v[70:71]
	v_cvt_pk_bf16_f32 v122, v51, v49
	v_lshlrev_b32_e32 v48, 16, v12
	v_cvt_pk_bf16_f32 v120, v73, v75
	global_load_dwordx4 v[16:19], v157, s[48:49] offset:1024
	global_load_dwordx4 v[20:23], v157, s[50:51] offset:1024
	global_load_dwordx4 v[24:27], v157, s[48:49] offset:1040
	global_load_dwordx4 v[28:31], v157, s[50:51] offset:1040
	ds_read_b64 v[12:13], v160
	v_lshlrev_b32_e32 v70, 16, v15
	v_and_b32_e32 v15, 0xffff0000, v15
	v_lshlrev_b32_e32 v68, 16, v14
	v_and_b32_e32 v14, 0xffff0000, v14
	s_waitcnt lgkmcnt(0)
	v_sub_f32_e32 v48, v48, v12
	v_sub_f32_e32 v15, v15, v12
	v_sub_f32_e32 v50, v50, v12
	v_mul_f32_e32 v48, v13, v48
	v_mul_f32_e32 v15, v13, v15
	v_sub_f32_e32 v54, v54, v12
	v_mul_f32_e32 v50, v13, v50
	v_sub_f32_e32 v56, v56, v12
	v_sub_f32_e32 v14, v14, v12
	v_mul_f32_e32 v54, v13, v54
	v_sub_f32_e32 v68, v68, v12
	v_mul_f32_e32 v56, v13, v56
	v_mul_f32_e32 v14, v13, v14
	v_sub_f32_e32 v70, v70, v12
	v_mul_f32_e32 v68, v13, v68
	v_mul_f32_e32 v70, v13, v70
	v_mov_b32_e32 v63, v121
	v_mov_b32_e32 v61, v123
	s_waitcnt vmcnt(2)
	v_fma_f32 v16, v16, v48, v20
	v_fma_f32 v17, v17, v50, v21
	s_waitcnt vmcnt(0)
	v_fmac_f32_e32 v31, v27, v15
	v_cvt_pk_bf16_f32 v15, v16, v33
	ds_write_b16 v155, v15
	v_cvt_pk_bf16_f32 v15, v17, v33
	v_fma_f32 v18, v18, v54, v22
	ds_write_b16 v155, v15 offset:272
	v_cvt_pk_bf16_f32 v15, v18, v33
	v_fmac_f32_e32 v23, v19, v56
	v_fma_f32 v14, v25, v14, v29
	ds_write_b16 v155, v15 offset:544
	v_cvt_pk_bf16_f32 v15, v23, v33
	v_fma_f32 v19, v24, v68, v28
	ds_write_b16 v155, v15 offset:816
	v_cvt_pk_bf16_f32 v15, v19, v33
	ds_write_b16 v155, v15 offset:1088
	v_cvt_pk_bf16_f32 v14, v14, v33
	v_fma_f32 v20, v26, v70, v30
	ds_write_b16 v155, v14 offset:1360
	v_cvt_pk_bf16_f32 v14, v20, v33
	ds_write_b16 v155, v14 offset:1632
	v_cvt_pk_bf16_f32 v30, v31, v33
	global_load_dwordx4 v[14:17], v157, s[48:49] offset:1152
	global_load_dwordx4 v[18:21], v157, s[50:51] offset:1152
	global_load_dwordx4 v[22:25], v157, s[48:49] offset:1168
	global_load_dwordx4 v[26:29], v157, s[50:51] offset:1168
	v_lshlrev_b32_e32 v31, 16, v8
	v_and_b32_e32 v8, 0xffff0000, v8
	v_lshlrev_b32_e32 v54, 16, v11
	v_and_b32_e32 v11, 0xffff0000, v11
	v_sub_f32_e32 v8, v8, v12
	v_lshlrev_b32_e32 v48, 16, v9
	v_sub_f32_e32 v31, v31, v12
	v_sub_f32_e32 v11, v11, v12
	v_mul_f32_e32 v8, v13, v8
	v_and_b32_e32 v9, 0xffff0000, v9
	v_sub_f32_e32 v48, v48, v12
	v_mul_f32_e32 v31, v13, v31
	v_mul_f32_e32 v11, v13, v11
	v_lshlrev_b32_e32 v50, 16, v10
	v_sub_f32_e32 v9, v9, v12
	v_mul_f32_e32 v48, v13, v48
	ds_write_b16 v155, v30 offset:1904
	v_and_b32_e32 v10, 0xffff0000, v10
	v_sub_f32_e32 v50, v50, v12
	v_mul_f32_e32 v9, v13, v9
	v_sub_f32_e32 v10, v10, v12
	v_mul_f32_e32 v50, v13, v50
	v_sub_f32_e32 v54, v54, v12
	v_mul_f32_e32 v10, v13, v10
	v_mul_f32_e32 v54, v13, v54
	v_mul_f32_e32 v30, v59, v59
	v_mov_b32_e32 v68, v62
	v_mov_b32_e32 v70, v60
	s_waitcnt vmcnt(2)
	v_fma_f32 v8, v8, v15, v19
	v_fma_f32 v14, v31, v14, v18
	s_waitcnt vmcnt(0)
	v_fmac_f32_e32 v29, v11, v25
	v_cvt_pk_bf16_f32 v11, v14, v33
	ds_write_b16 v155, v11 offset:8704
	v_cvt_pk_bf16_f32 v8, v8, v33
	v_fma_f32 v15, v48, v16, v20
	ds_write_b16 v155, v8 offset:8976
	v_cvt_pk_bf16_f32 v8, v15, v33
	v_fmac_f32_e32 v21, v9, v17
	ds_write_b16 v155, v8 offset:9248
	v_cvt_pk_bf16_f32 v8, v21, v33
	v_fma_f32 v9, v50, v22, v26
	ds_write_b16 v155, v8 offset:9520
	v_cvt_pk_bf16_f32 v8, v9, v33
	v_fma_f32 v10, v10, v23, v27
	ds_write_b16 v155, v8 offset:9792
	v_cvt_pk_bf16_f32 v8, v10, v33
	v_fma_f32 v16, v54, v24, v28
	ds_write_b16 v155, v8 offset:10064
	v_cvt_pk_bf16_f32 v8, v16, v33
	ds_write_b16 v155, v8 offset:10336
	v_cvt_pk_bf16_f32 v48, v29, v33
	global_load_dwordx4 v[8:11], v157, s[48:49] offset:1280
	global_load_dwordx4 v[14:17], v157, s[50:51] offset:1280
	global_load_dwordx4 v[18:21], v157, s[48:49] offset:1296
	global_load_dwordx4 v[22:25], v157, s[50:51] offset:1296
	v_pk_add_f32 v[26:27], v[88:89], v[88:89] op_sel:[0,1] op_sel_hi:[1,0]
	v_pk_fma_f32 v[30:31], v[58:59], v[58:59], v[30:31] op_sel_hi:[1,1,0]
	v_mov_b32_e32 v56, v26
	v_pk_add_f32 v[26:27], v[26:27], v[86:87]
	v_lshlrev_b32_e32 v58, 16, v7
	v_lshlrev_b32_e32 v27, 16, v4
	v_and_b32_e32 v4, 0xffff0000, v4
	v_and_b32_e32 v7, 0xffff0000, v7
	v_sub_f32_e32 v4, v4, v12
	v_lshlrev_b32_e32 v50, 16, v5
	v_sub_f32_e32 v27, v27, v12
	v_sub_f32_e32 v7, v7, v12
	v_mul_f32_e32 v4, v13, v4
	v_and_b32_e32 v5, 0xffff0000, v5
	v_sub_f32_e32 v50, v50, v12
	v_mul_f32_e32 v27, v13, v27
	v_mul_f32_e32 v7, v13, v7
	v_lshlrev_b32_e32 v54, 16, v6
	v_sub_f32_e32 v5, v5, v12
	v_mul_f32_e32 v50, v13, v50
	ds_write_b16 v155, v48 offset:10608
	v_and_b32_e32 v6, 0xffff0000, v6
	v_sub_f32_e32 v54, v54, v12
	v_mul_f32_e32 v5, v13, v5
	v_sub_f32_e32 v6, v6, v12
	v_mul_f32_e32 v54, v13, v54
	v_sub_f32_e32 v58, v58, v12
	v_mul_f32_e32 v6, v13, v6
	v_mul_f32_e32 v58, v13, v58
	v_mov_b32_e32 v28, v86
	v_mov_b32_e32 v29, v57
	v_mov_b32_e32 v88, v84
	v_mov_b32_e32 v89, v55
	s_waitcnt vmcnt(2)
	v_fma_f32 v4, v4, v9, v15
	v_fma_f32 v8, v27, v8, v14
	s_waitcnt vmcnt(0)
	v_fmac_f32_e32 v25, v7, v21
	v_cvt_pk_bf16_f32 v7, v8, v33
	ds_write_b16 v155, v7 offset:17408
	v_cvt_pk_bf16_f32 v4, v4, v33
	v_fma_f32 v9, v50, v10, v16
	ds_write_b16 v155, v4 offset:17680
	v_cvt_pk_bf16_f32 v4, v9, v33
	v_fmac_f32_e32 v17, v5, v11
	ds_write_b16 v155, v4 offset:17952
	v_cvt_pk_bf16_f32 v4, v17, v33
	v_fma_f32 v5, v54, v18, v22
	ds_write_b16 v155, v4 offset:18224
	v_cvt_pk_bf16_f32 v4, v5, v33
	v_fma_f32 v6, v6, v19, v23
	ds_write_b16 v155, v4 offset:18496
	v_cvt_pk_bf16_f32 v4, v6, v33
	v_fma_f32 v10, v58, v20, v24
	ds_write_b16 v155, v4 offset:18768
	v_cvt_pk_bf16_f32 v4, v10, v33
	ds_write_b16 v155, v4 offset:19040
	v_cvt_pk_bf16_f32 v48, v25, v33
	global_load_dwordx4 v[4:7], v157, s[48:49] offset:1408
	global_load_dwordx4 v[8:11], v157, s[50:51] offset:1408
	global_load_dwordx4 v[14:17], v157, s[48:49] offset:1424
	global_load_dwordx4 v[18:21], v157, s[50:51] offset:1424
	v_pk_mul_f32 v[22:23], v[56:57], v[28:29]
	v_mov_b32_e32 v54, v30
	v_pk_add_f32 v[24:25], v[30:31], v[84:85]
	v_mov_b32_e32 v27, v23
	v_pk_mul_f32 v[22:23], v[54:55], v[88:89]
	v_pk_add_f32 v[28:29], v[66:67], v[64:65]
	v_mov_b32_e32 v25, v23
	v_pk_add_f32 v[22:23], v[26:27], v[24:25]
	v_lshlrev_b32_e32 v50, 16, v0
	v_and_b32_e32 v56, 0xffff0000, v0
	v_lshlrev_b32_e32 v57, 16, v1
	v_pk_mul_f32 v[0:1], v[92:93], v[92:93]
	v_pk_add_f32 v[22:23], v[22:23], v[28:29]
	v_pk_fma_f32 v[0:1], v[90:91], v[90:91], v[0:1]
	v_pk_add_f32 v[22:23], v[22:23], v[22:23] op_sel:[0,1] op_sel_hi:[1,0]
	v_pk_add_f32 v[0:1], v[0:1], v[0:1] op_sel:[0,1] op_sel_hi:[1,0]
	v_mov_b32_e32 v108, v22
	v_mov_b32_e32 v2, v0
	v_pk_add_f32 v[0:1], v[22:23], v[0:1]
	v_mul_f32_e32 v22, v97, v97
	v_mul_f32_e32 v24, v95, v95
	v_pk_fma_f32 v[22:23], v[96:97], v[96:97], v[22:23] op_sel_hi:[1,1,0]
	v_pk_fma_f32 v[24:25], v[94:95], v[94:95], v[24:25] op_sel_hi:[1,1,0]
	v_mov_b32_e32 v26, v22
	v_mov_b32_e32 v106, v24
	v_mov_b32_e32 v27, v107
	v_pk_add_f32 v[22:23], v[24:25], v[22:23]
	v_pk_fma_f32 v[24:25], v[100:101], v[102:103], v[110:111]
	v_pk_mul_f32 v[28:29], v[110:111], v[110:111]
	v_pk_fma_f32 v[30:31], v[98:99], v[104:105], v[112:113]
	v_pk_mul_f32 v[54:55], v[112:113], v[112:113]
	v_pk_mul_f32 v[2:3], v[108:109], v[2:3]
	v_pk_mul_f32 v[26:27], v[106:107], v[26:27]
	v_mov_b32_e32 v25, v29
	v_mov_b32_e32 v31, v55
	v_mov_b32_e32 v1, v3
	v_mov_b32_e32 v23, v27
	v_pk_add_f32 v[2:3], v[24:25], v[30:31]
	v_pk_add_f32 v[0:1], v[0:1], v[22:23]
	ds_write_b16 v155, v48 offset:19312
	v_pk_add_f32 v[66:67], v[0:1], v[2:3]
	v_pk_mul_f32 v[0:1], v[116:117], v[116:117]
	v_sub_f32_e32 v2, v57, v12
	v_pk_fma_f32 v[0:1], v[114:115], v[114:115], v[0:1]
	v_sub_f32_e32 v3, v76, v12
	v_pk_add_f32 v[64:65], v[0:1], v[0:1] op_sel:[0,1] op_sel_hi:[1,0]
	v_mul_f32_e32 v0, v119, v119
	v_pk_fma_f32 v[58:59], v[118:119], v[118:119], v[0:1] op_sel_hi:[1,1,0]
	v_sub_f32_e32 v0, v50, v12
	v_mul_f32_e32 v0, v13, v0
	v_sub_f32_e32 v1, v56, v12
	v_mul_f32_e32 v1, v13, v1
	v_mul_f32_e32 v2, v13, v2
	v_sub_f32_e32 v22, v77, v12
	v_mul_f32_e32 v3, v13, v3
	v_sub_f32_e32 v23, v78, v12
	v_mul_f32_e32 v22, v13, v22
	v_sub_f32_e32 v24, v79, v12
	v_mul_f32_e32 v23, v13, v23
	v_sub_f32_e32 v12, v80, v12
	v_mul_f32_e32 v24, v13, v24
	v_mul_f32_e32 v12, v13, v12
	s_waitcnt vmcnt(2)
	v_fma_f32 v0, v0, v4, v8
	v_cvt_pk_bf16_f32 v0, v0, v33
	v_fma_f32 v1, v1, v5, v9
	ds_write_b16 v155, v0 offset:26112
	v_cvt_pk_bf16_f32 v0, v1, v33
	v_fma_f32 v2, v2, v6, v10
	ds_write_b16 v155, v0 offset:26384
	v_cvt_pk_bf16_f32 v0, v2, v33
	v_fmac_f32_e32 v11, v3, v7
	ds_write_b16 v155, v0 offset:26656
	v_cvt_pk_bf16_f32 v0, v11, v33
	s_waitcnt vmcnt(0)
	v_fma_f32 v3, v22, v14, v18
	ds_write_b16 v155, v0 offset:26928
	v_cvt_pk_bf16_f32 v0, v3, v33
	v_fma_f32 v4, v23, v15, v19
	ds_write_b16 v155, v0 offset:27200
	v_cvt_pk_bf16_f32 v0, v4, v33
	v_fma_f32 v5, v24, v16, v20
	ds_write_b16 v155, v0 offset:27472
	v_cvt_pk_bf16_f32 v0, v5, v33
	v_fmac_f32_e32 v21, v12, v17
	ds_write_b16 v155, v0 offset:27744
	v_cvt_pk_bf16_f32 v0, v21, v33
	ds_write_b16 v155, v0 offset:28016
	s_waitcnt lgkmcnt(0)
	s_barrier
	v_add_co_u32_e32 v0, vcc, s27, v42
	v_pk_fma_f32 v[68:69], v[62:63], v[68:69], v[72:73]
	s_nop 0
	v_addc_co_u32_e32 v1, vcc, 0, v43, vcc
	global_load_dwordx4 v[20:23], v[0:1], off
	global_load_dwordx4 v[24:27], v[0:1], off offset:64
	global_load_dwordx2 v[84:85], v[40:41], off offset:1536
	global_load_dwordx4 v[28:31], v[0:1], off offset:128
	global_load_dwordx4 v[16:19], v[0:1], off offset:192
	global_load_dword v48, v[44:45], off offset:1024
	ds_read_b128 v[0:3], v152
	ds_read_b128 v[4:7], v152 offset:64
	ds_read_b128 v[54:57], v152 offset:128
	global_load_dwordx4 v[12:15], v[46:47], off offset:2816
	global_load_dwordx4 v[8:11], v[46:47], off offset:2880
	ds_read_b128 v[76:79], v152 offset:192
	v_pk_mul_f32 v[62:63], v[72:73], v[72:73]
	v_pk_fma_f32 v[70:71], v[60:61], v[70:71], v[74:75]
	v_pk_mul_f32 v[60:61], v[74:75], v[74:75]
	v_mov_b32_e32 v69, v63
	v_mov_b32_e32 v71, v61
	s_waitcnt vmcnt(7) lgkmcnt(3)
	v_mfma_f32_16x16x32_bf16 v[0:3], v[0:3], v[20:23], 0
	s_waitcnt vmcnt(6) lgkmcnt(2)
	v_mfma_f32_16x16x32_bf16 v[80:83], v[4:7], v[24:27], v[0:3]
	global_load_dwordx4 v[4:7], v[46:47], off offset:2944
	s_nop 4
	global_load_dwordx4 v[0:3], v[46:47], off offset:3008
	s_waitcnt vmcnt(7)
	v_lshlrev_b32_e32 v47, 16, v85
	v_lshlrev_b32_e32 v46, 16, v84
	s_waitcnt vmcnt(6) lgkmcnt(1)
	v_mfma_f32_16x16x32_bf16 v[54:57], v[54:57], v[28:31], v[80:83]
	s_waitcnt vmcnt(0)
	v_and_b32_e32 v72, 0xffff0000, v2
	s_waitcnt lgkmcnt(0)
	v_mfma_f32_16x16x32_bf16 v[54:57], v[76:79], v[16:19], v[54:57]
	v_and_b32_e32 v81, 0xffff0000, v85
	v_and_b32_e32 v80, 0xffff0000, v84
	v_lshlrev_b32_e32 v73, 16, v3
	v_and_b32_e32 v74, 0xffff0000, v3
	s_nop 3
	v_mov_b32_e32 v76, v54
	v_mov_b32_e32 v77, v56
	v_mov_b32_e32 v56, v55
	v_pk_add_f32 v[54:55], v[48:49], v[76:77] op_sel_hi:[0,1]
	v_pk_add_f32 v[56:57], v[48:49], v[56:57] op_sel_hi:[0,1]
	v_pk_mul_f32 v[76:77], v[54:55], v[46:47]
	v_pk_mul_f32 v[78:79], v[56:57], v[80:81]
	s_nop 0
	v_cvt_pk_bf16_f32 v159, v76, v78
	v_cvt_pk_bf16_f32 v158, v77, v79
	ds_read_b128 v[54:57], v152 offset:4352
	ds_read_b128 v[80:83], v152 offset:4416
	s_waitcnt lgkmcnt(1)
	v_mfma_f32_16x16x32_bf16 v[54:57], v[54:57], v[20:23], 0
	s_waitcnt lgkmcnt(0)
	v_mfma_f32_16x16x32_bf16 v[54:57], v[80:83], v[24:27], v[54:57]
	ds_read_b128 v[80:83], v152 offset:4480
	ds_read_b128 v[84:87], v152 offset:4544
	global_load_dwordx2 v[46:47], v[40:41], off offset:1568
	s_waitcnt lgkmcnt(1)
	v_mfma_f32_16x16x32_bf16 v[54:57], v[80:83], v[28:31], v[54:57]
	s_waitcnt vmcnt(0)
	v_lshlrev_b32_e32 v80, 16, v46
	s_waitcnt lgkmcnt(0)
	v_mfma_f32_16x16x32_bf16 v[54:57], v[84:87], v[16:19], v[54:57]
	v_and_b32_e32 v81, 0xffff0000, v46
	v_lshlrev_b32_e32 v46, 16, v47
	v_and_b32_e32 v47, 0xffff0000, v47
	s_nop 4
	v_pk_add_f32 v[54:55], v[48:49], v[54:55] op_sel_hi:[0,1]
	v_pk_add_f32 v[56:57], v[48:49], v[56:57] op_sel_hi:[0,1]
	v_pk_mul_f32 v[80:81], v[54:55], v[80:81]
	v_pk_mul_f32 v[82:83], v[56:57], v[46:47]
	v_cvt_pk_bf16_f32 v123, v80, v81
	s_nop 0
	v_cvt_pk_bf16_f32 v121, v82, v83
	ds_read_b128 v[54:57], v152 offset:8704
	ds_read_b128 v[84:87], v152 offset:8768
	s_waitcnt lgkmcnt(1)
	v_mfma_f32_16x16x32_bf16 v[54:57], v[54:57], v[20:23], 0
	s_waitcnt lgkmcnt(0)
	v_mfma_f32_16x16x32_bf16 v[54:57], v[84:87], v[24:27], v[54:57]
	ds_read_b128 v[84:87], v152 offset:8832
	ds_read_b128 v[88:91], v152 offset:8896
	global_load_dwordx2 v[46:47], v[40:41], off offset:1600
	s_waitcnt lgkmcnt(1)
	v_mfma_f32_16x16x32_bf16 v[54:57], v[84:87], v[28:31], v[54:57]
	s_waitcnt vmcnt(0)
	v_lshlrev_b32_e32 v84, 16, v47
	s_waitcnt lgkmcnt(0)
	v_mfma_f32_16x16x32_bf16 v[54:57], v[88:91], v[16:19], v[54:57]
	v_and_b32_e32 v47, 0xffff0000, v47
	s_nop 6
	v_add_f32_e32 v50, v48, v54
	v_add_f32_e32 v55, v48, v55
	v_add_f32_e32 v56, v48, v56
	v_add_f32_e32 v57, v48, v57
	v_lshlrev_b32_e32 v54, 16, v46
	v_and_b32_e32 v46, 0xffff0000, v46
	v_mul_f32_e32 v54, v50, v54
	v_mul_f32_e32 v86, v55, v46
	v_mul_f32_e32 v56, v56, v84
	v_mul_f32_e32 v84, v57, v47
	v_cvt_pk_bf16_f32 v119, v54, v86
	v_cvt_pk_bf16_f32 v118, v56, v84
	ds_read_b128 v[88:91], v152 offset:13056
	ds_read_b128 v[92:95], v152 offset:13120
	s_waitcnt lgkmcnt(1)
	v_mfma_f32_16x16x32_bf16 v[88:91], v[88:91], v[20:23], 0
	s_waitcnt lgkmcnt(0)
	v_mfma_f32_16x16x32_bf16 v[88:91], v[92:95], v[24:27], v[88:91]
	ds_read_b128 v[92:95], v152 offset:13184
	ds_read_b128 v[96:99], v152 offset:13248
	global_load_dwordx2 v[46:47], v[40:41], off offset:1632
	s_waitcnt vmcnt(0)
	v_lshlrev_b32_e32 v87, 16, v46
	s_waitcnt lgkmcnt(1)
	v_mfma_f32_16x16x32_bf16 v[92:95], v[92:95], v[28:31], v[88:91]
	v_and_b32_e32 v46, 0xffff0000, v46
	s_waitcnt lgkmcnt(0)
	v_mfma_f32_16x16x32_bf16 v[92:95], v[96:99], v[16:19], v[92:95]
	v_mov_b32_e32 v88, v54
	v_mov_b32_e32 v90, v56
	v_lshlrev_b32_e32 v89, 16, v47
	v_and_b32_e32 v91, 0xffff0000, v47
	s_nop 3
	v_add_f32_e32 v50, v48, v92
	v_add_f32_e32 v85, v48, v93
	v_add_f32_e32 v55, v48, v94
	v_add_f32_e32 v57, v48, v95
	v_mul_f32_e32 v95, v50, v87
	v_mul_f32_e32 v93, v85, v46
	v_pk_mul_f32 v[96:97], v[54:55], v[88:89]
	v_pk_mul_f32 v[98:99], v[56:57], v[90:91]
	v_cvt_pk_bf16_f32 v117, v95, v93
	v_mov_b32_e32 v3, v95
	v_cvt_pk_bf16_f32 v115, v97, v99
	ds_read_b128 v[100:103], v152 offset:17408
	ds_read_b128 v[104:107], v152 offset:17472
	s_waitcnt lgkmcnt(1)
	v_mfma_f32_16x16x32_bf16 v[100:103], v[100:103], v[20:23], 0
	s_waitcnt lgkmcnt(0)
	v_mfma_f32_16x16x32_bf16 v[100:103], v[104:107], v[24:27], v[100:103]
	ds_read_b128 v[104:107], v152 offset:17536
	ds_read_b128 v[108:111], v152 offset:17600
	global_load_dwordx2 v[46:47], v[40:41], off offset:1664
	s_waitcnt lgkmcnt(1)
	v_mfma_f32_16x16x32_bf16 v[100:103], v[104:107], v[28:31], v[100:103]
	s_waitcnt lgkmcnt(0)
	v_mfma_f32_16x16x32_bf16 v[100:103], v[108:111], v[16:19], v[100:103]
	s_nop 7
	v_mov_b32_e32 v104, v100
	v_mov_b32_e32 v105, v102
	v_mov_b32_e32 v102, v101
	v_pk_add_f32 v[100:101], v[48:49], v[104:105] op_sel_hi:[0,1]
	v_pk_add_f32 v[102:103], v[48:49], v[102:103] op_sel_hi:[0,1]
	s_waitcnt vmcnt(0)
	v_lshlrev_b32_e32 v105, 16, v47
	v_lshlrev_b32_e32 v104, 16, v46
	v_and_b32_e32 v47, 0xffff0000, v47
	v_and_b32_e32 v46, 0xffff0000, v46
	v_pk_mul_f32 v[100:101], v[100:101], v[104:105]
	v_pk_mul_f32 v[102:103], v[102:103], v[46:47]
	s_nop 0
	v_cvt_pk_bf16_f32 v116, v100, v102
	v_cvt_pk_bf16_f32 v114, v101, v103
	ds_read_b128 v[104:107], v152 offset:21760
	ds_read_b128 v[108:111], v152 offset:21824
	s_waitcnt lgkmcnt(1)
	v_mfma_f32_16x16x32_bf16 v[104:107], v[104:107], v[20:23], 0
	s_waitcnt lgkmcnt(0)
	v_mfma_f32_16x16x32_bf16 v[104:107], v[108:111], v[24:27], v[104:107]
	ds_read_b128 v[108:111], v152 offset:21888
	ds_read_b128 v[162:165], v152 offset:21952
	global_load_dwordx2 v[46:47], v[40:41], off offset:1696
	s_waitcnt lgkmcnt(1)
	v_mfma_f32_16x16x32_bf16 v[104:107], v[108:111], v[28:31], v[104:107]
	s_waitcnt vmcnt(0)
	v_lshlrev_b32_e32 v108, 16, v46
	s_waitcnt lgkmcnt(0)
	v_mfma_f32_16x16x32_bf16 v[104:107], v[162:165], v[16:19], v[104:107]
	v_and_b32_e32 v109, 0xffff0000, v46
	v_lshlrev_b32_e32 v110, 16, v47
	v_and_b32_e32 v111, 0xffff0000, v47
	s_nop 4
	v_pk_add_f32 v[104:105], v[48:49], v[104:105] op_sel_hi:[0,1]
	v_pk_add_f32 v[106:107], v[48:49], v[106:107] op_sel_hi:[0,1]
	v_pk_mul_f32 v[46:47], v[104:105], v[108:109]
	v_pk_mul_f32 v[104:105], v[106:107], v[110:111]
	v_cvt_pk_bf16_f32 v113, v46, v47
	s_nop 0
	v_cvt_pk_bf16_f32 v112, v104, v105
	ds_read_b128 v[106:109], v152 offset:26112
	ds_read_b128 v[162:165], v152 offset:26176
	s_waitcnt lgkmcnt(1)
	v_mfma_f32_16x16x32_bf16 v[106:109], v[106:109], v[20:23], 0
	s_waitcnt lgkmcnt(0)
	v_mfma_f32_16x16x32_bf16 v[106:109], v[162:165], v[24:27], v[106:109]
	ds_read_b128 v[162:165], v152 offset:26240
	ds_read_b128 v[166:169], v152 offset:26304
	global_load_dwordx2 v[110:111], v[40:41], off offset:1728
	s_waitcnt vmcnt(0)
	v_lshlrev_b32_e32 v56, 16, v110
	s_waitcnt lgkmcnt(1)
	v_mfma_f32_16x16x32_bf16 v[106:109], v[162:165], v[28:31], v[106:109]
	v_and_b32_e32 v88, 0xffff0000, v110
	v_lshlrev_b32_e32 v90, 16, v111
	v_and_b32_e32 v92, 0xffff0000, v111
	s_waitcnt lgkmcnt(0)
	v_mfma_f32_16x16x32_bf16 v[106:109], v[166:169], v[16:19], v[106:109]
	s_nop 7
	v_add_f32_e32 v50, v48, v106
	v_add_f32_e32 v54, v48, v107
	v_add_f32_e32 v85, v48, v108
	v_add_f32_e32 v87, v48, v109
	v_mul_f32_e32 v106, v50, v56
	v_mul_f32_e32 v56, v54, v88
	v_mul_f32_e32 v108, v85, v90
	v_mul_f32_e32 v54, v87, v92
	v_cvt_pk_bf16_f32 v111, v106, v56
	v_cvt_pk_bf16_f32 v110, v108, v54
	ds_read_b128 v[162:165], v152 offset:30464
	ds_read_b128 v[166:169], v152 offset:30528
	s_waitcnt lgkmcnt(1)
	v_mfma_f32_16x16x32_bf16 v[20:23], v[162:165], v[20:23], 0
	v_mov_b32_e32 v87, v55
	v_mov_b32_e32 v85, v57
	v_mov_b32_e32 v88, v86
	s_waitcnt lgkmcnt(0)
	v_mfma_f32_16x16x32_bf16 v[20:23], v[166:169], v[24:27], v[20:23]
	ds_read_b128 v[24:27], v152 offset:30592
	ds_read_b128 v[162:165], v152 offset:30656
	v_mov_b32_e32 v90, v84
	s_waitcnt lgkmcnt(1)
	v_mfma_f32_16x16x32_bf16 v[24:27], v[24:27], v[28:31], v[20:23]
	global_load_dwordx2 v[28:29], v[40:41], off offset:1760
	v_lshlrev_b32_e32 v30, 16, v15
	s_nop 0
	v_mov_b32_e32 v20, v106
	s_waitcnt lgkmcnt(0)
	v_mfma_f32_16x16x32_bf16 v[16:19], v[162:165], v[16:19], v[24:27]
	v_mov_b32_e32 v22, v108
	v_and_b32_e32 v15, 0xffff0000, v15
	v_mov_b32_e32 v31, v51
	s_waitcnt vmcnt(0)
	v_and_b32_e32 v24, 0xffff0000, v28
	s_nop 2
	v_add_f32_e32 v16, v48, v16
	v_add_f32_e32 v17, v48, v17
	v_add_f32_e32 v107, v48, v18
	v_add_f32_e32 v109, v48, v19
	v_lshlrev_b32_e32 v18, 16, v28
	v_lshlrev_b32_e32 v21, 16, v29
	v_and_b32_e32 v23, 0xffff0000, v29
	v_mul_f32_e32 v19, v16, v18
	v_mul_f32_e32 v17, v17, v24
	v_pk_mul_f32 v[26:27], v[106:107], v[20:21]
	v_pk_mul_f32 v[24:25], v[108:109], v[22:23]
	v_cvt_pk_bf16_f32 v106, v19, v17
	v_lshlrev_b32_e32 v16, 16, v12
	v_cvt_pk_bf16_f32 v29, v27, v25
	global_load_dwordx4 v[162:165], v157, s[48:49] offset:1536
	global_load_dwordx4 v[166:169], v157, s[50:51] offset:1536
	global_load_dwordx4 v[170:173], v157, s[48:49] offset:1552
	global_load_dwordx4 v[174:177], v157, s[50:51] offset:1552
	v_and_b32_e32 v18, 0xffff0000, v12
	v_lshlrev_b32_e32 v20, 16, v13
	v_and_b32_e32 v22, 0xffff0000, v13
	ds_read_b64 v[12:13], v160
	v_lshlrev_b32_e32 v28, 16, v14
	v_and_b32_e32 v14, 0xffff0000, v14
	v_mov_b32_e32 v57, v107
	v_mov_b32_e32 v55, v109
	s_waitcnt lgkmcnt(0)
	v_sub_f32_e32 v16, v16, v12
	v_sub_f32_e32 v15, v15, v12
	v_sub_f32_e32 v18, v18, v12
	v_mul_f32_e32 v16, v13, v16
	v_mul_f32_e32 v15, v13, v15
	v_sub_f32_e32 v20, v20, v12
	v_mul_f32_e32 v18, v13, v18
	v_sub_f32_e32 v22, v22, v12
	v_sub_f32_e32 v14, v14, v12
	v_mul_f32_e32 v20, v13, v20
	v_sub_f32_e32 v28, v28, v12
	v_mul_f32_e32 v22, v13, v22
	v_mul_f32_e32 v14, v13, v14
	v_sub_f32_e32 v30, v30, v12
	v_mul_f32_e32 v28, v13, v28
	v_mul_f32_e32 v30, v13, v30
	s_waitcnt vmcnt(2)
	v_fma_f32 v16, v162, v16, v166
	v_fma_f32 v18, v163, v18, v167
	s_waitcnt vmcnt(0)
	v_fmac_f32_e32 v177, v173, v15
	v_cvt_pk_bf16_f32 v15, v16, v33
	ds_write_b16 v155, v15 offset:34816
	v_cvt_pk_bf16_f32 v15, v18, v33
	v_fma_f32 v20, v164, v20, v168
	ds_write_b16 v155, v15 offset:35088
	v_cvt_pk_bf16_f32 v15, v20, v33
	v_fmac_f32_e32 v169, v165, v22
	v_fma_f32 v14, v171, v14, v175
	ds_write_b16 v155, v15 offset:35360
	v_cvt_pk_bf16_f32 v15, v169, v33
	v_fma_f32 v22, v170, v28, v174
	ds_write_b16 v155, v15 offset:35632
	v_cvt_pk_bf16_f32 v15, v22, v33
	ds_write_b16 v155, v15 offset:35904
	v_cvt_pk_bf16_f32 v14, v14, v33
	v_fma_f32 v28, v172, v30, v176
	ds_write_b16 v155, v14 offset:36176
	v_cvt_pk_bf16_f32 v14, v28, v33
	ds_write_b16 v155, v14 offset:36448
	v_cvt_pk_bf16_f32 v14, v177, v33
	global_load_dwordx4 v[160:163], v157, s[48:49] offset:1664
	global_load_dwordx4 v[164:167], v157, s[50:51] offset:1664
	global_load_dwordx4 v[168:171], v157, s[48:49] offset:1680
	global_load_dwordx4 v[172:175], v157, s[50:51] offset:1680
	v_lshlrev_b32_e32 v15, 16, v8
	v_and_b32_e32 v8, 0xffff0000, v8
	v_lshlrev_b32_e32 v20, 16, v11
	v_and_b32_e32 v11, 0xffff0000, v11
	v_sub_f32_e32 v8, v8, v12
	v_lshlrev_b32_e32 v16, 16, v9
	v_sub_f32_e32 v15, v15, v12
	v_sub_f32_e32 v11, v11, v12
	v_mul_f32_e32 v8, v13, v8
	v_and_b32_e32 v9, 0xffff0000, v9
	v_sub_f32_e32 v16, v16, v12
	v_mul_f32_e32 v15, v13, v15
	v_mul_f32_e32 v11, v13, v11
	v_lshlrev_b32_e32 v18, 16, v10
	v_sub_f32_e32 v9, v9, v12
	v_mul_f32_e32 v16, v13, v16
	ds_write_b16 v155, v14 offset:36720
	v_and_b32_e32 v10, 0xffff0000, v10
	v_sub_f32_e32 v18, v18, v12
	v_mul_f32_e32 v9, v13, v9
	v_sub_f32_e32 v10, v10, v12
	v_mul_f32_e32 v18, v13, v18
	v_sub_f32_e32 v20, v20, v12
	v_mul_f32_e32 v10, v13, v10
	v_mul_f32_e32 v20, v13, v20
	v_lshlrev_b32_e32 v22, 16, v7
	v_and_b32_e32 v7, 0xffff0000, v7
	v_sub_f32_e32 v7, v7, v12
	v_mul_f32_e32 v7, v13, v7
	v_sub_f32_e32 v22, v22, v12
	v_mul_f32_e32 v22, v13, v22
	v_mov_b32_e32 v30, v64
	v_lshlrev_b32_e32 v28, 16, v0
	s_waitcnt vmcnt(2)
	v_fma_f32 v8, v8, v161, v165
	v_fma_f32 v14, v15, v160, v164
	s_waitcnt vmcnt(0)
	v_fmac_f32_e32 v175, v11, v171
	v_cvt_pk_bf16_f32 v11, v14, v33
	ds_write_b16 v155, v11 offset:43520
	v_cvt_pk_bf16_f32 v8, v8, v33
	v_fma_f32 v15, v16, v162, v166
	ds_write_b16 v155, v8 offset:43792
	v_cvt_pk_bf16_f32 v8, v15, v33
	v_fmac_f32_e32 v167, v9, v163
	ds_write_b16 v155, v8 offset:44064
	v_cvt_pk_bf16_f32 v8, v167, v33
	v_fma_f32 v9, v18, v168, v172
	ds_write_b16 v155, v8 offset:44336
	v_cvt_pk_bf16_f32 v8, v9, v33
	v_fma_f32 v10, v10, v169, v173
	ds_write_b16 v155, v8 offset:44608
	v_cvt_pk_bf16_f32 v8, v10, v33
	v_fma_f32 v16, v20, v170, v174
	ds_write_b16 v155, v8 offset:44880
	v_cvt_pk_bf16_f32 v8, v16, v33
	ds_write_b16 v155, v8 offset:45152
	v_cvt_pk_bf16_f32 v18, v175, v33
	global_load_dwordx4 v[8:11], v157, s[48:49] offset:1792
	global_load_dwordx4 v[160:163], v157, s[50:51] offset:1792
	global_load_dwordx4 v[164:167], v157, s[48:49] offset:1808
	global_load_dwordx4 v[168:171], v157, s[50:51] offset:1808
	v_pk_add_f32 v[14:15], v[66:67], v[66:67] op_sel:[0,1] op_sel_hi:[1,0]
	v_mul_f32_e32 v16, v53, v53
	v_mov_b32_e32 v50, v14
	v_pk_add_f32 v[14:15], v[14:15], v[64:65]
	v_pk_fma_f32 v[52:53], v[52:53], v[52:53], v[16:17] op_sel_hi:[1,1,0]
	v_lshlrev_b32_e32 v15, 16, v4
	v_and_b32_e32 v4, 0xffff0000, v4
	v_sub_f32_e32 v4, v4, v12
	v_lshlrev_b32_e32 v16, 16, v5
	v_sub_f32_e32 v15, v15, v12
	v_mul_f32_e32 v4, v13, v4
	v_and_b32_e32 v5, 0xffff0000, v5
	v_sub_f32_e32 v16, v16, v12
	v_mul_f32_e32 v15, v13, v15
	v_lshlrev_b32_e32 v20, 16, v6
	v_sub_f32_e32 v5, v5, v12
	v_mul_f32_e32 v16, v13, v16
	ds_write_b16 v155, v18 offset:45424
	v_and_b32_e32 v6, 0xffff0000, v6
	v_sub_f32_e32 v20, v20, v12
	v_mul_f32_e32 v5, v13, v5
	v_sub_f32_e32 v6, v6, v12
	v_mul_f32_e32 v20, v13, v20
	v_mul_f32_e32 v6, v13, v6
	v_mov_b32_e32 v172, v58
	v_mov_b32_e32 v173, v49
	v_pk_mul_f32 v[30:31], v[50:51], v[30:31]
	v_mov_b32_e32 v48, v52
	v_pk_add_f32 v[50:51], v[52:53], v[58:59]
	v_pk_add_f32 v[52:53], v[68:69], v[70:71]
	v_and_b32_e32 v68, 0xffff0000, v0
	v_lshlrev_b32_e32 v69, 16, v1
	v_and_b32_e32 v70, 0xffff0000, v1
	v_pk_mul_f32 v[0:1], v[78:79], v[78:79]
	v_lshlrev_b32_e32 v71, 16, v2
	v_pk_fma_f32 v[0:1], v[76:77], v[76:77], v[0:1]
	v_pk_mul_f32 v[58:59], v[98:99], v[98:99]
	v_pk_add_f32 v[0:1], v[0:1], v[0:1] op_sel:[0,1] op_sel_hi:[1,0]
	s_waitcnt vmcnt(2)
	v_fma_f32 v4, v4, v9, v161
	v_fma_f32 v8, v15, v8, v160
	s_waitcnt vmcnt(0)
	v_fmac_f32_e32 v171, v7, v167
	v_cvt_pk_bf16_f32 v7, v8, v33
	ds_write_b16 v155, v7 offset:52224
	v_cvt_pk_bf16_f32 v4, v4, v33
	v_fma_f32 v9, v16, v10, v162
	ds_write_b16 v155, v4 offset:52496
	v_cvt_pk_bf16_f32 v4, v9, v33
	v_fmac_f32_e32 v163, v5, v11
	ds_write_b16 v155, v4 offset:52768
	v_cvt_pk_bf16_f32 v4, v163, v33
	v_fma_f32 v5, v20, v164, v168
	ds_write_b16 v155, v4 offset:53040
	v_cvt_pk_bf16_f32 v4, v5, v33
	v_fma_f32 v6, v6, v165, v169
	ds_write_b16 v155, v4 offset:53312
	v_cvt_pk_bf16_f32 v4, v6, v33
	v_fma_f32 v10, v22, v166, v170
	ds_write_b16 v155, v4 offset:53584
	v_cvt_pk_bf16_f32 v4, v10, v33
	ds_write_b16 v155, v4 offset:53856
	v_cvt_pk_bf16_f32 v18, v171, v33
	global_load_dwordx4 v[4:7], v157, s[48:49] offset:1920
	global_load_dwordx4 v[8:11], v157, s[50:51] offset:1920
	global_load_dwordx4 v[60:63], v157, s[48:49] offset:1936
	global_load_dwordx4 v[64:67], v157, s[50:51] offset:1936
	v_mov_b32_e32 v15, v31
	v_pk_mul_f32 v[30:31], v[48:49], v[172:173]
	v_mov_b32_e32 v2, v0
	v_mov_b32_e32 v51, v31
	v_pk_add_f32 v[14:15], v[14:15], v[50:51]
	v_mul_f32_e32 v16, v81, v81
	v_pk_add_f32 v[14:15], v[14:15], v[52:53]
	v_pk_fma_f32 v[30:31], v[80:81], v[80:81], v[16:17] op_sel_hi:[1,1,0]
	v_pk_add_f32 v[14:15], v[14:15], v[14:15] op_sel:[0,1] op_sel_hi:[1,0]
	v_mov_b32_e32 v92, v30
	v_mov_b32_e32 v94, v14
	v_pk_add_f32 v[0:1], v[14:15], v[0:1]
	v_mul_f32_e32 v14, v83, v83
	v_pk_fma_f32 v[14:15], v[82:83], v[82:83], v[14:15] op_sel_hi:[1,1,0]
	v_mov_b32_e32 v49, v93
	v_mov_b32_e32 v48, v14
	v_pk_add_f32 v[14:15], v[30:31], v[14:15]
	v_pk_fma_f32 v[30:31], v[86:87], v[88:89], v[96:97]
	v_pk_mul_f32 v[50:51], v[96:97], v[96:97]
	v_pk_fma_f32 v[52:53], v[84:85], v[90:91], v[98:99]
	v_pk_mul_f32 v[2:3], v[94:95], v[2:3]
	v_pk_mul_f32 v[48:49], v[92:93], v[48:49]
	v_mov_b32_e32 v31, v51
	v_mov_b32_e32 v53, v59
	v_mov_b32_e32 v1, v3
	v_mov_b32_e32 v15, v49
	v_pk_add_f32 v[2:3], v[30:31], v[52:53]
	v_pk_add_f32 v[0:1], v[0:1], v[14:15]
	ds_write_b16 v155, v18 offset:54128
	v_pk_add_f32 v[50:51], v[0:1], v[2:3]
	v_pk_mul_f32 v[0:1], v[102:103], v[102:103]
	v_sub_f32_e32 v2, v69, v12
	v_pk_fma_f32 v[0:1], v[100:101], v[100:101], v[0:1]
	v_sub_f32_e32 v3, v70, v12
	v_pk_add_f32 v[48:49], v[0:1], v[0:1] op_sel:[0,1] op_sel_hi:[1,0]
	v_mul_f32_e32 v0, v105, v105
	v_pk_fma_f32 v[30:31], v[104:105], v[104:105], v[0:1] op_sel_hi:[1,1,0]
	v_sub_f32_e32 v0, v28, v12
	v_mul_f32_e32 v0, v13, v0
	v_sub_f32_e32 v1, v68, v12
	v_mul_f32_e32 v1, v13, v1
	v_mul_f32_e32 v2, v13, v2
	v_sub_f32_e32 v14, v71, v12
	v_mul_f32_e32 v3, v13, v3
	v_sub_f32_e32 v15, v72, v12
	v_mul_f32_e32 v14, v13, v14
	v_sub_f32_e32 v16, v73, v12
	v_mul_f32_e32 v15, v13, v15
	v_sub_f32_e32 v12, v74, v12
	v_mul_f32_e32 v16, v13, v16
	v_mul_f32_e32 v12, v13, v12
	v_mov_b32_e32 v20, v56
	v_mov_b32_e32 v22, v54
	s_waitcnt vmcnt(2)
	v_fma_f32 v0, v0, v4, v8
	v_cvt_pk_bf16_f32 v0, v0, v33
	v_fma_f32 v1, v1, v5, v9
	ds_write_b16 v155, v0 offset:60928
	v_cvt_pk_bf16_f32 v0, v1, v33
	v_fma_f32 v2, v2, v6, v10
	ds_write_b16 v155, v0 offset:61200
	v_cvt_pk_bf16_f32 v0, v2, v33
	v_fmac_f32_e32 v11, v3, v7
	ds_write_b16 v155, v0 offset:61472
	v_cvt_pk_bf16_f32 v0, v11, v33
	s_waitcnt vmcnt(0)
	v_fma_f32 v3, v14, v60, v64
	ds_write_b16 v155, v0 offset:61744
	v_cvt_pk_bf16_f32 v0, v3, v33
	v_fma_f32 v4, v15, v61, v65
	ds_write_b16 v155, v0 offset:62016
	v_cvt_pk_bf16_f32 v0, v4, v33
	v_fma_f32 v5, v16, v62, v66
	ds_write_b16 v155, v0 offset:62288
	v_cvt_pk_bf16_f32 v0, v5, v33
	v_fmac_f32_e32 v67, v12, v63
	ds_write_b16 v155, v0 offset:62560
	v_cvt_pk_bf16_f32 v0, v67, v33
	ds_write_b16 v155, v0 offset:62832
	s_waitcnt lgkmcnt(0)
	s_barrier
	v_add_co_u32_e32 v4, vcc, s28, v42
	v_pk_fma_f32 v[56:57], v[56:57], v[20:21], v[26:27]
	s_nop 0
	v_addc_co_u32_e32 v5, vcc, 0, v43, vcc
	global_load_dwordx4 v[8:11], v[4:5], off
	global_load_dwordx4 v[0:3], v[4:5], off offset:64
	global_load_dwordx2 v[52:53], v[40:41], off offset:1792
	global_load_dwordx4 v[12:15], v[4:5], off offset:128
	s_nop 0
	global_load_dwordx4 v[4:7], v[4:5], off offset:192
	s_nop 0
	global_load_dword v28, v[44:45], off offset:1536
	ds_read_b128 v[42:45], v152 offset:34816
	ds_read_b128 v[58:61], v152 offset:34880
	ds_read_b128 v[62:65], v152 offset:34944
	v_pk_fma_f32 v[54:55], v[54:55], v[22:23], v[24:25]
	v_pk_mul_f32 v[24:25], v[24:25], v[24:25]
	v_pk_mul_f32 v[26:27], v[26:27], v[26:27]
	v_pk_add_f32 v[50:51], v[50:51], v[50:51] op_sel:[0,1] op_sel_hi:[1,0]
	v_mov_b32_e32 v168, v48
	v_mov_b32_e32 v169, v19
	v_mov_b32_e32 v170, v30
	v_mov_b32_e32 v171, v17
	s_waitcnt vmcnt(5) lgkmcnt(2)
	v_mfma_f32_16x16x32_bf16 v[42:45], v[42:45], v[8:11], 0
	s_waitcnt vmcnt(3)
	v_lshlrev_b32_e32 v67, 16, v53
	v_lshlrev_b32_e32 v66, 16, v52
	s_waitcnt lgkmcnt(1)
	v_mfma_f32_16x16x32_bf16 v[42:45], v[58:61], v[0:3], v[42:45]
	ds_read_b128 v[58:61], v152 offset:35008
	v_and_b32_e32 v53, 0xffff0000, v53
	v_and_b32_e32 v52, 0xffff0000, v52
	s_waitcnt vmcnt(2) lgkmcnt(1)
	v_mfma_f32_16x16x32_bf16 v[42:45], v[62:65], v[12:15], v[42:45]
	s_waitcnt vmcnt(1) lgkmcnt(0)
	v_mfma_f32_16x16x32_bf16 v[42:45], v[58:61], v[4:7], v[42:45]
	s_nop 7
	v_mov_b32_e32 v58, v42
	v_mov_b32_e32 v59, v44
	v_mov_b32_e32 v44, v43
	s_waitcnt vmcnt(0)
	v_pk_add_f32 v[42:43], v[28:29], v[58:59] op_sel_hi:[0,1]
	v_pk_add_f32 v[44:45], v[28:29], v[44:45] op_sel_hi:[0,1]
	v_pk_mul_f32 v[42:43], v[42:43], v[66:67]
	v_pk_mul_f32 v[44:45], v[44:45], v[52:53]
	s_nop 0
	v_cvt_pk_bf16_f32 v77, v42, v44
	v_cvt_pk_bf16_f32 v76, v43, v45
	ds_read_b128 v[58:61], v152 offset:39168
	ds_read_b128 v[62:65], v152 offset:39232
	s_waitcnt lgkmcnt(1)
	v_mfma_f32_16x16x32_bf16 v[58:61], v[58:61], v[8:11], 0
	s_waitcnt lgkmcnt(0)
	v_mfma_f32_16x16x32_bf16 v[58:61], v[62:65], v[0:3], v[58:61]
	ds_read_b128 v[62:65], v152 offset:39296
	ds_read_b128 v[66:69], v152 offset:39360
	global_load_dwordx2 v[52:53], v[40:41], off offset:1824
	s_waitcnt lgkmcnt(1)
	v_mfma_f32_16x16x32_bf16 v[58:61], v[62:65], v[12:15], v[58:61]
	s_waitcnt vmcnt(0)
	v_lshlrev_b32_e32 v62, 16, v52
	s_waitcnt lgkmcnt(0)
	v_mfma_f32_16x16x32_bf16 v[58:61], v[66:69], v[4:7], v[58:61]
	v_and_b32_e32 v63, 0xffff0000, v52
	v_lshlrev_b32_e32 v64, 16, v53
	v_and_b32_e32 v65, 0xffff0000, v53
	s_nop 4
	v_pk_add_f32 v[58:59], v[28:29], v[58:59] op_sel_hi:[0,1]
	v_pk_add_f32 v[60:61], v[28:29], v[60:61] op_sel_hi:[0,1]
	v_pk_mul_f32 v[52:53], v[58:59], v[62:63]
	v_pk_mul_f32 v[58:59], v[60:61], v[64:65]
	v_cvt_pk_bf16_f32 v75, v52, v53
	s_nop 0
	v_cvt_pk_bf16_f32 v74, v58, v59
	ds_read_b128 v[60:63], v152 offset:43520
	ds_read_b128 v[64:67], v152 offset:43584
	s_waitcnt lgkmcnt(1)
	v_mfma_f32_16x16x32_bf16 v[60:63], v[60:63], v[8:11], 0
	s_waitcnt lgkmcnt(0)
	v_mfma_f32_16x16x32_bf16 v[60:63], v[64:67], v[0:3], v[60:63]
	ds_read_b128 v[64:67], v152 offset:43648
	ds_read_b128 v[68:71], v152 offset:43712
	s_waitcnt lgkmcnt(1)
	v_mfma_f32_16x16x32_bf16 v[60:63], v[64:67], v[12:15], v[60:63]
	global_load_dwordx2 v[64:65], v[40:41], off offset:1856
	s_waitcnt vmcnt(0)
	v_lshlrev_b32_e32 v66, 16, v65
	s_waitcnt lgkmcnt(0)
	v_mfma_f32_16x16x32_bf16 v[60:63], v[68:71], v[4:7], v[60:63]
	v_and_b32_e32 v65, 0xffff0000, v65
	s_nop 6
	v_add_f32_e32 v16, v28, v60
	v_add_f32_e32 v18, v28, v61
	v_add_f32_e32 v60, v28, v62
	v_add_f32_e32 v61, v28, v63
	v_lshlrev_b32_e32 v62, 16, v64
	v_and_b32_e32 v63, 0xffff0000, v64
	v_mul_f32_e32 v64, v16, v62
	v_mul_f32_e32 v62, v18, v63
	v_mul_f32_e32 v66, v60, v66
	v_mul_f32_e32 v60, v61, v65
	v_cvt_pk_bf16_f32 v73, v64, v62
	v_cvt_pk_bf16_f32 v72, v66, v60
	ds_read_b128 v[68:71], v152 offset:47872
	ds_read_b128 v[78:81], v152 offset:47936
	s_waitcnt lgkmcnt(1)
	v_mfma_f32_16x16x32_bf16 v[68:71], v[68:71], v[8:11], 0
	v_mov_b32_e32 v94, v64
	v_mov_b32_e32 v96, v66
	s_waitcnt lgkmcnt(0)
	v_mfma_f32_16x16x32_bf16 v[68:71], v[78:81], v[0:3], v[68:71]
	ds_read_b128 v[78:81], v152 offset:48000
	ds_read_b128 v[82:85], v152 offset:48064
	s_waitcnt lgkmcnt(1)
	v_mfma_f32_16x16x32_bf16 v[68:71], v[78:81], v[12:15], v[68:71]
	global_load_dwordx2 v[78:79], v[40:41], off offset:1888
	s_waitcnt vmcnt(0)
	v_lshlrev_b32_e32 v61, 16, v78
	s_waitcnt lgkmcnt(0)
	v_mfma_f32_16x16x32_bf16 v[68:71], v[82:85], v[4:7], v[68:71]
	v_and_b32_e32 v63, 0xffff0000, v78
	v_lshlrev_b32_e32 v95, 16, v79
	v_and_b32_e32 v97, 0xffff0000, v79
	s_nop 4
	v_add_f32_e32 v16, v28, v68
	v_add_f32_e32 v18, v28, v69
	v_add_f32_e32 v65, v28, v70
	v_add_f32_e32 v67, v28, v71
	v_mul_f32_e32 v99, v16, v61
	v_mul_f32_e32 v101, v18, v63
	v_pk_mul_f32 v[102:103], v[64:65], v[94:95]
	v_pk_mul_f32 v[104:105], v[66:67], v[96:97]
	v_cvt_pk_bf16_f32 v71, v99, v101
	v_mul_f32_e32 v16, v47, v47
	v_cvt_pk_bf16_f32 v69, v103, v105
	ds_read_b128 v[78:81], v152 offset:52224
	ds_read_b128 v[82:85], v152 offset:52288
	s_waitcnt lgkmcnt(1)
	v_mfma_f32_16x16x32_bf16 v[78:81], v[78:81], v[8:11], 0
	v_mov_b32_e32 v18, v50
	v_pk_mul_f32 v[18:19], v[18:19], v[168:169]
	v_mov_b32_e32 v63, v65
	s_waitcnt lgkmcnt(0)
	v_mfma_f32_16x16x32_bf16 v[78:81], v[82:85], v[0:3], v[78:81]
	ds_read_b128 v[82:85], v152 offset:52352
	ds_read_b128 v[86:89], v152 offset:52416
	v_mov_b32_e32 v94, v62
	v_mov_b32_e32 v96, v60
	s_waitcnt lgkmcnt(1)
	v_mfma_f32_16x16x32_bf16 v[78:81], v[82:85], v[12:15], v[78:81]
	global_load_dwordx2 v[82:83], v[40:41], off offset:1920
	s_waitcnt lgkmcnt(0)
	v_mfma_f32_16x16x32_bf16 v[78:81], v[86:89], v[4:7], v[78:81]
	s_nop 7
	v_mov_b32_e32 v84, v78
	v_mov_b32_e32 v85, v80
	v_mov_b32_e32 v80, v79
	v_pk_add_f32 v[78:79], v[28:29], v[84:85] op_sel_hi:[0,1]
	v_pk_add_f32 v[80:81], v[28:29], v[80:81] op_sel_hi:[0,1]
	s_waitcnt vmcnt(0)
	v_lshlrev_b32_e32 v85, 16, v83
	v_lshlrev_b32_e32 v84, 16, v82
	v_and_b32_e32 v83, 0xffff0000, v83
	v_and_b32_e32 v82, 0xffff0000, v82
	v_pk_mul_f32 v[108:109], v[78:79], v[84:85]
	v_pk_mul_f32 v[160:161], v[80:81], v[82:83]
	s_nop 0
	v_cvt_pk_bf16_f32 v70, v108, v160
	v_cvt_pk_bf16_f32 v68, v109, v161
	ds_read_b128 v[78:81], v152 offset:56576
	ds_read_b128 v[82:85], v152 offset:56640
	s_waitcnt lgkmcnt(1)
	v_mfma_f32_16x16x32_bf16 v[78:81], v[78:81], v[8:11], 0
	s_waitcnt lgkmcnt(0)
	v_mfma_f32_16x16x32_bf16 v[78:81], v[82:85], v[0:3], v[78:81]
	ds_read_b128 v[82:85], v152 offset:56704
	ds_read_b128 v[86:89], v152 offset:56768
	s_waitcnt lgkmcnt(1)
	v_mfma_f32_16x16x32_bf16 v[78:81], v[82:85], v[12:15], v[78:81]
	global_load_dwordx2 v[82:83], v[40:41], off offset:1952
	s_waitcnt vmcnt(0)
	v_lshlrev_b32_e32 v84, 16, v82
	s_waitcnt lgkmcnt(0)
	v_mfma_f32_16x16x32_bf16 v[78:81], v[86:89], v[4:7], v[78:81]
	v_and_b32_e32 v85, 0xffff0000, v82
	v_lshlrev_b32_e32 v82, 16, v83
	v_and_b32_e32 v83, 0xffff0000, v83
	s_nop 4
	v_pk_add_f32 v[78:79], v[28:29], v[78:79] op_sel_hi:[0,1]
	v_pk_add_f32 v[80:81], v[28:29], v[80:81] op_sel_hi:[0,1]
	v_pk_mul_f32 v[162:163], v[78:79], v[84:85]
	v_pk_mul_f32 v[164:165], v[80:81], v[82:83]
	v_cvt_pk_bf16_f32 v66, v162, v163
	s_nop 0
	v_cvt_pk_bf16_f32 v64, v164, v165
	global_load_dwordx2 v[166:167], v[40:41], off offset:1984
	ds_read_b128 v[78:81], v152 offset:60928
	ds_read_b128 v[82:85], v152 offset:60992
	ds_read_b128 v[86:89], v152 offset:61056
	ds_read_b128 v[90:93], v152 offset:61120
	s_waitcnt lgkmcnt(3)
	v_mfma_f32_16x16x32_bf16 v[78:81], v[78:81], v[8:11], 0
	s_waitcnt vmcnt(0)
	v_lshlrev_b32_e32 v24, 16, v166
	s_waitcnt lgkmcnt(2)
	v_mfma_f32_16x16x32_bf16 v[78:81], v[82:85], v[0:3], v[78:81]
	v_and_b32_e32 v55, 0xffff0000, v166
	v_lshlrev_b32_e32 v57, 16, v167
	v_and_b32_e32 v61, 0xffff0000, v167
	s_waitcnt lgkmcnt(1)
	v_mfma_f32_16x16x32_bf16 v[78:81], v[86:89], v[12:15], v[78:81]
	s_waitcnt lgkmcnt(0)
	v_mfma_f32_16x16x32_bf16 v[20:23], v[90:93], v[4:7], v[78:81]
	s_nop 7
	v_add_f32_e32 v20, v28, v20
	v_add_f32_e32 v21, v28, v21
	v_add_f32_e32 v22, v28, v22
	v_add_f32_e32 v23, v28, v23
	v_mul_f32_e32 v26, v20, v24
	v_mul_f32_e32 v78, v21, v55
	v_mul_f32_e32 v80, v22, v57
	v_mul_f32_e32 v82, v23, v61
	v_cvt_pk_bf16_f32 v21, v26, v78
	v_cvt_pk_bf16_f32 v20, v80, v82
	global_load_dwordx2 v[84:85], v[40:41], off offset:2016
	v_pk_fma_f32 v[40:41], v[46:47], v[46:47], v[16:17] op_sel_hi:[1,1,0]
	v_pk_add_f32 v[22:23], v[50:51], v[48:49]
	v_mov_b32_e32 v16, v40
	v_mov_b32_e32 v55, v25
	v_pk_add_f32 v[24:25], v[40:41], v[30:31]
	v_pk_mul_f32 v[16:17], v[16:17], v[170:171]
	v_mov_b32_e32 v57, v27
	v_mov_b32_e32 v23, v19
	v_mov_b32_e32 v25, v17
	v_pk_add_f32 v[30:31], v[56:57], v[54:55]
	v_pk_add_f32 v[16:17], v[22:23], v[24:25]
	v_pk_mul_f32 v[18:19], v[44:45], v[44:45]
	v_pk_add_f32 v[16:17], v[16:17], v[30:31]
	v_pk_fma_f32 v[18:19], v[42:43], v[42:43], v[18:19]
	v_pk_add_f32 v[16:17], v[16:17], v[16:17] op_sel:[0,1] op_sel_hi:[1,0]
	v_pk_add_f32 v[18:19], v[18:19], v[18:19] op_sel:[0,1] op_sel_hi:[1,0]
	v_mov_b32_e32 v98, v16
	v_mov_b32_e32 v22, v18
	v_pk_add_f32 v[16:17], v[16:17], v[18:19]
	v_mul_f32_e32 v18, v59, v59
	v_mul_f32_e32 v24, v53, v53
	v_pk_fma_f32 v[18:19], v[58:59], v[58:59], v[18:19] op_sel_hi:[1,1,0]
	v_pk_fma_f32 v[24:25], v[52:53], v[52:53], v[24:25] op_sel_hi:[1,1,0]
	v_mov_b32_e32 v30, v18
	v_mov_b32_e32 v100, v24
	v_mov_b32_e32 v61, v67
	v_mov_b32_e32 v23, v99
	v_mov_b32_e32 v31, v101
	v_pk_add_f32 v[18:19], v[24:25], v[18:19]
	v_pk_fma_f32 v[24:25], v[62:63], v[94:95], v[102:103]
	v_pk_mul_f32 v[40:41], v[102:103], v[102:103]
	v_pk_fma_f32 v[42:43], v[60:61], v[96:97], v[104:105]
	v_pk_mul_f32 v[44:45], v[104:105], v[104:105]
	v_pk_mul_f32 v[22:23], v[98:99], v[22:23]
	v_pk_mul_f32 v[30:31], v[100:101], v[30:31]
	v_mov_b32_e32 v25, v41
	v_mov_b32_e32 v43, v45
	v_mov_b32_e32 v17, v23
	v_mov_b32_e32 v19, v31
	v_pk_add_f32 v[22:23], v[24:25], v[42:43]
	v_pk_add_f32 v[16:17], v[16:17], v[18:19]
	v_mul_f32_e32 v48, v165, v165
	v_pk_add_f32 v[16:17], v[16:17], v[22:23]
	v_pk_mul_f32 v[22:23], v[160:161], v[160:161]
	v_pk_add_f32 v[30:31], v[16:17], v[16:17] op_sel:[0,1] op_sel_hi:[1,0]
	ds_read_b128 v[16:19], v152 offset:65280
	v_pk_fma_f32 v[22:23], v[108:109], v[108:109], v[22:23]
	v_mov_b32_e32 v44, v30
	v_pk_add_f32 v[40:41], v[22:23], v[22:23] op_sel:[0,1] op_sel_hi:[1,0]
	ds_read_b128 v[22:25], v152 offset:65344
	v_mov_b32_e32 v46, v40
	v_pk_add_f32 v[30:31], v[30:31], v[40:41]
	ds_read_b128 v[40:43], v152 offset:65408
	s_waitcnt lgkmcnt(2)
	v_mfma_f32_16x16x32_bf16 v[8:11], v[16:19], v[8:11], 0
	ds_read_b128 v[16:19], v152 offset:65472
	v_mul_f32_e32 v50, v163, v163
	v_pk_fma_f32 v[48:49], v[164:165], v[164:165], v[48:49] op_sel_hi:[1,1,0]
	s_waitcnt lgkmcnt(2)
	v_mfma_f32_16x16x32_bf16 v[0:3], v[22:25], v[0:3], v[8:11]
	v_mov_b32_e32 v22, v48
	s_waitcnt lgkmcnt(1)
	v_mfma_f32_16x16x32_bf16 v[0:3], v[40:43], v[12:15], v[0:3]
	v_fma_f32 v8, v162, v162, v50
	v_fma_f32 v9, v163, v163, v50
	v_mov_b32_e32 v12, v26
	v_mov_b32_e32 v14, v80
	s_waitcnt lgkmcnt(0)
	v_mfma_f32_16x16x32_bf16 v[0:3], v[16:19], v[4:7], v[0:3]
	v_mov_b32_e32 v10, v8
	v_pk_add_f32 v[8:9], v[8:9], v[48:49]
	s_waitcnt vmcnt(0)
	v_lshlrev_b32_e32 v13, 16, v85
	s_nop 3
	v_add_f32_e32 v0, v28, v0
	v_add_f32_e32 v1, v28, v1
	v_add_f32_e32 v27, v28, v2
	v_add_f32_e32 v81, v28, v3
	v_lshlrev_b32_e32 v2, 16, v84
	v_and_b32_e32 v3, 0xffff0000, v84
	v_and_b32_e32 v15, 0xffff0000, v85
	v_mul_f32_e32 v45, v0, v2
	v_mul_f32_e32 v11, v1, v3
	v_mov_b32_e32 v79, v27
	v_mov_b32_e32 v83, v81
	v_pk_mul_f32 v[0:1], v[26:27], v[12:13]
	v_mov_b32_e32 v12, v78
	v_pk_mul_f32 v[2:3], v[80:81], v[14:15]
	v_mov_b32_e32 v14, v82
	v_mov_b32_e32 v47, v45
	v_mov_b32_e32 v23, v11
	v_cvt_pk_bf16_f32 v7, v45, v11
	v_cvt_pk_bf16_f32 v6, v1, v3
	v_pk_fma_f32 v[4:5], v[78:79], v[12:13], v[0:1]
	v_pk_mul_f32 v[0:1], v[0:1], v[0:1]
	v_pk_fma_f32 v[12:13], v[82:83], v[14:15], v[2:3]
	v_pk_mul_f32 v[2:3], v[2:3], v[2:3]
	v_pk_mul_f32 v[14:15], v[44:45], v[46:47]
	v_pk_mul_f32 v[10:11], v[10:11], v[22:23]
	v_mov_b32_e32 v5, v1
	v_mov_b32_e32 v13, v3
	v_mov_b32_e32 v31, v15
	v_mov_b32_e32 v9, v11
	v_pk_add_f32 v[0:1], v[4:5], v[12:13]
	v_pk_add_f32 v[2:3], v[30:31], v[8:9]
	s_nop 0
	v_pk_add_f32 v[0:1], v[2:3], v[0:1]
	s_barrier
	v_add_f32_e32 v8, v0, v1
	v_lshl_add_u64 v[4:5], v[38:39], 0, s[10:11]
	v_lshl_add_u64 v[0:1], v[4:5], 0, v[32:33]
	global_load_dwordx2 v[0:1], v[0:1], off
	v_or_b32_e32 v160, 0x20, v32
	v_mov_b32_e32 v161, v33
	v_lshl_add_u64 v[160:161], v[4:5], 0, v[160:161]
	global_load_dwordx2 v[160:161], v[160:161], off
	v_or_b32_e32 v162, 0x40, v32
	v_mov_b32_e32 v163, v33
	v_lshl_add_u64 v[162:163], v[4:5], 0, v[162:163]
	global_load_dwordx2 v[162:163], v[162:163], off
	v_or_b32_e32 v164, 0x60, v32
	v_mov_b32_e32 v165, v33
	v_lshl_add_u64 v[164:165], v[4:5], 0, v[164:165]
	global_load_dwordx2 v[164:165], v[164:165], off
	v_or_b32_e32 v166, 0x80, v32
	v_mov_b32_e32 v167, v33
	v_lshl_add_u64 v[166:167], v[4:5], 0, v[166:167]
	global_load_dwordx2 v[166:167], v[166:167], off
	v_or_b32_e32 v168, 0xa0, v32
	v_mov_b32_e32 v169, v33
	v_lshl_add_u64 v[168:169], v[4:5], 0, v[168:169]
	global_load_dwordx2 v[168:169], v[168:169], off
	v_or_b32_e32 v170, 0xc0, v32
	v_mov_b32_e32 v171, v33
	v_lshl_add_u64 v[170:171], v[4:5], 0, v[170:171]
	global_load_dwordx2 v[170:171], v[170:171], off
	v_or_b32_e32 v172, 0xe0, v32
	v_mov_b32_e32 v173, v33
	v_lshl_add_u64 v[172:173], v[4:5], 0, v[172:173]
	global_load_dwordx2 v[172:173], v[172:173], off
	v_or_b32_e32 v174, 0x100, v32
	v_mov_b32_e32 v175, v33
	v_lshl_add_u64 v[174:175], v[4:5], 0, v[174:175]
	global_load_dwordx2 v[174:175], v[174:175], off
	v_or_b32_e32 v176, 0x120, v32
	v_mov_b32_e32 v177, v33
	v_lshl_add_u64 v[176:177], v[4:5], 0, v[176:177]
	global_load_dwordx2 v[176:177], v[176:177], off
	v_or_b32_e32 v178, 0x140, v32
	v_mov_b32_e32 v179, v33
	v_lshl_add_u64 v[178:179], v[4:5], 0, v[178:179]
	global_load_dwordx2 v[178:179], v[178:179], off
	v_or_b32_e32 v180, 0x160, v32
	v_mov_b32_e32 v181, v33
	v_lshl_add_u64 v[180:181], v[4:5], 0, v[180:181]
	global_load_dwordx2 v[180:181], v[180:181], off
	v_or_b32_e32 v182, 0x180, v32
	v_mov_b32_e32 v183, v33
	v_lshl_add_u64 v[182:183], v[4:5], 0, v[182:183]
	global_load_dwordx2 v[182:183], v[182:183], off
	v_or_b32_e32 v184, 0x1a0, v32
	v_mov_b32_e32 v185, v33
	v_lshl_add_u64 v[184:185], v[4:5], 0, v[184:185]
	global_load_dwordx2 v[184:185], v[184:185], off
	v_or_b32_e32 v186, 0x1c0, v32
	v_mov_b32_e32 v187, v33
	v_lshl_add_u64 v[186:187], v[4:5], 0, v[186:187]
	global_load_dwordx2 v[186:187], v[186:187], off
	v_or_b32_e32 v188, 0x1e0, v32
	v_mov_b32_e32 v189, v33
	v_lshl_add_u64 v[188:189], v[4:5], 0, v[188:189]
	global_load_dwordx2 v[188:189], v[188:189], off
	v_or_b32_e32 v190, 0x200, v32
	v_mov_b32_e32 v191, v33
	v_lshl_add_u64 v[190:191], v[4:5], 0, v[190:191]
	global_load_dwordx2 v[190:191], v[190:191], off
	v_or_b32_e32 v192, 0x220, v32
	v_mov_b32_e32 v193, v33
	v_lshl_add_u64 v[192:193], v[4:5], 0, v[192:193]
	global_load_dwordx2 v[192:193], v[192:193], off
	v_or_b32_e32 v194, 0x240, v32
	v_mov_b32_e32 v195, v33
	v_lshl_add_u64 v[194:195], v[4:5], 0, v[194:195]
	global_load_dwordx2 v[194:195], v[194:195], off
	v_or_b32_e32 v196, 0x260, v32
	v_mov_b32_e32 v197, v33
	v_lshl_add_u64 v[196:197], v[4:5], 0, v[196:197]
	global_load_dwordx2 v[196:197], v[196:197], off
	v_or_b32_e32 v198, 0x280, v32
	v_mov_b32_e32 v199, v33
	v_lshl_add_u64 v[198:199], v[4:5], 0, v[198:199]
	global_load_dwordx2 v[198:199], v[198:199], off
	v_or_b32_e32 v200, 0x2a0, v32
	v_mov_b32_e32 v201, v33
	v_lshl_add_u64 v[200:201], v[4:5], 0, v[200:201]
	global_load_dwordx2 v[200:201], v[200:201], off
	v_or_b32_e32 v202, 0x2c0, v32
	v_mov_b32_e32 v203, v33
	v_lshl_add_u64 v[202:203], v[4:5], 0, v[202:203]
	global_load_dwordx2 v[202:203], v[202:203], off
	v_or_b32_e32 v204, 0x2e0, v32
	v_mov_b32_e32 v205, v33
	v_lshl_add_u64 v[204:205], v[4:5], 0, v[204:205]
	global_load_dwordx2 v[204:205], v[204:205], off
	v_or_b32_e32 v206, 0x300, v32
	v_mov_b32_e32 v207, v33
	v_lshl_add_u64 v[206:207], v[4:5], 0, v[206:207]
	global_load_dwordx2 v[206:207], v[206:207], off
	v_or_b32_e32 v208, 0x320, v32
	v_mov_b32_e32 v209, v33
	v_lshl_add_u64 v[208:209], v[4:5], 0, v[208:209]
	global_load_dwordx2 v[208:209], v[208:209], off
	v_or_b32_e32 v210, 0x340, v32
	v_mov_b32_e32 v211, v33
	v_lshl_add_u64 v[210:211], v[4:5], 0, v[210:211]
	global_load_dwordx2 v[210:211], v[210:211], off
	v_or_b32_e32 v212, 0x360, v32
	v_mov_b32_e32 v213, v33
	v_lshl_add_u64 v[212:213], v[4:5], 0, v[212:213]
	global_load_dwordx2 v[212:213], v[212:213], off
	v_or_b32_e32 v214, 0x380, v32
	v_mov_b32_e32 v215, v33
	v_lshl_add_u64 v[214:215], v[4:5], 0, v[214:215]
	global_load_dwordx2 v[214:215], v[214:215], off
	v_or_b32_e32 v216, 0x3a0, v32
	v_mov_b32_e32 v217, v33
	v_lshl_add_u64 v[216:217], v[4:5], 0, v[216:217]
	global_load_dwordx2 v[216:217], v[216:217], off
	v_or_b32_e32 v218, 0x3c0, v32
	v_mov_b32_e32 v219, v33
	v_lshl_add_u64 v[218:219], v[4:5], 0, v[218:219]
	global_load_dwordx2 v[218:219], v[218:219], off
	v_or_b32_e32 v220, 0x3e0, v32
	v_mov_b32_e32 v221, v33
	v_lshl_add_u64 v[220:221], v[4:5], 0, v[220:221]
	global_load_dwordx2 v[220:221], v[220:221], off
	ds_swizzle_b32 v10, v8 offset:swizzle(SWAP,16)
	v_lshlrev_b64 v[2:3], 11, v[36:37]
	v_lshl_add_u64 v[18:19], s[86:87], 0, v[2:3]
	v_lshlrev_b32_e32 v9, 16, v150
	v_and_b32_e32 v11, 0xffff0000, v150
	s_waitcnt lgkmcnt(0)
	v_add_f32_e32 v8, v8, v10
	v_mov_b32_e32 v10, v8
	s_nop 1
	v_permlane32_swap_b32_e32 v8, v10
	v_add_f32_e32 v8, v8, v10
	v_fmamk_f32 v8, v8, 0x3b000000, v124
	v_mul_f32_e32 v10, 0x4b800000, v8
	v_cmp_gt_f32_e32 vcc, s3, v8
	v_lshlrev_b32_e32 v13, 16, v148
	v_and_b32_e32 v15, 0xffff0000, v148
	v_cndmask_b32_e32 v8, v8, v10, vcc
	v_rsq_f32_e32 v8, v8
	v_or_b32_e32 v16, 32, v32
	v_mov_b32_e32 v17, v33
	v_lshl_add_u64 v[16:17], v[4:5], 0, v[16:17]
	v_mul_f32_e32 v2, 0x45800000, v8
	v_cndmask_b32_e32 v3, v8, v2, vcc
	v_mov_b32_e32 v24, v3
	v_mov_b32_e32 v26, v3
	v_mov_b32_e32 v30, v3
	s_add_i32 s54, s54, s52
	s_add_u32 s4, s4, s6
	s_addc_u32 s5, s5, s7
	s_cmpk_gt_i32 s54, 0xff
	s_waitcnt vmcnt(0)
	v_lshlrev_b32_e32 v8, 16, v0
	v_and_b32_e32 v10, 0xffff0000, v0
	v_mul_f32_e32 v0, 0xbfb8aa3b, v8
	v_exp_f32_e32 v0, v0
	v_lshlrev_b32_e32 v12, 16, v1
	v_and_b32_e32 v14, 0xffff0000, v1
	v_mul_f32_e32 v1, 0xbfb8aa3b, v10
	v_exp_f32_e32 v1, v1
	v_add_f32_e32 v0, 1.0, v0
	v_rcp_f32_e32 v2, v0
	v_mul_f32_e32 v0, 0xbfb8aa3b, v12
	v_exp_f32_e32 v0, v0
	v_add_f32_e32 v1, 1.0, v1
	v_pk_mul_f32 v[8:9], v[2:3], v[8:9]
	v_rcp_f32_e32 v2, v1
	v_mul_f32_e32 v1, 0xbfb8aa3b, v14
	v_exp_f32_e32 v22, v1
	v_add_f32_e32 v0, 1.0, v0
	v_pk_mul_f32 v[10:11], v[2:3], v[10:11]
	v_rcp_f32_e32 v2, v0
	v_lshl_add_u64 v[0:1], v[18:19], 0, v[32:33]
	v_add_f32_e32 v18, 1.0, v22
	v_mul_f32_e32 v19, v8, v9
	v_pk_mul_f32 v[8:9], v[2:3], v[12:13]
	v_rcp_f32_e32 v2, v18
	v_mul_f32_e32 v10, v10, v11
	v_mul_f32_e32 v11, v8, v9
	v_cvt_pk_bf16_f32 v10, v19, v10
	v_pk_mul_f32 v[8:9], v[2:3], v[14:15]
	v_and_b32_e32 v12, 0xffff0000, v145
	v_mul_f32_e32 v2, v8, v9
	v_cvt_pk_bf16_f32 v11, v11, v2
	global_store_dwordx2 v[0:1], v[10:11], off offset:1024
	v_mov_b64_e32 v[8:9], v[160:161]
	v_lshlrev_b32_e32 v10, 16, v145
	v_lshlrev_b32_e32 v14, 16, v142
	v_mov_b32_e32 v22, v3
	v_and_b32_e32 v16, 0xffff0000, v142
	v_or_b32_e32 v18, 64, v32
	v_mov_b32_e32 v19, v33
	v_lshl_add_u64 v[18:19], v[4:5], 0, v[18:19]
	v_lshlrev_b32_e32 v11, 16, v8
	v_and_b32_e32 v13, 0xffff0000, v8
	v_lshlrev_b32_e32 v15, 16, v9
	v_and_b32_e32 v17, 0xffff0000, v9
	v_mul_f32_e32 v2, 0xbfb8aa3b, v11
	v_mul_f32_e32 v8, 0xbfb8aa3b, v13
	v_mul_f32_e32 v9, 0xbfb8aa3b, v15
	v_mul_f32_e32 v23, 0xbfb8aa3b, v17
	v_exp_f32_e32 v2, v2
	v_exp_f32_e32 v8, v8
	v_exp_f32_e32 v9, v9
	v_exp_f32_e32 v23, v23
	v_add_f32_e32 v2, 1.0, v2
	v_add_f32_e32 v8, 1.0, v8
	v_add_f32_e32 v9, 1.0, v9
	v_add_f32_e32 v28, 1.0, v23
	v_rcp_f32_e32 v23, v2
	v_rcp_f32_e32 v25, v8
	v_rcp_f32_e32 v27, v9
	v_rcp_f32_e32 v31, v28
	v_pk_mul_f32 v[8:9], v[22:23], v[10:11]
	v_pk_mul_f32 v[10:11], v[24:25], v[12:13]
	v_pk_mul_f32 v[12:13], v[26:27], v[14:15]
	v_pk_mul_f32 v[14:15], v[30:31], v[16:17]
	v_mul_f32_e32 v2, v8, v9
	v_mul_f32_e32 v8, v10, v11
	v_mul_f32_e32 v9, v12, v13
	v_mul_f32_e32 v10, v14, v15
	v_cvt_pk_bf16_f32 v8, v2, v8
	v_cvt_pk_bf16_f32 v9, v9, v10
	global_store_dwordx2 v[0:1], v[8:9], off offset:1056
	v_mov_b64_e32 v[8:9], v[162:163]
	v_lshlrev_b32_e32 v10, 16, v139
	v_and_b32_e32 v12, 0xffff0000, v139
	v_lshlrev_b32_e32 v14, 16, v137
	v_and_b32_e32 v16, 0xffff0000, v137
	v_or_b32_e32 v18, 0x60, v32
	v_mov_b32_e32 v19, v33
	v_lshl_add_u64 v[18:19], v[4:5], 0, v[18:19]
	v_lshlrev_b32_e32 v11, 16, v8
	v_and_b32_e32 v13, 0xffff0000, v8
	v_lshlrev_b32_e32 v15, 16, v9
	v_and_b32_e32 v17, 0xffff0000, v9
	v_mul_f32_e32 v2, 0xbfb8aa3b, v11
	v_mul_f32_e32 v8, 0xbfb8aa3b, v13
	v_mul_f32_e32 v9, 0xbfb8aa3b, v15
	v_mul_f32_e32 v23, 0xbfb8aa3b, v17
	v_exp_f32_e32 v2, v2
	v_exp_f32_e32 v8, v8
	v_exp_f32_e32 v9, v9
	v_exp_f32_e32 v23, v23
	v_add_f32_e32 v2, 1.0, v2
	v_add_f32_e32 v8, 1.0, v8
	v_add_f32_e32 v9, 1.0, v9
	v_add_f32_e32 v28, 1.0, v23
	v_rcp_f32_e32 v23, v2
	v_rcp_f32_e32 v25, v8
	v_rcp_f32_e32 v27, v9
	v_rcp_f32_e32 v31, v28
	v_pk_mul_f32 v[8:9], v[22:23], v[10:11]
	v_pk_mul_f32 v[10:11], v[24:25], v[12:13]
	v_pk_mul_f32 v[12:13], v[26:27], v[14:15]
	v_pk_mul_f32 v[14:15], v[30:31], v[16:17]
	v_mul_f32_e32 v2, v8, v9
	v_mul_f32_e32 v8, v10, v11
	v_mul_f32_e32 v9, v12, v13
	v_mul_f32_e32 v10, v14, v15
	v_cvt_pk_bf16_f32 v8, v2, v8
	v_cvt_pk_bf16_f32 v9, v9, v10
	global_store_dwordx2 v[0:1], v[8:9], off offset:1088
	v_mov_b64_e32 v[8:9], v[164:165]
	v_lshlrev_b32_e32 v10, 16, v136
	v_and_b32_e32 v12, 0xffff0000, v136
	v_lshlrev_b32_e32 v14, 16, v133
	v_and_b32_e32 v16, 0xffff0000, v133
	v_or_b32_e32 v18, 0x80, v32
	v_mov_b32_e32 v19, v33
	v_lshl_add_u64 v[18:19], v[4:5], 0, v[18:19]
	v_lshlrev_b32_e32 v11, 16, v8
	v_and_b32_e32 v13, 0xffff0000, v8
	v_lshlrev_b32_e32 v15, 16, v9
	v_and_b32_e32 v17, 0xffff0000, v9
	v_mul_f32_e32 v2, 0xbfb8aa3b, v11
	v_mul_f32_e32 v8, 0xbfb8aa3b, v13
	v_mul_f32_e32 v9, 0xbfb8aa3b, v15
	v_mul_f32_e32 v23, 0xbfb8aa3b, v17
	v_exp_f32_e32 v2, v2
	v_exp_f32_e32 v8, v8
	v_exp_f32_e32 v9, v9
	v_exp_f32_e32 v23, v23
	v_add_f32_e32 v2, 1.0, v2
	v_add_f32_e32 v8, 1.0, v8
	v_add_f32_e32 v9, 1.0, v9
	v_add_f32_e32 v28, 1.0, v23
	v_rcp_f32_e32 v23, v2
	v_rcp_f32_e32 v25, v8
	v_rcp_f32_e32 v27, v9
	v_rcp_f32_e32 v31, v28
	v_pk_mul_f32 v[8:9], v[22:23], v[10:11]
	v_pk_mul_f32 v[10:11], v[24:25], v[12:13]
	v_pk_mul_f32 v[12:13], v[26:27], v[14:15]
	v_pk_mul_f32 v[14:15], v[30:31], v[16:17]
	v_mul_f32_e32 v2, v8, v9
	v_mul_f32_e32 v8, v10, v11
	v_mul_f32_e32 v9, v12, v13
	v_mul_f32_e32 v10, v14, v15
	v_cvt_pk_bf16_f32 v8, v2, v8
	v_cvt_pk_bf16_f32 v9, v9, v10
	global_store_dwordx2 v[0:1], v[8:9], off offset:1120
	v_mov_b64_e32 v[8:9], v[166:167]
	v_lshlrev_b32_e32 v10, 16, v134
	v_and_b32_e32 v12, 0xffff0000, v134
	v_lshlrev_b32_e32 v14, 16, v132
	v_and_b32_e32 v16, 0xffff0000, v132
	v_or_b32_e32 v18, 0xa0, v32
	v_mov_b32_e32 v19, v33
	v_lshl_add_u64 v[18:19], v[4:5], 0, v[18:19]
	v_lshlrev_b32_e32 v11, 16, v8
	v_and_b32_e32 v13, 0xffff0000, v8
	v_lshlrev_b32_e32 v15, 16, v9
	v_and_b32_e32 v17, 0xffff0000, v9
	v_mul_f32_e32 v2, 0xbfb8aa3b, v11
	v_mul_f32_e32 v8, 0xbfb8aa3b, v13
	v_mul_f32_e32 v9, 0xbfb8aa3b, v15
	v_mul_f32_e32 v23, 0xbfb8aa3b, v17
	v_exp_f32_e32 v2, v2
	v_exp_f32_e32 v8, v8
	v_exp_f32_e32 v9, v9
	v_exp_f32_e32 v23, v23
	v_add_f32_e32 v2, 1.0, v2
	v_add_f32_e32 v8, 1.0, v8
	v_add_f32_e32 v9, 1.0, v9
	v_add_f32_e32 v28, 1.0, v23
	v_rcp_f32_e32 v23, v2
	v_rcp_f32_e32 v25, v8
	v_rcp_f32_e32 v27, v9
	v_rcp_f32_e32 v31, v28
	v_pk_mul_f32 v[8:9], v[22:23], v[10:11]
	v_pk_mul_f32 v[10:11], v[24:25], v[12:13]
	v_pk_mul_f32 v[12:13], v[26:27], v[14:15]
	v_pk_mul_f32 v[14:15], v[30:31], v[16:17]
	v_mul_f32_e32 v2, v8, v9
	v_mul_f32_e32 v8, v10, v11
	v_mul_f32_e32 v9, v12, v13
	v_mul_f32_e32 v10, v14, v15
	v_cvt_pk_bf16_f32 v8, v2, v8
	v_cvt_pk_bf16_f32 v9, v9, v10
	global_store_dwordx2 v[0:1], v[8:9], off offset:1152
	v_mov_b64_e32 v[8:9], v[168:169]
	v_lshlrev_b32_e32 v10, 16, v130
	v_and_b32_e32 v12, 0xffff0000, v130
	v_lshlrev_b32_e32 v14, 16, v129
	v_and_b32_e32 v16, 0xffff0000, v129
	v_or_b32_e32 v18, 0xc0, v32
	v_mov_b32_e32 v19, v33
	v_lshl_add_u64 v[18:19], v[4:5], 0, v[18:19]
	v_lshlrev_b32_e32 v11, 16, v8
	v_and_b32_e32 v13, 0xffff0000, v8
	v_lshlrev_b32_e32 v15, 16, v9
	v_and_b32_e32 v17, 0xffff0000, v9
	v_mul_f32_e32 v2, 0xbfb8aa3b, v11
	v_mul_f32_e32 v8, 0xbfb8aa3b, v13
	v_mul_f32_e32 v9, 0xbfb8aa3b, v15
	v_mul_f32_e32 v23, 0xbfb8aa3b, v17
	v_exp_f32_e32 v2, v2
	v_exp_f32_e32 v8, v8
	v_exp_f32_e32 v9, v9
	v_exp_f32_e32 v23, v23
	v_add_f32_e32 v2, 1.0, v2
	v_add_f32_e32 v8, 1.0, v8
	v_add_f32_e32 v9, 1.0, v9
	v_add_f32_e32 v28, 1.0, v23
	v_rcp_f32_e32 v23, v2
	v_rcp_f32_e32 v25, v8
	v_rcp_f32_e32 v27, v9
	v_rcp_f32_e32 v31, v28
	v_pk_mul_f32 v[8:9], v[22:23], v[10:11]
	v_pk_mul_f32 v[10:11], v[24:25], v[12:13]
	v_pk_mul_f32 v[12:13], v[26:27], v[14:15]
	v_pk_mul_f32 v[14:15], v[30:31], v[16:17]
	v_mul_f32_e32 v2, v8, v9
	v_mul_f32_e32 v8, v10, v11
	v_mul_f32_e32 v9, v12, v13
	v_mul_f32_e32 v10, v14, v15
	v_cvt_pk_bf16_f32 v8, v2, v8
	v_cvt_pk_bf16_f32 v9, v9, v10
	global_store_dwordx2 v[0:1], v[8:9], off offset:1184
	v_mov_b64_e32 v[8:9], v[170:171]
	v_lshlrev_b32_e32 v10, 16, v128
	v_and_b32_e32 v12, 0xffff0000, v128
	v_lshlrev_b32_e32 v14, 16, v127
	v_and_b32_e32 v16, 0xffff0000, v127
	v_or_b32_e32 v18, 0xe0, v32
	v_mov_b32_e32 v19, v33
	v_lshl_add_u64 v[18:19], v[4:5], 0, v[18:19]
	v_lshlrev_b32_e32 v11, 16, v8
	v_and_b32_e32 v13, 0xffff0000, v8
	v_lshlrev_b32_e32 v15, 16, v9
	v_and_b32_e32 v17, 0xffff0000, v9
	v_mul_f32_e32 v2, 0xbfb8aa3b, v11
	v_mul_f32_e32 v8, 0xbfb8aa3b, v13
	v_mul_f32_e32 v9, 0xbfb8aa3b, v15
	v_mul_f32_e32 v23, 0xbfb8aa3b, v17
	v_exp_f32_e32 v2, v2
	v_exp_f32_e32 v8, v8
	v_exp_f32_e32 v9, v9
	v_exp_f32_e32 v23, v23
	v_add_f32_e32 v2, 1.0, v2
	v_add_f32_e32 v8, 1.0, v8
	v_add_f32_e32 v9, 1.0, v9
	v_add_f32_e32 v28, 1.0, v23
	v_rcp_f32_e32 v23, v2
	v_rcp_f32_e32 v25, v8
	v_rcp_f32_e32 v27, v9
	v_rcp_f32_e32 v31, v28
	v_pk_mul_f32 v[8:9], v[22:23], v[10:11]
	v_pk_mul_f32 v[10:11], v[24:25], v[12:13]
	v_pk_mul_f32 v[12:13], v[26:27], v[14:15]
	v_pk_mul_f32 v[14:15], v[30:31], v[16:17]
	v_mul_f32_e32 v2, v8, v9
	v_mul_f32_e32 v8, v10, v11
	v_mul_f32_e32 v9, v12, v13
	v_mul_f32_e32 v10, v14, v15
	v_cvt_pk_bf16_f32 v8, v2, v8
	v_cvt_pk_bf16_f32 v9, v9, v10
	global_store_dwordx2 v[0:1], v[8:9], off offset:1216
	v_mov_b64_e32 v[8:9], v[172:173]
	v_lshlrev_b32_e32 v10, 16, v126
	v_and_b32_e32 v12, 0xffff0000, v126
	v_lshlrev_b32_e32 v14, 16, v125
	v_and_b32_e32 v16, 0xffff0000, v125
	v_or_b32_e32 v18, 0x100, v32
	v_mov_b32_e32 v19, v33
	v_lshl_add_u64 v[18:19], v[4:5], 0, v[18:19]
	v_lshlrev_b32_e32 v11, 16, v8
	v_and_b32_e32 v13, 0xffff0000, v8
	v_lshlrev_b32_e32 v15, 16, v9
	v_and_b32_e32 v17, 0xffff0000, v9
	v_mul_f32_e32 v2, 0xbfb8aa3b, v11
	v_mul_f32_e32 v8, 0xbfb8aa3b, v13
	v_mul_f32_e32 v9, 0xbfb8aa3b, v15
	v_mul_f32_e32 v23, 0xbfb8aa3b, v17
	v_exp_f32_e32 v2, v2
	v_exp_f32_e32 v8, v8
	v_exp_f32_e32 v9, v9
	v_exp_f32_e32 v23, v23
	v_add_f32_e32 v2, 1.0, v2
	v_add_f32_e32 v8, 1.0, v8
	v_add_f32_e32 v9, 1.0, v9
	v_add_f32_e32 v28, 1.0, v23
	v_rcp_f32_e32 v23, v2
	v_rcp_f32_e32 v25, v8
	v_rcp_f32_e32 v27, v9
	v_rcp_f32_e32 v31, v28
	v_pk_mul_f32 v[8:9], v[22:23], v[10:11]
	v_pk_mul_f32 v[10:11], v[24:25], v[12:13]
	v_pk_mul_f32 v[12:13], v[26:27], v[14:15]
	v_pk_mul_f32 v[14:15], v[30:31], v[16:17]
	v_mul_f32_e32 v2, v8, v9
	v_mul_f32_e32 v8, v10, v11
	v_mul_f32_e32 v9, v12, v13
	v_mul_f32_e32 v10, v14, v15
	v_cvt_pk_bf16_f32 v8, v2, v8
	v_cvt_pk_bf16_f32 v9, v9, v10
	global_store_dwordx2 v[0:1], v[8:9], off offset:1248
	v_mov_b64_e32 v[8:9], v[174:175]
	v_lshlrev_b32_e32 v10, 16, v156
	v_and_b32_e32 v12, 0xffff0000, v156
	v_lshlrev_b32_e32 v14, 16, v154
	v_and_b32_e32 v16, 0xffff0000, v154
	v_or_b32_e32 v18, 0x120, v32
	v_mov_b32_e32 v19, v33
	v_lshl_add_u64 v[18:19], v[4:5], 0, v[18:19]
	v_lshlrev_b32_e32 v11, 16, v8
	v_and_b32_e32 v13, 0xffff0000, v8
	v_lshlrev_b32_e32 v15, 16, v9
	v_and_b32_e32 v17, 0xffff0000, v9
	v_mul_f32_e32 v2, 0xbfb8aa3b, v11
	v_mul_f32_e32 v8, 0xbfb8aa3b, v13
	v_mul_f32_e32 v9, 0xbfb8aa3b, v15
	v_mul_f32_e32 v23, 0xbfb8aa3b, v17
	v_exp_f32_e32 v2, v2
	v_exp_f32_e32 v8, v8
	v_exp_f32_e32 v9, v9
	v_exp_f32_e32 v23, v23
	v_add_f32_e32 v2, 1.0, v2
	v_add_f32_e32 v8, 1.0, v8
	v_add_f32_e32 v9, 1.0, v9
	v_add_f32_e32 v28, 1.0, v23
	v_rcp_f32_e32 v23, v2
	v_rcp_f32_e32 v25, v8
	v_rcp_f32_e32 v27, v9
	v_rcp_f32_e32 v31, v28
	v_pk_mul_f32 v[8:9], v[22:23], v[10:11]
	v_pk_mul_f32 v[10:11], v[24:25], v[12:13]
	v_pk_mul_f32 v[12:13], v[26:27], v[14:15]
	v_pk_mul_f32 v[14:15], v[30:31], v[16:17]
	v_mul_f32_e32 v2, v8, v9
	v_mul_f32_e32 v8, v10, v11
	v_mul_f32_e32 v9, v12, v13
	v_mul_f32_e32 v10, v14, v15
	v_cvt_pk_bf16_f32 v8, v2, v8
	v_cvt_pk_bf16_f32 v9, v9, v10
	global_store_dwordx2 v[0:1], v[8:9], off offset:1280
	v_mov_b64_e32 v[8:9], v[176:177]
	v_lshlrev_b32_e32 v10, 16, v153
	v_and_b32_e32 v12, 0xffff0000, v153
	v_lshlrev_b32_e32 v14, 16, v151
	v_and_b32_e32 v16, 0xffff0000, v151
	v_or_b32_e32 v18, 0x140, v32
	v_mov_b32_e32 v19, v33
	v_lshl_add_u64 v[18:19], v[4:5], 0, v[18:19]
	v_lshlrev_b32_e32 v11, 16, v8
	v_and_b32_e32 v13, 0xffff0000, v8
	v_lshlrev_b32_e32 v15, 16, v9
	v_and_b32_e32 v17, 0xffff0000, v9
	v_mul_f32_e32 v2, 0xbfb8aa3b, v11
	v_mul_f32_e32 v8, 0xbfb8aa3b, v13
	v_mul_f32_e32 v9, 0xbfb8aa3b, v15
	v_mul_f32_e32 v23, 0xbfb8aa3b, v17
	v_exp_f32_e32 v2, v2
	v_exp_f32_e32 v8, v8
	v_exp_f32_e32 v9, v9
	v_exp_f32_e32 v23, v23
	v_add_f32_e32 v2, 1.0, v2
	v_add_f32_e32 v8, 1.0, v8
	v_add_f32_e32 v9, 1.0, v9
	v_add_f32_e32 v28, 1.0, v23
	v_rcp_f32_e32 v23, v2
	v_rcp_f32_e32 v25, v8
	v_rcp_f32_e32 v27, v9
	v_rcp_f32_e32 v31, v28
	v_pk_mul_f32 v[8:9], v[22:23], v[10:11]
	v_pk_mul_f32 v[10:11], v[24:25], v[12:13]
	v_pk_mul_f32 v[12:13], v[26:27], v[14:15]
	v_pk_mul_f32 v[14:15], v[30:31], v[16:17]
	v_mul_f32_e32 v2, v8, v9
	v_mul_f32_e32 v8, v10, v11
	v_mul_f32_e32 v9, v12, v13
	v_mul_f32_e32 v10, v14, v15
	v_cvt_pk_bf16_f32 v8, v2, v8
	v_cvt_pk_bf16_f32 v9, v9, v10
	global_store_dwordx2 v[0:1], v[8:9], off offset:1312
	v_mov_b64_e32 v[8:9], v[178:179]
	v_lshlrev_b32_e32 v10, 16, v149
	v_and_b32_e32 v12, 0xffff0000, v149
	v_lshlrev_b32_e32 v14, 16, v147
	v_and_b32_e32 v16, 0xffff0000, v147
	v_or_b32_e32 v18, 0x160, v32
	v_mov_b32_e32 v19, v33
	v_lshl_add_u64 v[18:19], v[4:5], 0, v[18:19]
	v_lshlrev_b32_e32 v11, 16, v8
	v_and_b32_e32 v13, 0xffff0000, v8
	v_lshlrev_b32_e32 v15, 16, v9
	v_and_b32_e32 v17, 0xffff0000, v9
	v_mul_f32_e32 v2, 0xbfb8aa3b, v11
	v_mul_f32_e32 v8, 0xbfb8aa3b, v13
	v_mul_f32_e32 v9, 0xbfb8aa3b, v15
	v_mul_f32_e32 v23, 0xbfb8aa3b, v17
	v_exp_f32_e32 v2, v2
	v_exp_f32_e32 v8, v8
	v_exp_f32_e32 v9, v9
	v_exp_f32_e32 v23, v23
	v_add_f32_e32 v2, 1.0, v2
	v_add_f32_e32 v8, 1.0, v8
	v_add_f32_e32 v9, 1.0, v9
	v_add_f32_e32 v28, 1.0, v23
	v_rcp_f32_e32 v23, v2
	v_rcp_f32_e32 v25, v8
	v_rcp_f32_e32 v27, v9
	v_rcp_f32_e32 v31, v28
	v_pk_mul_f32 v[8:9], v[22:23], v[10:11]
	v_pk_mul_f32 v[10:11], v[24:25], v[12:13]
	v_pk_mul_f32 v[12:13], v[26:27], v[14:15]
	v_pk_mul_f32 v[14:15], v[30:31], v[16:17]
	v_mul_f32_e32 v2, v8, v9
	v_mul_f32_e32 v8, v10, v11
	v_mul_f32_e32 v9, v12, v13
	v_mul_f32_e32 v10, v14, v15
	v_cvt_pk_bf16_f32 v8, v2, v8
	v_cvt_pk_bf16_f32 v9, v9, v10
	global_store_dwordx2 v[0:1], v[8:9], off offset:1344
	v_mov_b64_e32 v[8:9], v[180:181]
	v_lshlrev_b32_e32 v10, 16, v146
	v_and_b32_e32 v12, 0xffff0000, v146
	v_lshlrev_b32_e32 v14, 16, v143
	v_and_b32_e32 v16, 0xffff0000, v143
	v_or_b32_e32 v18, 0x180, v32
	v_mov_b32_e32 v19, v33
	v_lshl_add_u64 v[18:19], v[4:5], 0, v[18:19]
	v_lshlrev_b32_e32 v11, 16, v8
	v_and_b32_e32 v13, 0xffff0000, v8
	v_lshlrev_b32_e32 v15, 16, v9
	v_and_b32_e32 v17, 0xffff0000, v9
	v_mul_f32_e32 v2, 0xbfb8aa3b, v11
	v_mul_f32_e32 v8, 0xbfb8aa3b, v13
	v_mul_f32_e32 v9, 0xbfb8aa3b, v15
	v_mul_f32_e32 v23, 0xbfb8aa3b, v17
	v_exp_f32_e32 v2, v2
	v_exp_f32_e32 v8, v8
	v_exp_f32_e32 v9, v9
	v_exp_f32_e32 v23, v23
	v_add_f32_e32 v2, 1.0, v2
	v_add_f32_e32 v8, 1.0, v8
	v_add_f32_e32 v9, 1.0, v9
	v_add_f32_e32 v28, 1.0, v23
	v_rcp_f32_e32 v23, v2
	v_rcp_f32_e32 v25, v8
	v_rcp_f32_e32 v27, v9
	v_rcp_f32_e32 v31, v28
	v_pk_mul_f32 v[8:9], v[22:23], v[10:11]
	v_pk_mul_f32 v[10:11], v[24:25], v[12:13]
	v_pk_mul_f32 v[12:13], v[26:27], v[14:15]
	v_pk_mul_f32 v[14:15], v[30:31], v[16:17]
	v_mul_f32_e32 v2, v8, v9
	v_mul_f32_e32 v8, v10, v11
	v_mul_f32_e32 v9, v12, v13
	v_mul_f32_e32 v10, v14, v15
	v_cvt_pk_bf16_f32 v8, v2, v8
	v_cvt_pk_bf16_f32 v9, v9, v10
	global_store_dwordx2 v[0:1], v[8:9], off offset:1376
	v_mov_b64_e32 v[8:9], v[182:183]
	v_lshlrev_b32_e32 v10, 16, v144
	v_and_b32_e32 v12, 0xffff0000, v144
	v_lshlrev_b32_e32 v14, 16, v141
	v_and_b32_e32 v16, 0xffff0000, v141
	v_or_b32_e32 v18, 0x1a0, v32
	v_mov_b32_e32 v19, v33
	v_lshl_add_u64 v[18:19], v[4:5], 0, v[18:19]
	v_lshlrev_b32_e32 v11, 16, v8
	v_and_b32_e32 v13, 0xffff0000, v8
	v_lshlrev_b32_e32 v15, 16, v9
	v_and_b32_e32 v17, 0xffff0000, v9
	v_mul_f32_e32 v2, 0xbfb8aa3b, v11
	v_mul_f32_e32 v8, 0xbfb8aa3b, v13
	v_mul_f32_e32 v9, 0xbfb8aa3b, v15
	v_mul_f32_e32 v23, 0xbfb8aa3b, v17
	v_exp_f32_e32 v2, v2
	v_exp_f32_e32 v8, v8
	v_exp_f32_e32 v9, v9
	v_exp_f32_e32 v23, v23
	v_add_f32_e32 v2, 1.0, v2
	v_add_f32_e32 v8, 1.0, v8
	v_add_f32_e32 v9, 1.0, v9
	v_add_f32_e32 v28, 1.0, v23
	v_rcp_f32_e32 v23, v2
	v_rcp_f32_e32 v25, v8
	v_rcp_f32_e32 v27, v9
	v_rcp_f32_e32 v31, v28
	v_pk_mul_f32 v[8:9], v[22:23], v[10:11]
	v_pk_mul_f32 v[10:11], v[24:25], v[12:13]
	v_pk_mul_f32 v[12:13], v[26:27], v[14:15]
	v_pk_mul_f32 v[14:15], v[30:31], v[16:17]
	v_mul_f32_e32 v2, v8, v9
	v_mul_f32_e32 v8, v10, v11
	v_mul_f32_e32 v9, v12, v13
	v_mul_f32_e32 v10, v14, v15
	v_cvt_pk_bf16_f32 v8, v2, v8
	v_cvt_pk_bf16_f32 v9, v9, v10
	global_store_dwordx2 v[0:1], v[8:9], off offset:1408
	v_mov_b64_e32 v[8:9], v[184:185]
	v_lshlrev_b32_e32 v10, 16, v140
	v_and_b32_e32 v12, 0xffff0000, v140
	v_lshlrev_b32_e32 v14, 16, v138
	v_and_b32_e32 v16, 0xffff0000, v138
	v_or_b32_e32 v18, 0x1c0, v32
	v_mov_b32_e32 v19, v33
	v_lshl_add_u64 v[18:19], v[4:5], 0, v[18:19]
	v_lshlrev_b32_e32 v11, 16, v8
	v_and_b32_e32 v13, 0xffff0000, v8
	v_lshlrev_b32_e32 v15, 16, v9
	v_and_b32_e32 v17, 0xffff0000, v9
	v_mul_f32_e32 v2, 0xbfb8aa3b, v11
	v_mul_f32_e32 v8, 0xbfb8aa3b, v13
	v_mul_f32_e32 v9, 0xbfb8aa3b, v15
	v_mul_f32_e32 v23, 0xbfb8aa3b, v17
	v_exp_f32_e32 v2, v2
	v_exp_f32_e32 v8, v8
	v_exp_f32_e32 v9, v9
	v_exp_f32_e32 v23, v23
	v_add_f32_e32 v2, 1.0, v2
	v_add_f32_e32 v8, 1.0, v8
	v_add_f32_e32 v9, 1.0, v9
	v_add_f32_e32 v28, 1.0, v23
	v_rcp_f32_e32 v23, v2
	v_rcp_f32_e32 v25, v8
	v_rcp_f32_e32 v27, v9
	v_rcp_f32_e32 v31, v28
	v_pk_mul_f32 v[8:9], v[22:23], v[10:11]
	v_pk_mul_f32 v[10:11], v[24:25], v[12:13]
	v_pk_mul_f32 v[12:13], v[26:27], v[14:15]
	v_pk_mul_f32 v[14:15], v[30:31], v[16:17]
	v_mul_f32_e32 v2, v8, v9
	v_mul_f32_e32 v8, v10, v11
	v_mul_f32_e32 v9, v12, v13
	v_mul_f32_e32 v10, v14, v15
	v_cvt_pk_bf16_f32 v8, v2, v8
	v_cvt_pk_bf16_f32 v9, v9, v10
	global_store_dwordx2 v[0:1], v[8:9], off offset:1440
	v_mov_b64_e32 v[8:9], v[186:187]
	v_lshlrev_b32_e32 v10, 16, v135
	v_and_b32_e32 v12, 0xffff0000, v135
	v_lshlrev_b32_e32 v14, 16, v131
	v_and_b32_e32 v16, 0xffff0000, v131
	v_or_b32_e32 v18, 0x1e0, v32
	v_mov_b32_e32 v19, v33
	v_lshl_add_u64 v[18:19], v[4:5], 0, v[18:19]
	v_lshlrev_b32_e32 v11, 16, v8
	v_and_b32_e32 v13, 0xffff0000, v8
	v_lshlrev_b32_e32 v15, 16, v9
	v_and_b32_e32 v17, 0xffff0000, v9
	v_mul_f32_e32 v2, 0xbfb8aa3b, v11
	v_mul_f32_e32 v8, 0xbfb8aa3b, v13
	v_mul_f32_e32 v9, 0xbfb8aa3b, v15
	v_mul_f32_e32 v23, 0xbfb8aa3b, v17
	v_exp_f32_e32 v2, v2
	v_exp_f32_e32 v8, v8
	v_exp_f32_e32 v9, v9
	v_exp_f32_e32 v23, v23
	v_add_f32_e32 v2, 1.0, v2
	v_add_f32_e32 v8, 1.0, v8
	v_add_f32_e32 v9, 1.0, v9
	v_add_f32_e32 v28, 1.0, v23
	v_rcp_f32_e32 v23, v2
	v_rcp_f32_e32 v25, v8
	v_rcp_f32_e32 v27, v9
	v_rcp_f32_e32 v31, v28
	v_pk_mul_f32 v[8:9], v[22:23], v[10:11]
	v_pk_mul_f32 v[10:11], v[24:25], v[12:13]
	v_pk_mul_f32 v[12:13], v[26:27], v[14:15]
	v_pk_mul_f32 v[14:15], v[30:31], v[16:17]
	v_mul_f32_e32 v2, v8, v9
	v_mul_f32_e32 v8, v10, v11
	v_mul_f32_e32 v9, v12, v13
	v_mul_f32_e32 v10, v14, v15
	v_cvt_pk_bf16_f32 v8, v2, v8
	v_cvt_pk_bf16_f32 v9, v9, v10
	global_store_dwordx2 v[0:1], v[8:9], off offset:1472
	v_mov_b64_e32 v[8:9], v[188:189]
	v_lshlrev_b32_e32 v10, 16, v122
	v_and_b32_e32 v12, 0xffff0000, v122
	v_lshlrev_b32_e32 v14, 16, v120
	v_and_b32_e32 v16, 0xffff0000, v120
	v_or_b32_e32 v18, 0x200, v32
	v_mov_b32_e32 v19, v33
	v_lshl_add_u64 v[18:19], v[4:5], 0, v[18:19]
	v_lshlrev_b32_e32 v11, 16, v8
	v_and_b32_e32 v13, 0xffff0000, v8
	v_lshlrev_b32_e32 v15, 16, v9
	v_and_b32_e32 v17, 0xffff0000, v9
	v_mul_f32_e32 v2, 0xbfb8aa3b, v11
	v_mul_f32_e32 v8, 0xbfb8aa3b, v13
	v_mul_f32_e32 v9, 0xbfb8aa3b, v15
	v_mul_f32_e32 v23, 0xbfb8aa3b, v17
	v_exp_f32_e32 v2, v2
	v_exp_f32_e32 v8, v8
	v_exp_f32_e32 v9, v9
	v_exp_f32_e32 v23, v23
	v_add_f32_e32 v2, 1.0, v2
	v_add_f32_e32 v8, 1.0, v8
	v_add_f32_e32 v9, 1.0, v9
	v_add_f32_e32 v28, 1.0, v23
	v_rcp_f32_e32 v23, v2
	v_rcp_f32_e32 v25, v8
	v_rcp_f32_e32 v27, v9
	v_rcp_f32_e32 v31, v28
	v_pk_mul_f32 v[8:9], v[22:23], v[10:11]
	v_pk_mul_f32 v[10:11], v[24:25], v[12:13]
	v_pk_mul_f32 v[12:13], v[26:27], v[14:15]
	v_pk_mul_f32 v[14:15], v[30:31], v[16:17]
	v_mul_f32_e32 v2, v8, v9
	v_mul_f32_e32 v8, v10, v11
	v_mul_f32_e32 v9, v12, v13
	v_mul_f32_e32 v10, v14, v15
	v_cvt_pk_bf16_f32 v8, v2, v8
	v_cvt_pk_bf16_f32 v9, v9, v10
	global_store_dwordx2 v[0:1], v[8:9], off offset:1504
	v_mov_b64_e32 v[8:9], v[190:191]
	v_lshlrev_b32_e32 v10, 16, v159
	v_and_b32_e32 v12, 0xffff0000, v159
	v_lshlrev_b32_e32 v14, 16, v158
	v_and_b32_e32 v16, 0xffff0000, v158
	v_or_b32_e32 v18, 0x220, v32
	v_mov_b32_e32 v19, v33
	v_lshl_add_u64 v[18:19], v[4:5], 0, v[18:19]
	v_lshlrev_b32_e32 v11, 16, v8
	v_and_b32_e32 v13, 0xffff0000, v8
	v_lshlrev_b32_e32 v15, 16, v9
	v_and_b32_e32 v17, 0xffff0000, v9
	v_mul_f32_e32 v2, 0xbfb8aa3b, v11
	v_mul_f32_e32 v8, 0xbfb8aa3b, v13
	v_mul_f32_e32 v9, 0xbfb8aa3b, v15
	v_mul_f32_e32 v23, 0xbfb8aa3b, v17
	v_exp_f32_e32 v2, v2
	v_exp_f32_e32 v8, v8
	v_exp_f32_e32 v9, v9
	v_exp_f32_e32 v23, v23
	v_add_f32_e32 v2, 1.0, v2
	v_add_f32_e32 v8, 1.0, v8
	v_add_f32_e32 v9, 1.0, v9
	v_add_f32_e32 v28, 1.0, v23
	v_rcp_f32_e32 v23, v2
	v_rcp_f32_e32 v25, v8
	v_rcp_f32_e32 v27, v9
	v_rcp_f32_e32 v31, v28
	v_pk_mul_f32 v[8:9], v[22:23], v[10:11]
	v_pk_mul_f32 v[10:11], v[24:25], v[12:13]
	v_pk_mul_f32 v[12:13], v[26:27], v[14:15]
	v_pk_mul_f32 v[14:15], v[30:31], v[16:17]
	v_mul_f32_e32 v2, v8, v9
	v_mul_f32_e32 v8, v10, v11
	v_mul_f32_e32 v9, v12, v13
	v_mul_f32_e32 v10, v14, v15
	v_cvt_pk_bf16_f32 v8, v2, v8
	v_cvt_pk_bf16_f32 v9, v9, v10
	global_store_dwordx2 v[0:1], v[8:9], off offset:1536
	v_mov_b64_e32 v[8:9], v[192:193]
	v_lshlrev_b32_e32 v10, 16, v123
	v_and_b32_e32 v12, 0xffff0000, v123
	v_lshlrev_b32_e32 v14, 16, v121
	v_and_b32_e32 v16, 0xffff0000, v121
	v_or_b32_e32 v18, 0x240, v32
	v_mov_b32_e32 v19, v33
	v_lshl_add_u64 v[18:19], v[4:5], 0, v[18:19]
	v_lshlrev_b32_e32 v11, 16, v8
	v_and_b32_e32 v13, 0xffff0000, v8
	v_lshlrev_b32_e32 v15, 16, v9
	v_and_b32_e32 v17, 0xffff0000, v9
	v_mul_f32_e32 v2, 0xbfb8aa3b, v11
	v_mul_f32_e32 v8, 0xbfb8aa3b, v13
	v_mul_f32_e32 v9, 0xbfb8aa3b, v15
	v_mul_f32_e32 v23, 0xbfb8aa3b, v17
	v_exp_f32_e32 v2, v2
	v_exp_f32_e32 v8, v8
	v_exp_f32_e32 v9, v9
	v_exp_f32_e32 v23, v23
	v_add_f32_e32 v2, 1.0, v2
	v_add_f32_e32 v8, 1.0, v8
	v_add_f32_e32 v9, 1.0, v9
	v_add_f32_e32 v28, 1.0, v23
	v_rcp_f32_e32 v23, v2
	v_rcp_f32_e32 v25, v8
	v_rcp_f32_e32 v27, v9
	v_rcp_f32_e32 v31, v28
	v_pk_mul_f32 v[8:9], v[22:23], v[10:11]
	v_pk_mul_f32 v[10:11], v[24:25], v[12:13]
	v_pk_mul_f32 v[12:13], v[26:27], v[14:15]
	v_pk_mul_f32 v[14:15], v[30:31], v[16:17]
	v_mul_f32_e32 v2, v8, v9
	v_mul_f32_e32 v8, v10, v11
	v_mul_f32_e32 v9, v12, v13
	v_mul_f32_e32 v10, v14, v15
	v_cvt_pk_bf16_f32 v8, v2, v8
	v_cvt_pk_bf16_f32 v9, v9, v10
	global_store_dwordx2 v[0:1], v[8:9], off offset:1568
	v_mov_b64_e32 v[8:9], v[194:195]
	v_lshlrev_b32_e32 v10, 16, v119
	v_and_b32_e32 v12, 0xffff0000, v119
	v_lshlrev_b32_e32 v14, 16, v118
	v_and_b32_e32 v16, 0xffff0000, v118
	v_or_b32_e32 v18, 0x260, v32
	v_mov_b32_e32 v19, v33
	v_lshl_add_u64 v[18:19], v[4:5], 0, v[18:19]
	v_lshlrev_b32_e32 v11, 16, v8
	v_and_b32_e32 v13, 0xffff0000, v8
	v_lshlrev_b32_e32 v15, 16, v9
	v_and_b32_e32 v17, 0xffff0000, v9
	v_mul_f32_e32 v2, 0xbfb8aa3b, v11
	v_mul_f32_e32 v8, 0xbfb8aa3b, v13
	v_mul_f32_e32 v9, 0xbfb8aa3b, v15
	v_mul_f32_e32 v23, 0xbfb8aa3b, v17
	v_exp_f32_e32 v2, v2
	v_exp_f32_e32 v8, v8
	v_exp_f32_e32 v9, v9
	v_exp_f32_e32 v23, v23
	v_add_f32_e32 v2, 1.0, v2
	v_add_f32_e32 v8, 1.0, v8
	v_add_f32_e32 v9, 1.0, v9
	v_add_f32_e32 v28, 1.0, v23
	v_rcp_f32_e32 v23, v2
	v_rcp_f32_e32 v25, v8
	v_rcp_f32_e32 v27, v9
	v_rcp_f32_e32 v31, v28
	v_pk_mul_f32 v[8:9], v[22:23], v[10:11]
	v_pk_mul_f32 v[10:11], v[24:25], v[12:13]
	v_pk_mul_f32 v[12:13], v[26:27], v[14:15]
	v_pk_mul_f32 v[14:15], v[30:31], v[16:17]
	v_mul_f32_e32 v2, v8, v9
	v_mul_f32_e32 v8, v10, v11
	v_mul_f32_e32 v9, v12, v13
	v_mul_f32_e32 v10, v14, v15
	v_cvt_pk_bf16_f32 v8, v2, v8
	v_cvt_pk_bf16_f32 v9, v9, v10
	global_store_dwordx2 v[0:1], v[8:9], off offset:1600
	v_mov_b64_e32 v[8:9], v[196:197]
	v_lshlrev_b32_e32 v10, 16, v117
	v_and_b32_e32 v12, 0xffff0000, v117
	v_lshlrev_b32_e32 v14, 16, v115
	v_and_b32_e32 v16, 0xffff0000, v115
	v_or_b32_e32 v18, 0x280, v32
	v_mov_b32_e32 v19, v33
	v_lshl_add_u64 v[18:19], v[4:5], 0, v[18:19]
	v_lshlrev_b32_e32 v11, 16, v8
	v_and_b32_e32 v13, 0xffff0000, v8
	v_lshlrev_b32_e32 v15, 16, v9
	v_and_b32_e32 v17, 0xffff0000, v9
	v_mul_f32_e32 v2, 0xbfb8aa3b, v11
	v_mul_f32_e32 v8, 0xbfb8aa3b, v13
	v_mul_f32_e32 v9, 0xbfb8aa3b, v15
	v_mul_f32_e32 v23, 0xbfb8aa3b, v17
	v_exp_f32_e32 v2, v2
	v_exp_f32_e32 v8, v8
	v_exp_f32_e32 v9, v9
	v_exp_f32_e32 v23, v23
	v_add_f32_e32 v2, 1.0, v2
	v_add_f32_e32 v8, 1.0, v8
	v_add_f32_e32 v9, 1.0, v9
	v_add_f32_e32 v28, 1.0, v23
	v_rcp_f32_e32 v23, v2
	v_rcp_f32_e32 v25, v8
	v_rcp_f32_e32 v27, v9
	v_rcp_f32_e32 v31, v28
	v_pk_mul_f32 v[8:9], v[22:23], v[10:11]
	v_pk_mul_f32 v[10:11], v[24:25], v[12:13]
	v_pk_mul_f32 v[12:13], v[26:27], v[14:15]
	v_pk_mul_f32 v[14:15], v[30:31], v[16:17]
	v_mul_f32_e32 v2, v8, v9
	v_mul_f32_e32 v8, v10, v11
	v_mul_f32_e32 v9, v12, v13
	v_mul_f32_e32 v10, v14, v15
	v_cvt_pk_bf16_f32 v8, v2, v8
	v_cvt_pk_bf16_f32 v9, v9, v10
	global_store_dwordx2 v[0:1], v[8:9], off offset:1632
	v_mov_b64_e32 v[8:9], v[198:199]
	v_lshlrev_b32_e32 v10, 16, v116
	v_and_b32_e32 v12, 0xffff0000, v116
	v_lshlrev_b32_e32 v14, 16, v114
	v_and_b32_e32 v16, 0xffff0000, v114
	v_or_b32_e32 v18, 0x2a0, v32
	v_mov_b32_e32 v19, v33
	v_lshl_add_u64 v[18:19], v[4:5], 0, v[18:19]
	v_lshlrev_b32_e32 v11, 16, v8
	v_and_b32_e32 v13, 0xffff0000, v8
	v_lshlrev_b32_e32 v15, 16, v9
	v_and_b32_e32 v17, 0xffff0000, v9
	v_mul_f32_e32 v2, 0xbfb8aa3b, v11
	v_mul_f32_e32 v8, 0xbfb8aa3b, v13
	v_mul_f32_e32 v9, 0xbfb8aa3b, v15
	v_mul_f32_e32 v23, 0xbfb8aa3b, v17
	v_exp_f32_e32 v2, v2
	v_exp_f32_e32 v8, v8
	v_exp_f32_e32 v9, v9
	v_exp_f32_e32 v23, v23
	v_add_f32_e32 v2, 1.0, v2
	v_add_f32_e32 v8, 1.0, v8
	v_add_f32_e32 v9, 1.0, v9
	v_add_f32_e32 v28, 1.0, v23
	v_rcp_f32_e32 v23, v2
	v_rcp_f32_e32 v25, v8
	v_rcp_f32_e32 v27, v9
	v_rcp_f32_e32 v31, v28
	v_pk_mul_f32 v[8:9], v[22:23], v[10:11]
	v_pk_mul_f32 v[10:11], v[24:25], v[12:13]
	v_pk_mul_f32 v[12:13], v[26:27], v[14:15]
	v_pk_mul_f32 v[14:15], v[30:31], v[16:17]
	v_mul_f32_e32 v2, v8, v9
	v_mul_f32_e32 v8, v10, v11
	v_mul_f32_e32 v9, v12, v13
	v_mul_f32_e32 v10, v14, v15
	v_cvt_pk_bf16_f32 v8, v2, v8
	v_cvt_pk_bf16_f32 v9, v9, v10
	global_store_dwordx2 v[0:1], v[8:9], off offset:1664
	v_mov_b64_e32 v[8:9], v[200:201]
	v_lshlrev_b32_e32 v10, 16, v113
	v_and_b32_e32 v12, 0xffff0000, v113
	v_lshlrev_b32_e32 v14, 16, v112
	v_and_b32_e32 v16, 0xffff0000, v112
	v_or_b32_e32 v18, 0x2c0, v32
	v_mov_b32_e32 v19, v33
	v_lshl_add_u64 v[18:19], v[4:5], 0, v[18:19]
	v_lshlrev_b32_e32 v11, 16, v8
	v_and_b32_e32 v13, 0xffff0000, v8
	v_lshlrev_b32_e32 v15, 16, v9
	v_and_b32_e32 v17, 0xffff0000, v9
	v_mul_f32_e32 v2, 0xbfb8aa3b, v11
	v_mul_f32_e32 v8, 0xbfb8aa3b, v13
	v_mul_f32_e32 v9, 0xbfb8aa3b, v15
	v_mul_f32_e32 v23, 0xbfb8aa3b, v17
	v_exp_f32_e32 v2, v2
	v_exp_f32_e32 v8, v8
	v_exp_f32_e32 v9, v9
	v_exp_f32_e32 v23, v23
	v_add_f32_e32 v2, 1.0, v2
	v_add_f32_e32 v8, 1.0, v8
	v_add_f32_e32 v9, 1.0, v9
	v_add_f32_e32 v28, 1.0, v23
	v_rcp_f32_e32 v23, v2
	v_rcp_f32_e32 v25, v8
	v_rcp_f32_e32 v27, v9
	v_rcp_f32_e32 v31, v28
	v_pk_mul_f32 v[8:9], v[22:23], v[10:11]
	v_pk_mul_f32 v[10:11], v[24:25], v[12:13]
	v_pk_mul_f32 v[12:13], v[26:27], v[14:15]
	v_pk_mul_f32 v[14:15], v[30:31], v[16:17]
	v_mul_f32_e32 v2, v8, v9
	v_mul_f32_e32 v8, v10, v11
	v_mul_f32_e32 v9, v12, v13
	v_mul_f32_e32 v10, v14, v15
	v_cvt_pk_bf16_f32 v8, v2, v8
	v_cvt_pk_bf16_f32 v9, v9, v10
	global_store_dwordx2 v[0:1], v[8:9], off offset:1696
	v_mov_b64_e32 v[8:9], v[202:203]
	v_lshlrev_b32_e32 v10, 16, v111
	v_and_b32_e32 v12, 0xffff0000, v111
	v_lshlrev_b32_e32 v14, 16, v110
	v_and_b32_e32 v16, 0xffff0000, v110
	v_or_b32_e32 v18, 0x2e0, v32
	v_mov_b32_e32 v19, v33
	v_lshl_add_u64 v[18:19], v[4:5], 0, v[18:19]
	v_lshlrev_b32_e32 v11, 16, v8
	v_and_b32_e32 v13, 0xffff0000, v8
	v_lshlrev_b32_e32 v15, 16, v9
	v_and_b32_e32 v17, 0xffff0000, v9
	v_mul_f32_e32 v2, 0xbfb8aa3b, v11
	v_mul_f32_e32 v8, 0xbfb8aa3b, v13
	v_mul_f32_e32 v9, 0xbfb8aa3b, v15
	v_mul_f32_e32 v23, 0xbfb8aa3b, v17
	v_exp_f32_e32 v2, v2
	v_exp_f32_e32 v8, v8
	v_exp_f32_e32 v9, v9
	v_exp_f32_e32 v23, v23
	v_add_f32_e32 v2, 1.0, v2
	v_add_f32_e32 v8, 1.0, v8
	v_add_f32_e32 v9, 1.0, v9
	v_add_f32_e32 v28, 1.0, v23
	v_rcp_f32_e32 v23, v2
	v_rcp_f32_e32 v25, v8
	v_rcp_f32_e32 v27, v9
	v_rcp_f32_e32 v31, v28
	v_pk_mul_f32 v[8:9], v[22:23], v[10:11]
	v_pk_mul_f32 v[10:11], v[24:25], v[12:13]
	v_pk_mul_f32 v[12:13], v[26:27], v[14:15]
	v_pk_mul_f32 v[14:15], v[30:31], v[16:17]
	v_mul_f32_e32 v2, v8, v9
	v_mul_f32_e32 v8, v10, v11
	v_mul_f32_e32 v9, v12, v13
	v_mul_f32_e32 v10, v14, v15
	v_cvt_pk_bf16_f32 v8, v2, v8
	v_cvt_pk_bf16_f32 v9, v9, v10
	global_store_dwordx2 v[0:1], v[8:9], off offset:1728
	v_mov_b64_e32 v[8:9], v[204:205]
	v_lshlrev_b32_e32 v14, 16, v29
	v_and_b32_e32 v16, 0xffff0000, v29
	v_lshlrev_b32_e32 v10, 16, v106
	v_and_b32_e32 v12, 0xffff0000, v106
	v_mov_b32_e32 v28, v3
	v_or_b32_e32 v18, 0x300, v32
	v_mov_b32_e32 v19, v33
	v_lshl_add_u64 v[18:19], v[4:5], 0, v[18:19]
	v_lshlrev_b32_e32 v11, 16, v8
	v_and_b32_e32 v13, 0xffff0000, v8
	v_lshlrev_b32_e32 v15, 16, v9
	v_and_b32_e32 v17, 0xffff0000, v9
	v_mul_f32_e32 v2, 0xbfb8aa3b, v11
	v_mul_f32_e32 v8, 0xbfb8aa3b, v13
	v_mul_f32_e32 v9, 0xbfb8aa3b, v15
	v_mul_f32_e32 v23, 0xbfb8aa3b, v17
	v_exp_f32_e32 v2, v2
	v_exp_f32_e32 v8, v8
	v_exp_f32_e32 v9, v9
	v_exp_f32_e32 v23, v23
	v_add_f32_e32 v2, 1.0, v2
	v_add_f32_e32 v8, 1.0, v8
	v_add_f32_e32 v9, 1.0, v9
	v_add_f32_e32 v29, 1.0, v23
	v_rcp_f32_e32 v23, v2
	v_rcp_f32_e32 v25, v8
	v_rcp_f32_e32 v27, v9
	v_rcp_f32_e32 v29, v29
	v_pk_mul_f32 v[8:9], v[22:23], v[10:11]
	v_pk_mul_f32 v[10:11], v[24:25], v[12:13]
	v_pk_mul_f32 v[12:13], v[26:27], v[14:15]
	v_pk_mul_f32 v[14:15], v[28:29], v[16:17]
	v_mul_f32_e32 v2, v8, v9
	v_mul_f32_e32 v8, v10, v11
	v_mul_f32_e32 v9, v12, v13
	v_mul_f32_e32 v10, v14, v15
	v_cvt_pk_bf16_f32 v8, v2, v8
	v_cvt_pk_bf16_f32 v9, v9, v10
	global_store_dwordx2 v[0:1], v[8:9], off offset:1760
	v_mov_b64_e32 v[8:9], v[206:207]
	v_lshlrev_b32_e32 v10, 16, v77
	v_and_b32_e32 v12, 0xffff0000, v77
	v_lshlrev_b32_e32 v14, 16, v76
	v_and_b32_e32 v16, 0xffff0000, v76
	v_or_b32_e32 v18, 0x320, v32
	v_mov_b32_e32 v19, v33
	v_lshl_add_u64 v[18:19], v[4:5], 0, v[18:19]
	v_lshlrev_b32_e32 v11, 16, v8
	v_and_b32_e32 v13, 0xffff0000, v8
	v_lshlrev_b32_e32 v15, 16, v9
	v_and_b32_e32 v17, 0xffff0000, v9
	v_mul_f32_e32 v2, 0xbfb8aa3b, v11
	v_mul_f32_e32 v8, 0xbfb8aa3b, v13
	v_mul_f32_e32 v9, 0xbfb8aa3b, v15
	v_mul_f32_e32 v23, 0xbfb8aa3b, v17
	v_exp_f32_e32 v2, v2
	v_exp_f32_e32 v8, v8
	v_exp_f32_e32 v9, v9
	v_exp_f32_e32 v23, v23
	v_add_f32_e32 v2, 1.0, v2
	v_add_f32_e32 v8, 1.0, v8
	v_add_f32_e32 v9, 1.0, v9
	v_add_f32_e32 v29, 1.0, v23
	v_rcp_f32_e32 v23, v2
	v_rcp_f32_e32 v25, v8
	v_rcp_f32_e32 v27, v9
	v_rcp_f32_e32 v29, v29
	v_pk_mul_f32 v[8:9], v[22:23], v[10:11]
	v_pk_mul_f32 v[10:11], v[24:25], v[12:13]
	v_pk_mul_f32 v[12:13], v[26:27], v[14:15]
	v_pk_mul_f32 v[14:15], v[28:29], v[16:17]
	v_mul_f32_e32 v2, v8, v9
	v_mul_f32_e32 v8, v10, v11
	v_mul_f32_e32 v9, v12, v13
	v_mul_f32_e32 v10, v14, v15
	v_cvt_pk_bf16_f32 v8, v2, v8
	v_cvt_pk_bf16_f32 v9, v9, v10
	global_store_dwordx2 v[0:1], v[8:9], off offset:1792
	v_mov_b64_e32 v[8:9], v[208:209]
	v_lshlrev_b32_e32 v10, 16, v75
	v_and_b32_e32 v12, 0xffff0000, v75
	v_lshlrev_b32_e32 v14, 16, v74
	v_and_b32_e32 v16, 0xffff0000, v74
	v_or_b32_e32 v18, 0x340, v32
	v_mov_b32_e32 v19, v33
	v_lshl_add_u64 v[18:19], v[4:5], 0, v[18:19]
	v_lshlrev_b32_e32 v11, 16, v8
	v_and_b32_e32 v13, 0xffff0000, v8
	v_lshlrev_b32_e32 v15, 16, v9
	v_and_b32_e32 v17, 0xffff0000, v9
	v_mul_f32_e32 v2, 0xbfb8aa3b, v11
	v_mul_f32_e32 v8, 0xbfb8aa3b, v13
	v_mul_f32_e32 v9, 0xbfb8aa3b, v15
	v_mul_f32_e32 v23, 0xbfb8aa3b, v17
	v_exp_f32_e32 v2, v2
	v_exp_f32_e32 v8, v8
	v_exp_f32_e32 v9, v9
	v_exp_f32_e32 v23, v23
	v_add_f32_e32 v2, 1.0, v2
	v_add_f32_e32 v8, 1.0, v8
	v_add_f32_e32 v9, 1.0, v9
	v_add_f32_e32 v29, 1.0, v23
	v_rcp_f32_e32 v23, v2
	v_rcp_f32_e32 v25, v8
	v_rcp_f32_e32 v27, v9
	v_rcp_f32_e32 v29, v29
	v_pk_mul_f32 v[8:9], v[22:23], v[10:11]
	v_pk_mul_f32 v[10:11], v[24:25], v[12:13]
	v_pk_mul_f32 v[12:13], v[26:27], v[14:15]
	v_pk_mul_f32 v[14:15], v[28:29], v[16:17]
	v_mul_f32_e32 v2, v8, v9
	v_mul_f32_e32 v8, v10, v11
	v_mul_f32_e32 v9, v12, v13
	v_mul_f32_e32 v10, v14, v15
	v_cvt_pk_bf16_f32 v8, v2, v8
	v_cvt_pk_bf16_f32 v9, v9, v10
	global_store_dwordx2 v[0:1], v[8:9], off offset:1824
	v_mov_b64_e32 v[8:9], v[210:211]
	v_lshlrev_b32_e32 v10, 16, v73
	v_and_b32_e32 v12, 0xffff0000, v73
	v_lshlrev_b32_e32 v14, 16, v72
	v_and_b32_e32 v16, 0xffff0000, v72
	v_or_b32_e32 v18, 0x360, v32
	v_mov_b32_e32 v19, v33
	v_lshl_add_u64 v[18:19], v[4:5], 0, v[18:19]
	v_lshlrev_b32_e32 v11, 16, v8
	v_and_b32_e32 v13, 0xffff0000, v8
	v_lshlrev_b32_e32 v15, 16, v9
	v_and_b32_e32 v17, 0xffff0000, v9
	v_mul_f32_e32 v2, 0xbfb8aa3b, v11
	v_mul_f32_e32 v8, 0xbfb8aa3b, v13
	v_mul_f32_e32 v9, 0xbfb8aa3b, v15
	v_mul_f32_e32 v23, 0xbfb8aa3b, v17
	v_exp_f32_e32 v2, v2
	v_exp_f32_e32 v8, v8
	v_exp_f32_e32 v9, v9
	v_exp_f32_e32 v23, v23
	v_add_f32_e32 v2, 1.0, v2
	v_add_f32_e32 v8, 1.0, v8
	v_add_f32_e32 v9, 1.0, v9
	v_add_f32_e32 v29, 1.0, v23
	v_rcp_f32_e32 v23, v2
	v_rcp_f32_e32 v25, v8
	v_rcp_f32_e32 v27, v9
	v_rcp_f32_e32 v29, v29
	v_pk_mul_f32 v[8:9], v[22:23], v[10:11]
	v_pk_mul_f32 v[10:11], v[24:25], v[12:13]
	v_pk_mul_f32 v[12:13], v[26:27], v[14:15]
	v_pk_mul_f32 v[14:15], v[28:29], v[16:17]
	v_mul_f32_e32 v2, v8, v9
	v_mul_f32_e32 v8, v10, v11
	v_mul_f32_e32 v9, v12, v13
	v_mul_f32_e32 v10, v14, v15
	v_cvt_pk_bf16_f32 v8, v2, v8
	v_cvt_pk_bf16_f32 v9, v9, v10
	global_store_dwordx2 v[0:1], v[8:9], off offset:1856
	v_mov_b64_e32 v[8:9], v[212:213]
	v_lshlrev_b32_e32 v10, 16, v71
	v_and_b32_e32 v12, 0xffff0000, v71
	v_lshlrev_b32_e32 v14, 16, v69
	v_and_b32_e32 v16, 0xffff0000, v69
	v_or_b32_e32 v18, 0x380, v32
	v_mov_b32_e32 v19, v33
	v_lshl_add_u64 v[18:19], v[4:5], 0, v[18:19]
	v_lshlrev_b32_e32 v11, 16, v8
	v_and_b32_e32 v13, 0xffff0000, v8
	v_lshlrev_b32_e32 v15, 16, v9
	v_and_b32_e32 v17, 0xffff0000, v9
	v_mul_f32_e32 v2, 0xbfb8aa3b, v11
	v_mul_f32_e32 v8, 0xbfb8aa3b, v13
	v_mul_f32_e32 v9, 0xbfb8aa3b, v15
	v_mul_f32_e32 v23, 0xbfb8aa3b, v17
	v_exp_f32_e32 v2, v2
	v_exp_f32_e32 v8, v8
	v_exp_f32_e32 v9, v9
	v_exp_f32_e32 v23, v23
	v_add_f32_e32 v2, 1.0, v2
	v_add_f32_e32 v8, 1.0, v8
	v_add_f32_e32 v9, 1.0, v9
	v_add_f32_e32 v29, 1.0, v23
	v_rcp_f32_e32 v23, v2
	v_rcp_f32_e32 v25, v8
	v_rcp_f32_e32 v27, v9
	v_rcp_f32_e32 v29, v29
	v_pk_mul_f32 v[8:9], v[22:23], v[10:11]
	v_pk_mul_f32 v[10:11], v[24:25], v[12:13]
	v_pk_mul_f32 v[12:13], v[26:27], v[14:15]
	v_pk_mul_f32 v[14:15], v[28:29], v[16:17]
	v_mul_f32_e32 v2, v8, v9
	v_mul_f32_e32 v8, v10, v11
	v_mul_f32_e32 v9, v12, v13
	v_mul_f32_e32 v10, v14, v15
	v_cvt_pk_bf16_f32 v8, v2, v8
	v_cvt_pk_bf16_f32 v9, v9, v10
	global_store_dwordx2 v[0:1], v[8:9], off offset:1888
	v_mov_b64_e32 v[8:9], v[214:215]
	v_lshlrev_b32_e32 v10, 16, v70
	v_and_b32_e32 v12, 0xffff0000, v70
	v_lshlrev_b32_e32 v14, 16, v68
	v_and_b32_e32 v16, 0xffff0000, v68
	v_or_b32_e32 v18, 0x3a0, v32
	v_mov_b32_e32 v19, v33
	v_lshl_add_u64 v[18:19], v[4:5], 0, v[18:19]
	v_lshlrev_b32_e32 v11, 16, v8
	v_and_b32_e32 v13, 0xffff0000, v8
	v_lshlrev_b32_e32 v15, 16, v9
	v_and_b32_e32 v17, 0xffff0000, v9
	v_mul_f32_e32 v2, 0xbfb8aa3b, v11
	v_mul_f32_e32 v8, 0xbfb8aa3b, v13
	v_mul_f32_e32 v9, 0xbfb8aa3b, v15
	v_mul_f32_e32 v23, 0xbfb8aa3b, v17
	v_exp_f32_e32 v2, v2
	v_exp_f32_e32 v8, v8
	v_exp_f32_e32 v9, v9
	v_exp_f32_e32 v23, v23
	v_add_f32_e32 v2, 1.0, v2
	v_add_f32_e32 v8, 1.0, v8
	v_add_f32_e32 v9, 1.0, v9
	v_add_f32_e32 v29, 1.0, v23
	v_rcp_f32_e32 v23, v2
	v_rcp_f32_e32 v25, v8
	v_rcp_f32_e32 v27, v9
	v_rcp_f32_e32 v29, v29
	v_pk_mul_f32 v[8:9], v[22:23], v[10:11]
	v_pk_mul_f32 v[10:11], v[24:25], v[12:13]
	v_pk_mul_f32 v[12:13], v[26:27], v[14:15]
	v_pk_mul_f32 v[14:15], v[28:29], v[16:17]
	v_mul_f32_e32 v2, v8, v9
	v_mul_f32_e32 v8, v10, v11
	v_mul_f32_e32 v9, v12, v13
	v_mul_f32_e32 v10, v14, v15
	v_cvt_pk_bf16_f32 v8, v2, v8
	v_cvt_pk_bf16_f32 v9, v9, v10
	global_store_dwordx2 v[0:1], v[8:9], off offset:1920
	v_mov_b64_e32 v[8:9], v[216:217]
	v_lshlrev_b32_e32 v10, 16, v66
	v_and_b32_e32 v12, 0xffff0000, v66
	v_lshlrev_b32_e32 v14, 16, v64
	v_and_b32_e32 v16, 0xffff0000, v64
	v_or_b32_e32 v18, 0x3c0, v32
	v_mov_b32_e32 v19, v33
	v_lshl_add_u64 v[18:19], v[4:5], 0, v[18:19]
	v_or_b32_e32 v32, 0x3e0, v32
	v_lshl_add_u64 v[4:5], v[4:5], 0, v[32:33]
	v_lshlrev_b32_e32 v11, 16, v8
	v_and_b32_e32 v13, 0xffff0000, v8
	v_lshlrev_b32_e32 v15, 16, v9
	v_and_b32_e32 v17, 0xffff0000, v9
	v_mul_f32_e32 v2, 0xbfb8aa3b, v11
	v_mul_f32_e32 v8, 0xbfb8aa3b, v13
	v_mul_f32_e32 v9, 0xbfb8aa3b, v15
	v_mul_f32_e32 v23, 0xbfb8aa3b, v17
	v_exp_f32_e32 v2, v2
	v_exp_f32_e32 v8, v8
	v_exp_f32_e32 v9, v9
	v_exp_f32_e32 v23, v23
	v_add_f32_e32 v2, 1.0, v2
	v_add_f32_e32 v8, 1.0, v8
	v_add_f32_e32 v9, 1.0, v9
	v_add_f32_e32 v29, 1.0, v23
	v_rcp_f32_e32 v23, v2
	v_rcp_f32_e32 v25, v8
	v_rcp_f32_e32 v27, v9
	v_rcp_f32_e32 v29, v29
	v_pk_mul_f32 v[8:9], v[22:23], v[10:11]
	v_pk_mul_f32 v[10:11], v[24:25], v[12:13]
	v_pk_mul_f32 v[12:13], v[26:27], v[14:15]
	v_pk_mul_f32 v[14:15], v[28:29], v[16:17]
	v_mul_f32_e32 v2, v8, v9
	v_mul_f32_e32 v8, v10, v11
	v_mul_f32_e32 v9, v12, v13
	v_mul_f32_e32 v10, v14, v15
	v_cvt_pk_bf16_f32 v8, v2, v8
	v_cvt_pk_bf16_f32 v9, v9, v10
	global_store_dwordx2 v[0:1], v[8:9], off offset:1952
	v_mov_b64_e32 v[8:9], v[218:219]
	v_lshlrev_b32_e32 v10, 16, v21
	v_and_b32_e32 v12, 0xffff0000, v21
	v_lshlrev_b32_e32 v14, 16, v20
	v_and_b32_e32 v16, 0xffff0000, v20
	v_mov_b32_e32 v18, v3
	v_mov_b32_e32 v20, v3
	v_lshlrev_b32_e32 v11, 16, v8
	v_and_b32_e32 v13, 0xffff0000, v8
	v_lshlrev_b32_e32 v15, 16, v9
	v_and_b32_e32 v17, 0xffff0000, v9
	v_mul_f32_e32 v2, 0xbfb8aa3b, v11
	v_mul_f32_e32 v8, 0xbfb8aa3b, v13
	v_mul_f32_e32 v9, 0xbfb8aa3b, v15
	v_mul_f32_e32 v19, 0xbfb8aa3b, v17
	v_exp_f32_e32 v2, v2
	v_exp_f32_e32 v8, v8
	v_exp_f32_e32 v9, v9
	v_exp_f32_e32 v19, v19
	v_add_f32_e32 v2, 1.0, v2
	v_add_f32_e32 v8, 1.0, v8
	v_add_f32_e32 v9, 1.0, v9
	v_add_f32_e32 v25, 1.0, v19
	v_rcp_f32_e32 v19, v2
	v_rcp_f32_e32 v21, v8
	v_rcp_f32_e32 v23, v9
	v_rcp_f32_e32 v25, v25
	v_pk_mul_f32 v[8:9], v[18:19], v[10:11]
	v_pk_mul_f32 v[10:11], v[20:21], v[12:13]
	v_pk_mul_f32 v[12:13], v[22:23], v[14:15]
	v_pk_mul_f32 v[14:15], v[24:25], v[16:17]
	v_mul_f32_e32 v2, v8, v9
	v_mul_f32_e32 v8, v10, v11
	v_mul_f32_e32 v9, v12, v13
	v_mul_f32_e32 v10, v14, v15
	v_cvt_pk_bf16_f32 v8, v2, v8
	v_cvt_pk_bf16_f32 v9, v9, v10
	global_store_dwordx2 v[0:1], v[8:9], off offset:1984
	v_mov_b64_e32 v[4:5], v[220:221]
	v_mov_b32_e32 v12, v3
	v_mov_b32_e32 v14, v3
	v_mov_b32_e32 v16, v3
	v_lshlrev_b32_e32 v2, 16, v7
	v_and_b32_e32 v8, 0xffff0000, v7
	v_lshlrev_b32_e32 v10, 16, v6
	v_and_b32_e32 v6, 0xffff0000, v6
	v_lshlrev_b32_e32 v3, 16, v4
	v_and_b32_e32 v9, 0xffff0000, v4
	v_lshlrev_b32_e32 v11, 16, v5
	v_and_b32_e32 v7, 0xffff0000, v5
	v_mul_f32_e32 v4, 0xbfb8aa3b, v3
	v_mul_f32_e32 v5, 0xbfb8aa3b, v9
	v_mul_f32_e32 v13, 0xbfb8aa3b, v11
	v_mul_f32_e32 v15, 0xbfb8aa3b, v7
	v_exp_f32_e32 v4, v4
	v_exp_f32_e32 v5, v5
	v_exp_f32_e32 v13, v13
	v_exp_f32_e32 v15, v15
	v_add_f32_e32 v4, 1.0, v4
	v_add_f32_e32 v5, 1.0, v5
	v_add_f32_e32 v17, 1.0, v13
	v_add_f32_e32 v19, 1.0, v15
	v_rcp_f32_e32 v13, v4
	v_rcp_f32_e32 v15, v5
	v_rcp_f32_e32 v17, v17
	v_rcp_f32_e32 v19, v19
	v_pk_mul_f32 v[2:3], v[12:13], v[2:3]
	v_pk_mul_f32 v[4:5], v[14:15], v[8:9]
	v_pk_mul_f32 v[8:9], v[16:17], v[10:11]
	v_pk_mul_f32 v[6:7], v[18:19], v[6:7]
	v_mul_f32_e32 v2, v2, v3
	v_mul_f32_e32 v3, v4, v5
	v_mul_f32_e32 v4, v8, v9
	v_mul_f32_e32 v5, v6, v7
	v_cvt_pk_bf16_f32 v2, v2, v3
	v_cvt_pk_bf16_f32 v3, v4, v5
	global_store_dwordx2 v[0:1], v[2:3], off offset:2016
	s_cbranch_scc1 .LBB0_900
